# v44 + phases 1/5: A-fragment ds_reads issued first, ahead of the segment's scalar bookkeeping
# baseline (speedup 1.0000x reference)
.LBB0_127:
	ds_read_b128 v[162:165], v144
	ds_read_b128 v[166:169], v144 offset:1024
	ds_read_b128 v[170:173], v144 offset:2048
	ds_read_b128 v[174:177], v144 offset:3072
	ds_read_b128 v[192:195], v144 offset:4096
	ds_read_b128 v[196:199], v144 offset:5120
	ds_read_b128 v[200:203], v144 offset:6144
	ds_read_b128 v[204:207], v144 offset:7168
	s_add_u32 s22, s20, 0xfff80080
	s_addc_u32 s23, s21, -1
	s_add_i32 s50, 0, 0x10000
	s_cmp_eq_u32 s49, 4
	s_cselect_b32 s23, s81, s23
	s_cselect_b32 s22, s80, s22
	s_cselect_b32 s39, s19, s48
	s_cselect_b32 s38, s31, s47
	v_lshl_add_u64 v[178:179], s[20:21], 0, v[138:139]
	s_add_i32 m0, s27, 0xc000
	s_nop 0
	global_load_lds_dwordx4 v[178:179], off
	v_lshl_add_u64 v[178:179], s[20:21], 0, v[140:141]
	s_add_i32 m0, s27, 0xe000
	s_nop 0
	global_load_lds_dwordx4 v[178:179], off
	s_waitcnt lgkmcnt(8)
	s_barrier
	s_waitcnt lgkmcnt(0)
	v_mfma_f32_16x16x32_bf16 v[126:129], v[146:149], v[162:165], v[126:129]
	v_mfma_f32_16x16x32_bf16 v[122:125], v[154:157], v[162:165], v[122:125]
	v_mfma_f32_16x16x32_bf16 v[118:121], v[146:149], v[170:173], v[118:121]
	v_mfma_f32_16x16x32_bf16 v[114:117], v[154:157], v[170:173], v[114:117]
	v_mfma_f32_16x16x32_bf16 v[102:105], v[146:149], v[192:195], v[102:105]
	v_mfma_f32_16x16x32_bf16 v[98:101], v[154:157], v[192:195], v[98:101]
	v_mfma_f32_16x16x32_bf16 v[86:89], v[146:149], v[200:203], v[86:89]
	v_mfma_f32_16x16x32_bf16 v[82:85], v[154:157], v[200:203], v[82:85]
	v_mfma_f32_16x16x32_bf16 v[126:129], v[150:153], v[166:169], v[126:129]
	v_mfma_f32_16x16x32_bf16 v[122:125], v[158:161], v[166:169], v[122:125]
	v_mfma_f32_16x16x32_bf16 v[118:121], v[150:153], v[174:177], v[118:121]
	v_mfma_f32_16x16x32_bf16 v[114:117], v[158:161], v[174:177], v[114:117]
	v_mfma_f32_16x16x32_bf16 v[102:105], v[150:153], v[196:199], v[102:105]
	v_mfma_f32_16x16x32_bf16 v[98:101], v[158:161], v[196:199], v[98:101]
	v_mfma_f32_16x16x32_bf16 v[86:89], v[150:153], v[204:207], v[86:89]
	v_mfma_f32_16x16x32_bf16 v[82:85], v[158:161], v[204:207], v[82:85]
	s_barrier
	s_add_i32 s52, 0, 0x14000
	s_add_i32 s50, s50, s26
	v_add_u32_e32 v145, s52, v142
	v_lshl_add_u64 v[178:179], s[38:39], 0, v[134:135]
	s_mov_b32 m0, s50
	ds_read_b128 v[208:211], v145
	ds_read_b128 v[224:227], v145 offset:1024
	ds_read_b128 v[228:231], v145 offset:2048
	ds_read_b128 v[232:235], v145 offset:3072
	global_load_lds_dwordx4 v[178:179], off
	v_lshl_add_u64 v[212:213], s[38:39], 0, v[130:131]
	s_add_i32 m0, s50, 0x2000
	s_nop 0
	global_load_lds_dwordx4 v[212:213], off
	s_mov_b32 m0, s27
	v_lshl_add_u64 v[236:237], s[22:23], 0, v[136:137]
	s_barrier
	s_waitcnt lgkmcnt(0)
	v_mfma_f32_16x16x32_bf16 v[110:113], v[208:211], v[162:165], v[110:113]
	v_mfma_f32_16x16x32_bf16 v[106:109], v[228:231], v[162:165], v[106:109]
	v_mfma_f32_16x16x32_bf16 v[94:97], v[208:211], v[170:173], v[94:97]
	v_mfma_f32_16x16x32_bf16 v[90:93], v[228:231], v[170:173], v[90:93]
	v_mfma_f32_16x16x32_bf16 v[78:81], v[208:211], v[192:195], v[78:81]
	v_mfma_f32_16x16x32_bf16 v[74:77], v[228:231], v[192:195], v[74:77]
	v_mfma_f32_16x16x32_bf16 v[70:73], v[208:211], v[200:203], v[70:73]
	v_mfma_f32_16x16x32_bf16 v[66:69], v[228:231], v[200:203], v[66:69]
	v_mfma_f32_16x16x32_bf16 v[110:113], v[224:227], v[166:169], v[110:113]
	v_mfma_f32_16x16x32_bf16 v[106:109], v[232:235], v[166:169], v[106:109]
	v_mfma_f32_16x16x32_bf16 v[94:97], v[224:227], v[174:177], v[94:97]
	v_mfma_f32_16x16x32_bf16 v[90:93], v[232:235], v[174:177], v[90:93]
	v_mfma_f32_16x16x32_bf16 v[78:81], v[224:227], v[196:199], v[78:81]
	v_mfma_f32_16x16x32_bf16 v[74:77], v[232:235], v[196:199], v[74:77]
	v_mfma_f32_16x16x32_bf16 v[70:73], v[224:227], v[204:207], v[70:73]
	v_mfma_f32_16x16x32_bf16 v[66:69], v[232:235], v[204:207], v[66:69]
	s_barrier
	ds_read_b128 v[162:165], v144 offset:16384
	ds_read_b128 v[166:169], v144 offset:17408
	ds_read_b128 v[170:173], v144 offset:18432
	ds_read_b128 v[174:177], v144 offset:19456
	ds_read_b128 v[192:195], v144 offset:20480
	ds_read_b128 v[196:199], v144 offset:21504
	ds_read_b128 v[200:203], v144 offset:22528
	ds_read_b128 v[204:207], v144 offset:23552
	global_load_lds_dwordx4 v[236:237], off
	v_lshl_add_u64 v[238:239], s[22:23], 0, v[132:133]
	s_mov_b32 m0, s28
	s_nop 0
	global_load_lds_dwordx4 v[238:239], off
	s_waitcnt vmcnt(10)
	s_barrier
	s_waitcnt lgkmcnt(0)
	v_mfma_f32_16x16x32_bf16 v[62:65], v[146:149], v[162:165], v[62:65]
	v_mfma_f32_16x16x32_bf16 v[58:61], v[154:157], v[162:165], v[58:61]
	v_mfma_f32_16x16x32_bf16 v[54:57], v[146:149], v[170:173], v[54:57]
	v_mfma_f32_16x16x32_bf16 v[50:53], v[154:157], v[170:173], v[50:53]
	v_mfma_f32_16x16x32_bf16 v[38:41], v[146:149], v[192:195], v[38:41]
	v_mfma_f32_16x16x32_bf16 v[34:37], v[154:157], v[192:195], v[34:37]
	v_mfma_f32_16x16x32_bf16 v[22:25], v[146:149], v[200:203], v[22:25]
	v_mfma_f32_16x16x32_bf16 v[18:21], v[154:157], v[200:203], v[18:21]
	v_mfma_f32_16x16x32_bf16 v[62:65], v[150:153], v[166:169], v[62:65]
	v_mfma_f32_16x16x32_bf16 v[58:61], v[158:161], v[166:169], v[58:61]
	v_mfma_f32_16x16x32_bf16 v[54:57], v[150:153], v[174:177], v[54:57]
	v_mfma_f32_16x16x32_bf16 v[50:53], v[158:161], v[174:177], v[50:53]
	v_mfma_f32_16x16x32_bf16 v[38:41], v[150:153], v[196:199], v[38:41]
	v_mfma_f32_16x16x32_bf16 v[34:37], v[158:161], v[196:199], v[34:37]
	v_mfma_f32_16x16x32_bf16 v[22:25], v[150:153], v[204:207], v[22:25]
	v_mfma_f32_16x16x32_bf16 v[18:21], v[158:161], v[204:207], v[18:21]
	s_barrier
	s_add_u32 s50, s38, 0x20000
	s_addc_u32 s51, s39, 0
	s_add_i32 s52, s52, s26
	v_lshl_add_u64 v[146:147], s[50:51], 0, v[134:135]
	s_mov_b32 m0, s52
	s_nop 0
	global_load_lds_dwordx4 v[146:147], off
	v_lshl_add_u64 v[146:147], s[50:51], 0, v[130:131]
	s_add_i32 m0, s52, 0x2000
	s_nop 0
	global_load_lds_dwordx4 v[146:147], off
	v_add_u32_e32 v145, 0x18000, v142
	ds_read_b128 v[146:149], v145
	ds_read_b128 v[150:153], v145 offset:1024
	ds_read_b128 v[154:157], v145 offset:2048
	ds_read_b128 v[158:161], v145 offset:3072
	s_add_i32 s50, 0, 0x18000
	s_waitcnt vmcnt(6)
	s_barrier
	v_mfma_f32_16x16x32_bf16 v[46:49], v[208:211], v[162:165], v[46:49]
	v_mfma_f32_16x16x32_bf16 v[42:45], v[228:231], v[162:165], v[42:45]
	v_mfma_f32_16x16x32_bf16 v[30:33], v[208:211], v[170:173], v[30:33]
	v_mfma_f32_16x16x32_bf16 v[26:29], v[228:231], v[170:173], v[26:29]
	v_mfma_f32_16x16x32_bf16 v[14:17], v[208:211], v[192:195], v[14:17]
	v_mfma_f32_16x16x32_bf16 v[10:13], v[228:231], v[192:195], v[10:13]
	v_mfma_f32_16x16x32_bf16 v[6:9], v[208:211], v[200:203], v[6:9]
	v_mfma_f32_16x16x32_bf16 v[2:5], v[228:231], v[200:203], v[2:5]
	v_mfma_f32_16x16x32_bf16 v[46:49], v[224:227], v[166:169], v[46:49]
	v_mfma_f32_16x16x32_bf16 v[42:45], v[232:235], v[166:169], v[42:45]
	v_mfma_f32_16x16x32_bf16 v[30:33], v[224:227], v[174:177], v[30:33]
	v_mfma_f32_16x16x32_bf16 v[26:29], v[232:235], v[174:177], v[26:29]
	v_mfma_f32_16x16x32_bf16 v[14:17], v[224:227], v[196:199], v[14:17]
	v_mfma_f32_16x16x32_bf16 v[10:13], v[232:235], v[196:199], v[10:13]
	v_mfma_f32_16x16x32_bf16 v[6:9], v[224:227], v[204:207], v[6:9]
	v_mfma_f32_16x16x32_bf16 v[2:5], v[232:235], v[204:207], v[2:5]
	s_barrier
	ds_read_b128 v[162:165], v144 offset:32768
	ds_read_b128 v[166:169], v144 offset:33792
	ds_read_b128 v[170:173], v144 offset:34816
	ds_read_b128 v[174:177], v144 offset:35840
	ds_read_b128 v[192:195], v144 offset:36864
	ds_read_b128 v[196:199], v144 offset:37888
	ds_read_b128 v[200:203], v144 offset:38912
	ds_read_b128 v[204:207], v144 offset:39936
	s_add_u32 s22, s22, 0x80000
	s_addc_u32 s23, s23, 0
	s_mov_b32 m0, s29
	v_lshl_add_u64 v[208:209], s[22:23], 0, v[136:137]
	global_load_lds_dwordx4 v[208:209], off
	v_lshl_add_u64 v[208:209], s[22:23], 0, v[132:133]
	s_mov_b32 m0, s36
	s_nop 0
	global_load_lds_dwordx4 v[208:209], off
	s_waitcnt lgkmcnt(8)
	s_barrier
	s_waitcnt lgkmcnt(0)
	v_mfma_f32_16x16x32_bf16 v[126:129], v[146:149], v[162:165], v[126:129]
	v_mfma_f32_16x16x32_bf16 v[122:125], v[154:157], v[162:165], v[122:125]
	v_mfma_f32_16x16x32_bf16 v[118:121], v[146:149], v[170:173], v[118:121]
	v_mfma_f32_16x16x32_bf16 v[114:117], v[154:157], v[170:173], v[114:117]
	v_mfma_f32_16x16x32_bf16 v[102:105], v[146:149], v[192:195], v[102:105]
	v_mfma_f32_16x16x32_bf16 v[98:101], v[154:157], v[192:195], v[98:101]
	v_mfma_f32_16x16x32_bf16 v[86:89], v[146:149], v[200:203], v[86:89]
	v_mfma_f32_16x16x32_bf16 v[82:85], v[154:157], v[200:203], v[82:85]
	v_mfma_f32_16x16x32_bf16 v[126:129], v[150:153], v[166:169], v[126:129]
	v_mfma_f32_16x16x32_bf16 v[122:125], v[158:161], v[166:169], v[122:125]
	v_mfma_f32_16x16x32_bf16 v[118:121], v[150:153], v[174:177], v[118:121]
	v_mfma_f32_16x16x32_bf16 v[114:117], v[158:161], v[174:177], v[114:117]
	v_mfma_f32_16x16x32_bf16 v[102:105], v[150:153], v[196:199], v[102:105]
	v_mfma_f32_16x16x32_bf16 v[98:101], v[158:161], v[196:199], v[98:101]
	v_mfma_f32_16x16x32_bf16 v[86:89], v[150:153], v[204:207], v[86:89]
	v_mfma_f32_16x16x32_bf16 v[82:85], v[158:161], v[204:207], v[82:85]
	s_barrier
	s_add_i32 s51, 0, 0x1c000
	s_add_i32 s22, s50, s26
	v_add_u32_e32 v145, s51, v142
	v_lshl_add_u64 v[178:179], v[178:179], 0, s[78:79]
	s_mov_b32 m0, s22
	ds_read_b128 v[208:211], v145
	ds_read_b128 v[224:227], v145 offset:1024
	ds_read_b128 v[228:231], v145 offset:2048
	ds_read_b128 v[232:235], v145 offset:3072
	global_load_lds_dwordx4 v[178:179], off
	v_lshl_add_u64 v[178:179], v[212:213], 0, s[78:79]
	s_add_i32 m0, s22, 0x2000
	s_nop 0
	global_load_lds_dwordx4 v[178:179], off
	s_mov_b32 m0, s42
	v_lshl_add_u64 v[178:179], v[236:237], 0, s[78:79]
	s_barrier
	s_waitcnt lgkmcnt(0)
	v_mfma_f32_16x16x32_bf16 v[110:113], v[208:211], v[162:165], v[110:113]
	v_mfma_f32_16x16x32_bf16 v[106:109], v[228:231], v[162:165], v[106:109]
	v_mfma_f32_16x16x32_bf16 v[94:97], v[208:211], v[170:173], v[94:97]
	v_mfma_f32_16x16x32_bf16 v[90:93], v[228:231], v[170:173], v[90:93]
	v_mfma_f32_16x16x32_bf16 v[78:81], v[208:211], v[192:195], v[78:81]
	v_mfma_f32_16x16x32_bf16 v[74:77], v[228:231], v[192:195], v[74:77]
	v_mfma_f32_16x16x32_bf16 v[70:73], v[208:211], v[200:203], v[70:73]
	v_mfma_f32_16x16x32_bf16 v[66:69], v[228:231], v[200:203], v[66:69]
	v_mfma_f32_16x16x32_bf16 v[110:113], v[224:227], v[166:169], v[110:113]
	v_mfma_f32_16x16x32_bf16 v[106:109], v[232:235], v[166:169], v[106:109]
	v_mfma_f32_16x16x32_bf16 v[94:97], v[224:227], v[174:177], v[94:97]
	v_mfma_f32_16x16x32_bf16 v[90:93], v[232:235], v[174:177], v[90:93]
	v_mfma_f32_16x16x32_bf16 v[78:81], v[224:227], v[196:199], v[78:81]
	v_mfma_f32_16x16x32_bf16 v[74:77], v[232:235], v[196:199], v[74:77]
	v_mfma_f32_16x16x32_bf16 v[70:73], v[224:227], v[204:207], v[70:73]
	v_mfma_f32_16x16x32_bf16 v[66:69], v[232:235], v[204:207], v[66:69]
	s_barrier
	ds_read_b128 v[162:165], v144 offset:49152
	ds_read_b128 v[166:169], v144 offset:50176
	ds_read_b128 v[170:173], v144 offset:51200
	ds_read_b128 v[174:177], v144 offset:52224
	ds_read_b128 v[192:195], v144 offset:53248
	ds_read_b128 v[196:199], v144 offset:54272
	ds_read_b128 v[200:203], v144 offset:55296
	ds_read_b128 v[204:207], v144 offset:56320
	global_load_lds_dwordx4 v[178:179], off
	v_lshl_add_u64 v[178:179], v[238:239], 0, s[78:79]
	s_mov_b32 m0, s43
	s_nop 0
	global_load_lds_dwordx4 v[178:179], off
	s_waitcnt vmcnt(10)
	s_barrier
	s_waitcnt lgkmcnt(0)
	v_mfma_f32_16x16x32_bf16 v[62:65], v[146:149], v[162:165], v[62:65]
	v_mfma_f32_16x16x32_bf16 v[58:61], v[154:157], v[162:165], v[58:61]
	v_mfma_f32_16x16x32_bf16 v[54:57], v[146:149], v[170:173], v[54:57]
	v_mfma_f32_16x16x32_bf16 v[50:53], v[154:157], v[170:173], v[50:53]
	v_mfma_f32_16x16x32_bf16 v[38:41], v[146:149], v[192:195], v[38:41]
	v_mfma_f32_16x16x32_bf16 v[34:37], v[154:157], v[192:195], v[34:37]
	v_mfma_f32_16x16x32_bf16 v[22:25], v[146:149], v[200:203], v[22:25]
	v_mfma_f32_16x16x32_bf16 v[18:21], v[154:157], v[200:203], v[18:21]
	v_mfma_f32_16x16x32_bf16 v[62:65], v[150:153], v[166:169], v[62:65]
	v_mfma_f32_16x16x32_bf16 v[58:61], v[158:161], v[166:169], v[58:61]
	v_mfma_f32_16x16x32_bf16 v[54:57], v[150:153], v[174:177], v[54:57]
	v_mfma_f32_16x16x32_bf16 v[50:53], v[158:161], v[174:177], v[50:53]
	v_mfma_f32_16x16x32_bf16 v[38:41], v[150:153], v[196:199], v[38:41]
	v_mfma_f32_16x16x32_bf16 v[34:37], v[158:161], v[196:199], v[34:37]
	v_mfma_f32_16x16x32_bf16 v[22:25], v[150:153], v[204:207], v[22:25]
	v_mfma_f32_16x16x32_bf16 v[18:21], v[158:161], v[204:207], v[18:21]
	s_barrier
	s_add_u32 s22, s38, 0x20080
	s_addc_u32 s23, s39, 0
	s_add_i32 s38, s51, s26
	v_lshl_add_u64 v[146:147], s[22:23], 0, v[134:135]
	s_mov_b32 m0, s38
	s_nop 0
	global_load_lds_dwordx4 v[146:147], off
	v_lshl_add_u64 v[146:147], s[22:23], 0, v[130:131]
	s_add_i32 m0, s38, 0x2000
	s_nop 0
	global_load_lds_dwordx4 v[146:147], off
	v_add_u32_e32 v145, 0x10000, v142
	ds_read_b128 v[146:149], v145
	ds_read_b128 v[150:153], v145 offset:1024
	ds_read_b128 v[154:157], v145 offset:2048
	ds_read_b128 v[158:161], v145 offset:3072
	s_add_i32 s49, s49, 2
	s_add_u32 s20, s20, 0x100
	s_addc_u32 s21, s21, 0
	s_add_u32 s47, s47, 0x100
	s_addc_u32 s48, s48, 0
	s_cmp_gt_u32 s49, 5
	s_waitcnt vmcnt(6)
	s_barrier
	v_mfma_f32_16x16x32_bf16 v[46:49], v[208:211], v[162:165], v[46:49]
	v_mfma_f32_16x16x32_bf16 v[42:45], v[228:231], v[162:165], v[42:45]
	v_mfma_f32_16x16x32_bf16 v[30:33], v[208:211], v[170:173], v[30:33]
	v_mfma_f32_16x16x32_bf16 v[26:29], v[228:231], v[170:173], v[26:29]
	v_mfma_f32_16x16x32_bf16 v[14:17], v[208:211], v[192:195], v[14:17]
	v_mfma_f32_16x16x32_bf16 v[10:13], v[228:231], v[192:195], v[10:13]
	v_mfma_f32_16x16x32_bf16 v[6:9], v[208:211], v[200:203], v[6:9]
	v_mfma_f32_16x16x32_bf16 v[2:5], v[228:231], v[200:203], v[2:5]
	v_mfma_f32_16x16x32_bf16 v[46:49], v[224:227], v[166:169], v[46:49]
	v_mfma_f32_16x16x32_bf16 v[42:45], v[232:235], v[166:169], v[42:45]
	v_mfma_f32_16x16x32_bf16 v[30:33], v[224:227], v[174:177], v[30:33]
	v_mfma_f32_16x16x32_bf16 v[26:29], v[232:235], v[174:177], v[26:29]
	v_mfma_f32_16x16x32_bf16 v[14:17], v[224:227], v[196:199], v[14:17]
	v_mfma_f32_16x16x32_bf16 v[10:13], v[232:235], v[196:199], v[10:13]
	v_mfma_f32_16x16x32_bf16 v[6:9], v[224:227], v[204:207], v[6:9]
	v_mfma_f32_16x16x32_bf16 v[2:5], v[232:235], v[204:207], v[2:5]
	s_barrier
	s_cbranch_scc0 .LBB0_127
	s_waitcnt lgkmcnt(0)
	v_lshl_add_u32 v146, s46, 8, v1
	v_lshl_or_b32 v148, s45, 8, v143
	v_ashrrev_i32_e32 v147, 31, v146
	v_readlane_b32 s48, v254, 40
	v_ashrrev_i32_e32 v149, 31, v148
	v_lshlrev_b64 v[150:151], 12, v[146:147]
	v_readlane_b32 s52, v254, 44
	v_readlane_b32 s53, v254, 45
	v_lshlrev_b64 v[148:149], 1, v[148:149]
	s_mov_b32 s19, 0x80000
	v_lshl_add_u64 v[150:151], s[52:53], 0, v[150:151]
	v_lshl_add_u64 v[150:151], v[150:151], 0, v[148:149]
	s_mov_b64 s[20:21], 0x80000
	v_cvt_pk_bf16_f32 v62, v62, v63
	v_cvt_pk_bf16_f32 v63, v64, v65
	v_cvt_pk_bf16_f32 v64, v58, v59
	v_add_co_u32_e32 v58, vcc, s19, v150
	v_cvt_pk_bf16_f32 v70, v70, v71
	v_cvt_pk_bf16_f32 v71, v72, v73
	v_cvt_pk_bf16_f32 v72, v66, v67
	v_lshl_add_u64 v[66:67], v[150:151], 0, s[20:21]
	v_addc_co_u32_e32 v59, vcc, 0, v151, vcc
	v_cvt_pk_bf16_f32 v46, v46, v47
	v_cvt_pk_bf16_f32 v47, v48, v49
	v_cvt_pk_bf16_f32 v48, v42, v43
	v_cvt_pk_bf16_f32 v49, v44, v45
	s_mov_b32 s19, 0x90000
	v_cvt_pk_bf16_f32 v110, v110, v111
	v_cvt_pk_bf16_f32 v111, v112, v113
	v_cvt_pk_bf16_f32 v112, v106, v107
	v_or_b32_e32 v106, 16, v146
	global_store_dwordx4 v[66:67], v[46:49], off offset:256
	s_mov_b64 s[20:21], 0x90000
	v_ashrrev_i32_e32 v107, 31, v106
	v_add_co_u32_e32 v48, vcc, s19, v150
	v_cvt_pk_bf16_f32 v94, v94, v95
	v_cvt_pk_bf16_f32 v95, v96, v97
	v_cvt_pk_bf16_f32 v96, v90, v91
	v_or_b32_e32 v90, 32, v146
	v_lshl_add_u64 v[46:47], v[150:151], 0, s[20:21]
	v_addc_co_u32_e32 v49, vcc, 0, v151, vcc
	v_cvt_pk_bf16_f32 v30, v30, v31
	v_cvt_pk_bf16_f32 v31, v32, v33
	v_cvt_pk_bf16_f32 v32, v26, v27
	v_cvt_pk_bf16_f32 v33, v28, v29
	s_mov_b32 s19, 0xa0000
	v_lshlrev_b64 v[106:107], 12, v[106:107]
	v_ashrrev_i32_e32 v91, 31, v90
	v_cvt_pk_bf16_f32 v78, v78, v79
	v_cvt_pk_bf16_f32 v79, v80, v81
	v_cvt_pk_bf16_f32 v80, v74, v75
	v_or_b32_e32 v74, 48, v146
	global_store_dwordx4 v[46:47], v[30:33], off offset:256
	s_mov_b64 s[20:21], 0xa0000
	v_cvt_pk_bf16_f32 v113, v108, v109
	v_add_co_u32_e32 v32, vcc, s19, v150
	v_lshl_add_u64 v[106:107], s[52:53], 0, v[106:107]
	v_lshlrev_b64 v[90:91], 12, v[90:91]
	v_ashrrev_i32_e32 v75, 31, v74
	v_lshl_add_u64 v[30:31], v[150:151], 0, s[20:21]
	v_addc_co_u32_e32 v33, vcc, 0, v151, vcc
	v_cvt_pk_bf16_f32 v14, v14, v15
	v_cvt_pk_bf16_f32 v15, v16, v17
	v_cvt_pk_bf16_f32 v16, v10, v11
	v_cvt_pk_bf16_f32 v17, v12, v13
	s_mov_b32 s19, 0xb0000
	global_store_dwordx4 v[150:151], v[110:113], off offset:256
	v_cvt_pk_bf16_f32 v97, v92, v93
	v_lshl_add_u64 v[90:91], s[52:53], 0, v[90:91]
	v_lshl_add_u64 v[110:111], v[106:107], 0, v[148:149]
	v_lshlrev_b64 v[74:75], 12, v[74:75]
	global_store_dwordx4 v[30:31], v[14:17], off offset:256
	global_store_dwordx4 v[110:111], v[94:97], off offset:256
	v_cvt_pk_bf16_f32 v81, v76, v77
	v_add_co_u32_e32 v16, vcc, s19, v150
	v_lshl_add_u64 v[94:95], v[90:91], 0, v[148:149]
	v_lshl_add_u64 v[74:75], s[52:53], 0, v[74:75]
	s_mov_b64 s[20:21], 0xb0000
	v_addc_co_u32_e32 v17, vcc, 0, v151, vcc
	v_cvt_pk_bf16_f32 v126, v126, v127
	v_cvt_pk_bf16_f32 v127, v128, v129
	v_cvt_pk_bf16_f32 v128, v122, v123
	v_cvt_pk_bf16_f32 v129, v124, v125
	v_cvt_pk_bf16_f32 v106, v118, v119
	v_cvt_pk_bf16_f32 v107, v120, v121
	v_cvt_pk_bf16_f32 v108, v114, v115
	v_cvt_pk_bf16_f32 v109, v116, v117
	v_cvt_pk_bf16_f32 v90, v102, v103
	v_cvt_pk_bf16_f32 v91, v104, v105
	v_cvt_pk_bf16_f32 v92, v98, v99
	v_cvt_pk_bf16_f32 v93, v100, v101
	global_store_dwordx4 v[94:95], v[78:81], off offset:256
	v_cvt_pk_bf16_f32 v76, v82, v83
	v_cvt_pk_bf16_f32 v77, v84, v85
	v_lshl_add_u64 v[78:79], v[74:75], 0, v[148:149]
	v_cvt_pk_bf16_f32 v74, v86, v87
	v_cvt_pk_bf16_f32 v75, v88, v89
	v_cvt_pk_bf16_f32 v73, v68, v69
	v_cvt_pk_bf16_f32 v65, v60, v61
	v_cvt_pk_bf16_f32 v42, v54, v55
	v_cvt_pk_bf16_f32 v43, v56, v57
	v_cvt_pk_bf16_f32 v44, v50, v51
	v_cvt_pk_bf16_f32 v45, v52, v53
	v_cvt_pk_bf16_f32 v26, v38, v39
	v_cvt_pk_bf16_f32 v27, v40, v41
	v_cvt_pk_bf16_f32 v28, v34, v35
	v_cvt_pk_bf16_f32 v29, v36, v37
	v_lshl_add_u64 v[14:15], v[150:151], 0, s[20:21]
	v_cvt_pk_bf16_f32 v10, v22, v23
	v_cvt_pk_bf16_f32 v11, v24, v25
	v_cvt_pk_bf16_f32 v12, v18, v19
	v_cvt_pk_bf16_f32 v13, v20, v21
	v_cvt_pk_bf16_f32 v6, v6, v7
	v_cvt_pk_bf16_f32 v7, v8, v9
	v_cvt_pk_bf16_f32 v8, v2, v3
	v_cvt_pk_bf16_f32 v9, v4, v5
	s_and_b64 vcc, exec, s[0:1]
	s_mov_b32 s45, s18
	s_mov_b32 s46, s30
	s_mov_b64 s[22:23], s[82:83]
	s_mov_b64 s[20:21], s[80:81]
	s_mov_b32 s64, 0x800000
	s_movk_i32 s65, 0x1fff
	v_readlane_b32 s49, v254, 41
	v_readlane_b32 s50, v254, 42
	v_readlane_b32 s51, v254, 43
	v_readlane_b32 s54, v254, 46
	v_readlane_b32 s55, v254, 47
	v_readlane_b32 s56, v254, 48
	v_readlane_b32 s57, v254, 49
	v_readlane_b32 s58, v254, 50
	v_readlane_b32 s59, v254, 51
	v_readlane_b32 s60, v254, 52
	v_readlane_b32 s61, v254, 53
	v_readlane_b32 s62, v254, 54
	v_readlane_b32 s63, v254, 55
	global_store_dwordx4 v[150:151], v[126:129], off
	global_store_dwordx4 v[110:111], v[106:109], off
	global_store_dwordx4 v[94:95], v[90:93], off
	global_store_dwordx4 v[78:79], v[74:77], off
	global_store_dwordx4 v[78:79], v[70:73], off offset:256
	global_store_dwordx4 v[58:59], v[62:65], off
	global_store_dwordx4 v[48:49], v[42:45], off
	global_store_dwordx4 v[32:33], v[26:29], off
	global_store_dwordx4 v[16:17], v[10:13], off
	global_store_dwordx4 v[14:15], v[6:9], off offset:256
	s_cbranch_vccz .LBB0_118
	s_waitcnt vmcnt(0)
	v_readlane_b32 s44, v255, 30
	s_mov_b32 s66, s90
	s_cmpk_gt_u32 s25, 0xff
	v_readlane_b32 s45, v255, 31
	v_readlane_b32 s42, v255, 32
	s_cbranch_scc1 .LBB0_131
	s_barrier

.LBB0_240:
	ds_read_b128 v[158:161], v140
	ds_read_b128 v[162:165], v140 offset:1024
	ds_read_b128 v[166:169], v140 offset:2048
	ds_read_b128 v[170:173], v140 offset:3072
	ds_read_b128 v[174:177], v140 offset:4096
	ds_read_b128 v[192:195], v140 offset:5120
	ds_read_b128 v[196:199], v140 offset:6144
	ds_read_b128 v[200:203], v140 offset:7168
	s_add_u32 s22, s80, 0xfff80080
	s_addc_u32 s23, s81, -1
	s_add_i32 s52, 0, 0x10000
	s_cmp_eq_u32 s51, 28
	s_cselect_b32 s23, s21, s23
	s_cselect_b32 s22, s47, s22
	s_cselect_b32 s83, s19, s50
	s_cselect_b32 s82, s48, s49
	v_lshl_add_u64 v[178:179], s[80:81], 0, v[134:135]
	s_add_i32 m0, s27, 0xc000
	s_nop 0
	global_load_lds_dwordx4 v[178:179], off
	v_lshl_add_u64 v[178:179], s[80:81], 0, v[136:137]
	s_add_i32 m0, s27, 0xe000
	s_nop 0
	global_load_lds_dwordx4 v[178:179], off
	s_waitcnt lgkmcnt(8)
	s_barrier
	s_waitcnt lgkmcnt(0)
	v_mfma_f32_16x16x32_bf16 v[126:129], v[142:145], v[158:161], v[126:129]
	v_mfma_f32_16x16x32_bf16 v[122:125], v[150:153], v[158:161], v[122:125]
	v_mfma_f32_16x16x32_bf16 v[118:121], v[142:145], v[166:169], v[118:121]
	v_mfma_f32_16x16x32_bf16 v[114:117], v[150:153], v[166:169], v[114:117]
	v_mfma_f32_16x16x32_bf16 v[110:113], v[142:145], v[174:177], v[110:113]
	v_mfma_f32_16x16x32_bf16 v[102:105], v[150:153], v[174:177], v[102:105]
	v_mfma_f32_16x16x32_bf16 v[94:97], v[142:145], v[196:199], v[94:97]
	v_mfma_f32_16x16x32_bf16 v[86:89], v[150:153], v[196:199], v[86:89]
	v_mfma_f32_16x16x32_bf16 v[126:129], v[146:149], v[162:165], v[126:129]
	v_mfma_f32_16x16x32_bf16 v[122:125], v[154:157], v[162:165], v[122:125]
	v_mfma_f32_16x16x32_bf16 v[118:121], v[146:149], v[170:173], v[118:121]
	v_mfma_f32_16x16x32_bf16 v[114:117], v[154:157], v[170:173], v[114:117]
	v_mfma_f32_16x16x32_bf16 v[110:113], v[146:149], v[192:195], v[110:113]
	v_mfma_f32_16x16x32_bf16 v[102:105], v[154:157], v[192:195], v[102:105]
	v_mfma_f32_16x16x32_bf16 v[94:97], v[146:149], v[200:203], v[94:97]
	v_mfma_f32_16x16x32_bf16 v[86:89], v[154:157], v[200:203], v[86:89]
	s_barrier
	s_add_i32 s54, 0, 0x14000
	s_add_i32 s52, s52, s26
	v_add_u32_e32 v141, s54, v138
	v_lshl_add_u64 v[178:179], s[82:83], 0, v[132:133]
	s_mov_b32 m0, s52
	ds_read_b128 v[204:207], v141
	ds_read_b128 v[208:211], v141 offset:1024
	ds_read_b128 v[224:227], v141 offset:2048
	ds_read_b128 v[228:231], v141 offset:3072
	global_load_lds_dwordx4 v[178:179], off
	v_lshl_add_u64 v[212:213], s[82:83], 0, v[130:131]
	s_add_i32 m0, s52, 0x2000
	s_nop 0
	global_load_lds_dwordx4 v[212:213], off
	s_mov_b32 m0, s27
	v_lshl_add_u64 v[232:233], s[22:23], 0, v[132:133]
	s_barrier
	s_waitcnt lgkmcnt(0)
	v_mfma_f32_16x16x32_bf16 v[106:109], v[204:207], v[158:161], v[106:109]
	v_mfma_f32_16x16x32_bf16 v[98:101], v[224:227], v[158:161], v[98:101]
	v_mfma_f32_16x16x32_bf16 v[90:93], v[204:207], v[166:169], v[90:93]
	v_mfma_f32_16x16x32_bf16 v[82:85], v[224:227], v[166:169], v[82:85]
	v_mfma_f32_16x16x32_bf16 v[78:81], v[204:207], v[174:177], v[78:81]
	v_mfma_f32_16x16x32_bf16 v[74:77], v[224:227], v[174:177], v[74:77]
	v_mfma_f32_16x16x32_bf16 v[70:73], v[204:207], v[196:199], v[70:73]
	v_mfma_f32_16x16x32_bf16 v[66:69], v[224:227], v[196:199], v[66:69]
	v_mfma_f32_16x16x32_bf16 v[106:109], v[208:211], v[162:165], v[106:109]
	v_mfma_f32_16x16x32_bf16 v[98:101], v[228:231], v[162:165], v[98:101]
	v_mfma_f32_16x16x32_bf16 v[90:93], v[208:211], v[170:173], v[90:93]
	v_mfma_f32_16x16x32_bf16 v[82:85], v[228:231], v[170:173], v[82:85]
	v_mfma_f32_16x16x32_bf16 v[78:81], v[208:211], v[192:195], v[78:81]
	v_mfma_f32_16x16x32_bf16 v[74:77], v[228:231], v[192:195], v[74:77]
	v_mfma_f32_16x16x32_bf16 v[70:73], v[208:211], v[200:203], v[70:73]
	v_mfma_f32_16x16x32_bf16 v[66:69], v[228:231], v[200:203], v[66:69]
	s_barrier
	ds_read_b128 v[158:161], v140 offset:16384
	ds_read_b128 v[162:165], v140 offset:17408
	ds_read_b128 v[166:169], v140 offset:18432
	ds_read_b128 v[170:173], v140 offset:19456
	ds_read_b128 v[174:177], v140 offset:20480
	ds_read_b128 v[192:195], v140 offset:21504
	ds_read_b128 v[196:199], v140 offset:22528
	ds_read_b128 v[200:203], v140 offset:23552
	global_load_lds_dwordx4 v[232:233], off
	v_lshl_add_u64 v[234:235], s[22:23], 0, v[130:131]
	s_mov_b32 m0, s28
	s_nop 0
	global_load_lds_dwordx4 v[234:235], off
	s_waitcnt vmcnt(10)
	s_barrier
	s_waitcnt lgkmcnt(0)
	v_mfma_f32_16x16x32_bf16 v[62:65], v[142:145], v[158:161], v[62:65]
	v_mfma_f32_16x16x32_bf16 v[58:61], v[150:153], v[158:161], v[58:61]
	v_mfma_f32_16x16x32_bf16 v[54:57], v[142:145], v[166:169], v[54:57]
	v_mfma_f32_16x16x32_bf16 v[50:53], v[150:153], v[166:169], v[50:53]
	v_mfma_f32_16x16x32_bf16 v[46:49], v[142:145], v[174:177], v[46:49]
	v_mfma_f32_16x16x32_bf16 v[38:41], v[150:153], v[174:177], v[38:41]
	v_mfma_f32_16x16x32_bf16 v[30:33], v[142:145], v[196:199], v[30:33]
	v_mfma_f32_16x16x32_bf16 v[22:25], v[150:153], v[196:199], v[22:25]
	v_mfma_f32_16x16x32_bf16 v[62:65], v[146:149], v[162:165], v[62:65]
	v_mfma_f32_16x16x32_bf16 v[58:61], v[154:157], v[162:165], v[58:61]
	v_mfma_f32_16x16x32_bf16 v[54:57], v[146:149], v[170:173], v[54:57]
	v_mfma_f32_16x16x32_bf16 v[50:53], v[154:157], v[170:173], v[50:53]
	v_mfma_f32_16x16x32_bf16 v[46:49], v[146:149], v[192:195], v[46:49]
	v_mfma_f32_16x16x32_bf16 v[38:41], v[154:157], v[192:195], v[38:41]
	v_mfma_f32_16x16x32_bf16 v[30:33], v[146:149], v[200:203], v[30:33]
	v_mfma_f32_16x16x32_bf16 v[22:25], v[154:157], v[200:203], v[22:25]
	s_barrier
	s_add_u32 s52, s82, 0x80000
	s_addc_u32 s53, s83, 0
	s_add_i32 s54, s54, s26
	v_lshl_add_u64 v[142:143], s[52:53], 0, v[132:133]
	s_mov_b32 m0, s54
	s_nop 0
	global_load_lds_dwordx4 v[142:143], off
	v_lshl_add_u64 v[142:143], s[52:53], 0, v[130:131]
	s_add_i32 m0, s54, 0x2000
	s_nop 0
	global_load_lds_dwordx4 v[142:143], off
	v_add_u32_e32 v141, 0x18000, v138
	ds_read_b128 v[142:145], v141
	ds_read_b128 v[146:149], v141 offset:1024
	ds_read_b128 v[150:153], v141 offset:2048
	ds_read_b128 v[154:157], v141 offset:3072
	s_add_i32 s52, 0, 0x18000
	s_waitcnt vmcnt(6)
	s_barrier
	v_mfma_f32_16x16x32_bf16 v[42:45], v[204:207], v[158:161], v[42:45]
	v_mfma_f32_16x16x32_bf16 v[34:37], v[224:227], v[158:161], v[34:37]
	v_mfma_f32_16x16x32_bf16 v[26:29], v[204:207], v[166:169], v[26:29]
	v_mfma_f32_16x16x32_bf16 v[18:21], v[224:227], v[166:169], v[18:21]
	v_mfma_f32_16x16x32_bf16 v[14:17], v[204:207], v[174:177], v[14:17]
	v_mfma_f32_16x16x32_bf16 v[10:13], v[224:227], v[174:177], v[10:13]
	v_mfma_f32_16x16x32_bf16 v[6:9], v[204:207], v[196:199], v[6:9]
	v_mfma_f32_16x16x32_bf16 v[2:5], v[224:227], v[196:199], v[2:5]
	v_mfma_f32_16x16x32_bf16 v[42:45], v[208:211], v[162:165], v[42:45]
	v_mfma_f32_16x16x32_bf16 v[34:37], v[228:231], v[162:165], v[34:37]
	v_mfma_f32_16x16x32_bf16 v[26:29], v[208:211], v[170:173], v[26:29]
	v_mfma_f32_16x16x32_bf16 v[18:21], v[228:231], v[170:173], v[18:21]
	v_mfma_f32_16x16x32_bf16 v[14:17], v[208:211], v[192:195], v[14:17]
	v_mfma_f32_16x16x32_bf16 v[10:13], v[228:231], v[192:195], v[10:13]
	v_mfma_f32_16x16x32_bf16 v[6:9], v[208:211], v[200:203], v[6:9]
	v_mfma_f32_16x16x32_bf16 v[2:5], v[228:231], v[200:203], v[2:5]
	s_barrier
	ds_read_b128 v[158:161], v140 offset:32768
	ds_read_b128 v[162:165], v140 offset:33792
	ds_read_b128 v[166:169], v140 offset:34816
	ds_read_b128 v[170:173], v140 offset:35840
	ds_read_b128 v[174:177], v140 offset:36864
	ds_read_b128 v[192:195], v140 offset:37888
	ds_read_b128 v[196:199], v140 offset:38912
	ds_read_b128 v[200:203], v140 offset:39936
	s_add_u32 s22, s22, 0x80000
	s_addc_u32 s23, s23, 0
	s_mov_b32 m0, s29
	v_lshl_add_u64 v[204:205], s[22:23], 0, v[132:133]
	global_load_lds_dwordx4 v[204:205], off
	v_lshl_add_u64 v[204:205], s[22:23], 0, v[130:131]
	s_mov_b32 m0, s36
	s_nop 0
	global_load_lds_dwordx4 v[204:205], off
	s_waitcnt lgkmcnt(8)
	s_barrier
	s_waitcnt lgkmcnt(0)
	v_mfma_f32_16x16x32_bf16 v[126:129], v[142:145], v[158:161], v[126:129]
	v_mfma_f32_16x16x32_bf16 v[122:125], v[150:153], v[158:161], v[122:125]
	v_mfma_f32_16x16x32_bf16 v[118:121], v[142:145], v[166:169], v[118:121]
	v_mfma_f32_16x16x32_bf16 v[114:117], v[150:153], v[166:169], v[114:117]
	v_mfma_f32_16x16x32_bf16 v[110:113], v[142:145], v[174:177], v[110:113]
	v_mfma_f32_16x16x32_bf16 v[102:105], v[150:153], v[174:177], v[102:105]
	v_mfma_f32_16x16x32_bf16 v[94:97], v[142:145], v[196:199], v[94:97]
	v_mfma_f32_16x16x32_bf16 v[86:89], v[150:153], v[196:199], v[86:89]
	v_mfma_f32_16x16x32_bf16 v[126:129], v[146:149], v[162:165], v[126:129]
	v_mfma_f32_16x16x32_bf16 v[122:125], v[154:157], v[162:165], v[122:125]
	v_mfma_f32_16x16x32_bf16 v[118:121], v[146:149], v[170:173], v[118:121]
	v_mfma_f32_16x16x32_bf16 v[114:117], v[154:157], v[170:173], v[114:117]
	v_mfma_f32_16x16x32_bf16 v[110:113], v[146:149], v[192:195], v[110:113]
	v_mfma_f32_16x16x32_bf16 v[102:105], v[154:157], v[192:195], v[102:105]
	v_mfma_f32_16x16x32_bf16 v[94:97], v[146:149], v[200:203], v[94:97]
	v_mfma_f32_16x16x32_bf16 v[86:89], v[154:157], v[200:203], v[86:89]
	s_barrier
	s_add_i32 s53, 0, 0x1c000
	s_add_i32 s22, s52, s26
	v_add_u32_e32 v141, s53, v138
	v_lshl_add_u64 v[178:179], v[178:179], 0, s[78:79]
	s_mov_b32 m0, s22
	ds_read_b128 v[204:207], v141
	ds_read_b128 v[208:211], v141 offset:1024
	ds_read_b128 v[224:227], v141 offset:2048
	ds_read_b128 v[228:231], v141 offset:3072
	global_load_lds_dwordx4 v[178:179], off
	v_lshl_add_u64 v[178:179], v[212:213], 0, s[78:79]
	s_add_i32 m0, s22, 0x2000
	s_nop 0
	global_load_lds_dwordx4 v[178:179], off
	s_mov_b32 m0, s42
	v_lshl_add_u64 v[178:179], v[232:233], 0, s[78:79]
	s_barrier
	s_waitcnt lgkmcnt(0)
	v_mfma_f32_16x16x32_bf16 v[106:109], v[204:207], v[158:161], v[106:109]
	v_mfma_f32_16x16x32_bf16 v[98:101], v[224:227], v[158:161], v[98:101]
	v_mfma_f32_16x16x32_bf16 v[90:93], v[204:207], v[166:169], v[90:93]
	v_mfma_f32_16x16x32_bf16 v[82:85], v[224:227], v[166:169], v[82:85]
	v_mfma_f32_16x16x32_bf16 v[78:81], v[204:207], v[174:177], v[78:81]
	v_mfma_f32_16x16x32_bf16 v[74:77], v[224:227], v[174:177], v[74:77]
	v_mfma_f32_16x16x32_bf16 v[70:73], v[204:207], v[196:199], v[70:73]
	v_mfma_f32_16x16x32_bf16 v[66:69], v[224:227], v[196:199], v[66:69]
	v_mfma_f32_16x16x32_bf16 v[106:109], v[208:211], v[162:165], v[106:109]
	v_mfma_f32_16x16x32_bf16 v[98:101], v[228:231], v[162:165], v[98:101]
	v_mfma_f32_16x16x32_bf16 v[90:93], v[208:211], v[170:173], v[90:93]
	v_mfma_f32_16x16x32_bf16 v[82:85], v[228:231], v[170:173], v[82:85]
	v_mfma_f32_16x16x32_bf16 v[78:81], v[208:211], v[192:195], v[78:81]
	v_mfma_f32_16x16x32_bf16 v[74:77], v[228:231], v[192:195], v[74:77]
	v_mfma_f32_16x16x32_bf16 v[70:73], v[208:211], v[200:203], v[70:73]
	v_mfma_f32_16x16x32_bf16 v[66:69], v[228:231], v[200:203], v[66:69]
	s_barrier
	ds_read_b128 v[158:161], v140 offset:49152
	ds_read_b128 v[162:165], v140 offset:50176
	ds_read_b128 v[166:169], v140 offset:51200
	ds_read_b128 v[170:173], v140 offset:52224
	ds_read_b128 v[174:177], v140 offset:53248
	ds_read_b128 v[192:195], v140 offset:54272
	ds_read_b128 v[196:199], v140 offset:55296
	ds_read_b128 v[200:203], v140 offset:56320
	global_load_lds_dwordx4 v[178:179], off
	v_lshl_add_u64 v[178:179], v[234:235], 0, s[78:79]
	s_mov_b32 m0, s43
	s_nop 0
	global_load_lds_dwordx4 v[178:179], off
	s_waitcnt vmcnt(10)
	s_barrier
	s_waitcnt lgkmcnt(0)
	v_mfma_f32_16x16x32_bf16 v[62:65], v[142:145], v[158:161], v[62:65]
	v_mfma_f32_16x16x32_bf16 v[58:61], v[150:153], v[158:161], v[58:61]
	v_mfma_f32_16x16x32_bf16 v[54:57], v[142:145], v[166:169], v[54:57]
	v_mfma_f32_16x16x32_bf16 v[50:53], v[150:153], v[166:169], v[50:53]
	v_mfma_f32_16x16x32_bf16 v[46:49], v[142:145], v[174:177], v[46:49]
	v_mfma_f32_16x16x32_bf16 v[38:41], v[150:153], v[174:177], v[38:41]
	v_mfma_f32_16x16x32_bf16 v[30:33], v[142:145], v[196:199], v[30:33]
	v_mfma_f32_16x16x32_bf16 v[22:25], v[150:153], v[196:199], v[22:25]
	v_mfma_f32_16x16x32_bf16 v[62:65], v[146:149], v[162:165], v[62:65]
	v_mfma_f32_16x16x32_bf16 v[58:61], v[154:157], v[162:165], v[58:61]
	v_mfma_f32_16x16x32_bf16 v[54:57], v[146:149], v[170:173], v[54:57]
	v_mfma_f32_16x16x32_bf16 v[50:53], v[154:157], v[170:173], v[50:53]
	v_mfma_f32_16x16x32_bf16 v[46:49], v[146:149], v[192:195], v[46:49]
	v_mfma_f32_16x16x32_bf16 v[38:41], v[154:157], v[192:195], v[38:41]
	v_mfma_f32_16x16x32_bf16 v[30:33], v[146:149], v[200:203], v[30:33]
	v_mfma_f32_16x16x32_bf16 v[22:25], v[154:157], v[200:203], v[22:25]
	s_barrier
	s_add_u32 s22, s82, 0x80080
	s_addc_u32 s23, s83, 0
	s_add_i32 s52, s53, s26
	v_lshl_add_u64 v[142:143], s[22:23], 0, v[132:133]
	s_mov_b32 m0, s52
	s_nop 0
	global_load_lds_dwordx4 v[142:143], off
	v_lshl_add_u64 v[142:143], s[22:23], 0, v[130:131]
	s_add_i32 m0, s52, 0x2000
	s_nop 0
	global_load_lds_dwordx4 v[142:143], off
	v_add_u32_e32 v141, 0x10000, v138
	ds_read_b128 v[142:145], v141
	ds_read_b128 v[146:149], v141 offset:1024
	ds_read_b128 v[150:153], v141 offset:2048
	ds_read_b128 v[154:157], v141 offset:3072
	s_add_i32 s51, s51, 2
	s_add_u32 s80, s80, 0x100
	s_addc_u32 s81, s81, 0
	s_add_u32 s49, s49, 0x100
	s_addc_u32 s50, s50, 0
	s_cmp_gt_u32 s51, 29
	s_waitcnt vmcnt(6)
	s_barrier
	v_mfma_f32_16x16x32_bf16 v[42:45], v[204:207], v[158:161], v[42:45]
	v_mfma_f32_16x16x32_bf16 v[34:37], v[224:227], v[158:161], v[34:37]
	v_mfma_f32_16x16x32_bf16 v[26:29], v[204:207], v[166:169], v[26:29]
	v_mfma_f32_16x16x32_bf16 v[18:21], v[224:227], v[166:169], v[18:21]
	v_mfma_f32_16x16x32_bf16 v[14:17], v[204:207], v[174:177], v[14:17]
	v_mfma_f32_16x16x32_bf16 v[10:13], v[224:227], v[174:177], v[10:13]
	v_mfma_f32_16x16x32_bf16 v[6:9], v[204:207], v[196:199], v[6:9]
	v_mfma_f32_16x16x32_bf16 v[2:5], v[224:227], v[196:199], v[2:5]
	v_mfma_f32_16x16x32_bf16 v[42:45], v[208:211], v[162:165], v[42:45]
	v_mfma_f32_16x16x32_bf16 v[34:37], v[228:231], v[162:165], v[34:37]
	v_mfma_f32_16x16x32_bf16 v[26:29], v[208:211], v[170:173], v[26:29]
	v_mfma_f32_16x16x32_bf16 v[18:21], v[228:231], v[170:173], v[18:21]
	v_mfma_f32_16x16x32_bf16 v[14:17], v[208:211], v[192:195], v[14:17]
	v_mfma_f32_16x16x32_bf16 v[10:13], v[228:231], v[192:195], v[10:13]
	v_mfma_f32_16x16x32_bf16 v[6:9], v[208:211], v[200:203], v[6:9]
	v_mfma_f32_16x16x32_bf16 v[2:5], v[228:231], v[200:203], v[2:5]
	s_barrier
	s_cbranch_scc0 .LBB0_240
	s_waitcnt lgkmcnt(0)
	v_readlane_b32 s48, v254, 40
	v_lshl_or_b32 v142, s45, 8, v139
	v_readlane_b32 s52, v254, 44
	v_readlane_b32 s53, v254, 45
	v_lshl_add_u32 v141, s46, 8, v1
	v_ashrrev_i32_e32 v143, 31, v142
	v_mov_b64_e32 v[144:145], s[52:53]
	s_movk_i32 s19, 0x1400
	v_mad_i64_i32 v[146:147], s[22:23], v141, s19, v[144:145]
	v_lshlrev_b64 v[142:143], 2, v[142:143]
	v_lshl_add_u64 v[146:147], v[146:147], 0, v[142:143]
	global_store_dwordx4 v[146:147], v[126:129], off
	global_store_dwordx4 v[146:147], v[122:125], off offset:64
	global_store_dwordx4 v[146:147], v[106:109], off offset:512
	global_store_dwordx4 v[146:147], v[98:101], off offset:576
	s_movk_i32 s94, 0x1400
	s_and_b64 vcc, exec, s[0:1]
	v_or_b32_e32 v98, 16, v141
	v_mad_i64_i32 v[98:99], s[22:23], v98, s19, v[144:145]
	v_lshl_add_u64 v[98:99], v[98:99], 0, v[142:143]
	global_store_dwordx4 v[98:99], v[118:121], off
	global_store_dwordx4 v[98:99], v[114:117], off offset:64
	global_store_dwordx4 v[98:99], v[90:93], off offset:512
	global_store_dwordx4 v[98:99], v[82:85], off offset:576
	s_mov_b32 s45, s18
	s_mov_b32 s46, s20
	v_or_b32_e32 v82, 32, v141
	v_mad_i64_i32 v[82:83], s[22:23], v82, s19, v[144:145]
	v_lshl_add_u64 v[82:83], v[82:83], 0, v[142:143]
	global_store_dwordx4 v[82:83], v[110:113], off
	global_store_dwordx4 v[82:83], v[102:105], off offset:64
	global_store_dwordx4 v[82:83], v[78:81], off offset:512
	global_store_dwordx4 v[82:83], v[74:77], off offset:576
	s_mov_b64 s[80:81], s[30:31]
	v_readlane_b32 s49, v254, 41
	v_or_b32_e32 v74, 48, v141
	v_mad_i64_i32 v[74:75], s[22:23], v74, s19, v[144:145]
	v_lshl_add_u64 v[74:75], v[74:75], 0, v[142:143]
	global_store_dwordx4 v[74:75], v[94:97], off
	global_store_dwordx4 v[74:75], v[86:89], off offset:64
	global_store_dwordx4 v[74:75], v[70:73], off offset:512
	global_store_dwordx4 v[74:75], v[66:69], off offset:576
	v_readlane_b32 s50, v254, 42
	v_readlane_b32 s51, v254, 43
	v_add_u32_e32 v66, 0x80, v141
	v_mad_i64_i32 v[66:67], s[22:23], v66, s19, v[144:145]
	v_lshl_add_u64 v[66:67], v[66:67], 0, v[142:143]
	global_store_dwordx4 v[66:67], v[62:65], off
	global_store_dwordx4 v[66:67], v[58:61], off offset:64
	global_store_dwordx4 v[66:67], v[42:45], off offset:512
	global_store_dwordx4 v[66:67], v[34:37], off offset:576
	v_readlane_b32 s54, v254, 46
	v_readlane_b32 s55, v254, 47
	v_add_u32_e32 v34, 0x90, v141
	v_mad_i64_i32 v[34:35], s[22:23], v34, s19, v[144:145]
	v_lshl_add_u64 v[34:35], v[34:35], 0, v[142:143]
	global_store_dwordx4 v[34:35], v[54:57], off
	global_store_dwordx4 v[34:35], v[50:53], off offset:64
	global_store_dwordx4 v[34:35], v[26:29], off offset:512
	global_store_dwordx4 v[34:35], v[18:21], off offset:576
	v_readlane_b32 s56, v254, 48
	v_readlane_b32 s57, v254, 49
	v_add_u32_e32 v18, 0xa0, v141
	v_mad_i64_i32 v[18:19], s[22:23], v18, s19, v[144:145]
	v_lshl_add_u64 v[18:19], v[18:19], 0, v[142:143]
	global_store_dwordx4 v[18:19], v[46:49], off
	global_store_dwordx4 v[18:19], v[38:41], off offset:64
	global_store_dwordx4 v[18:19], v[14:17], off offset:512
	global_store_dwordx4 v[18:19], v[10:13], off offset:576
	v_readlane_b32 s58, v254, 50
	v_readlane_b32 s59, v254, 51
	v_add_u32_e32 v10, 0xb0, v141
	v_mad_i64_i32 v[10:11], s[22:23], v10, s19, v[144:145]
	v_lshl_add_u64 v[10:11], v[10:11], 0, v[142:143]
	s_mov_b64 s[22:23], s[38:39]
	v_readlane_b32 s60, v254, 52
	v_readlane_b32 s61, v254, 53
	v_readlane_b32 s62, v254, 54
	v_readlane_b32 s63, v254, 55
	global_store_dwordx4 v[10:11], v[30:33], off
	global_store_dwordx4 v[10:11], v[22:25], off offset:64
	global_store_dwordx4 v[10:11], v[6:9], off offset:512
	global_store_dwordx4 v[10:11], v[2:5], off offset:576
	s_cbranch_vccz .LBB0_237
	s_waitcnt vmcnt(0)
	v_readlane_b32 s44, v255, 30
	s_cmpk_gt_u32 s25, 0xff
	v_readlane_b32 s45, v255, 31
	v_readlane_b32 s42, v255, 32
	s_cbranch_scc1 .LBB0_244
	s_barrier

.LBB0_357:
	ds_read_b128 v[162:165], v144
	ds_read_b128 v[166:169], v144 offset:1024
	ds_read_b128 v[170:173], v144 offset:2048
	ds_read_b128 v[174:177], v144 offset:3072
	ds_read_b128 v[192:195], v144 offset:4096
	ds_read_b128 v[196:199], v144 offset:5120
	ds_read_b128 v[200:203], v144 offset:6144
	ds_read_b128 v[204:207], v144 offset:7168
	s_add_u32 s22, s20, 0xfffe0080
	s_addc_u32 s23, s21, -1
	s_add_i32 s52, 0, 0x10000
	s_cmp_eq_u32 s51, 4
	s_cselect_b32 s23, s31, s23
	s_cselect_b32 s22, s47, s22
	s_cselect_b32 s85, s19, s50
	s_cselect_b32 s84, s48, s49
	v_lshl_add_u64 v[178:179], s[20:21], 0, v[138:139]
	s_add_i32 m0, s27, 0xc000
	s_nop 0
	global_load_lds_dwordx4 v[178:179], off
	v_lshl_add_u64 v[178:179], s[20:21], 0, v[140:141]
	s_add_i32 m0, s27, 0xe000
	s_nop 0
	global_load_lds_dwordx4 v[178:179], off
	s_waitcnt lgkmcnt(8)
	s_barrier
	s_waitcnt lgkmcnt(0)
	v_mfma_f32_16x16x32_bf16 v[126:129], v[146:149], v[162:165], v[126:129]
	v_mfma_f32_16x16x32_bf16 v[122:125], v[154:157], v[162:165], v[122:125]
	v_mfma_f32_16x16x32_bf16 v[118:121], v[146:149], v[170:173], v[118:121]
	v_mfma_f32_16x16x32_bf16 v[114:117], v[154:157], v[170:173], v[114:117]
	v_mfma_f32_16x16x32_bf16 v[102:105], v[146:149], v[192:195], v[102:105]
	v_mfma_f32_16x16x32_bf16 v[98:101], v[154:157], v[192:195], v[98:101]
	v_mfma_f32_16x16x32_bf16 v[86:89], v[146:149], v[200:203], v[86:89]
	v_mfma_f32_16x16x32_bf16 v[82:85], v[154:157], v[200:203], v[82:85]
	v_mfma_f32_16x16x32_bf16 v[126:129], v[150:153], v[166:169], v[126:129]
	v_mfma_f32_16x16x32_bf16 v[122:125], v[158:161], v[166:169], v[122:125]
	v_mfma_f32_16x16x32_bf16 v[118:121], v[150:153], v[174:177], v[118:121]
	v_mfma_f32_16x16x32_bf16 v[114:117], v[158:161], v[174:177], v[114:117]
	v_mfma_f32_16x16x32_bf16 v[102:105], v[150:153], v[196:199], v[102:105]
	v_mfma_f32_16x16x32_bf16 v[98:101], v[158:161], v[196:199], v[98:101]
	v_mfma_f32_16x16x32_bf16 v[86:89], v[150:153], v[204:207], v[86:89]
	v_mfma_f32_16x16x32_bf16 v[82:85], v[158:161], v[204:207], v[82:85]
	s_barrier
	s_add_i32 s54, 0, 0x14000
	s_add_i32 s52, s52, s26
	v_add_u32_e32 v145, s54, v142
	v_lshl_add_u64 v[178:179], s[84:85], 0, v[134:135]
	s_mov_b32 m0, s52
	ds_read_b128 v[208:211], v145
	ds_read_b128 v[224:227], v145 offset:1024
	ds_read_b128 v[228:231], v145 offset:2048
	ds_read_b128 v[232:235], v145 offset:3072
	global_load_lds_dwordx4 v[178:179], off
	v_lshl_add_u64 v[212:213], s[84:85], 0, v[130:131]
	s_add_i32 m0, s52, 0x2000
	s_nop 0
	global_load_lds_dwordx4 v[212:213], off
	s_mov_b32 m0, s27
	v_lshl_add_u64 v[236:237], s[22:23], 0, v[136:137]
	s_barrier
	s_waitcnt lgkmcnt(0)
	v_mfma_f32_16x16x32_bf16 v[110:113], v[208:211], v[162:165], v[110:113]
	v_mfma_f32_16x16x32_bf16 v[106:109], v[228:231], v[162:165], v[106:109]
	v_mfma_f32_16x16x32_bf16 v[94:97], v[208:211], v[170:173], v[94:97]
	v_mfma_f32_16x16x32_bf16 v[90:93], v[228:231], v[170:173], v[90:93]
	v_mfma_f32_16x16x32_bf16 v[78:81], v[208:211], v[192:195], v[78:81]
	v_mfma_f32_16x16x32_bf16 v[74:77], v[228:231], v[192:195], v[74:77]
	v_mfma_f32_16x16x32_bf16 v[70:73], v[208:211], v[200:203], v[70:73]
	v_mfma_f32_16x16x32_bf16 v[66:69], v[228:231], v[200:203], v[66:69]
	v_mfma_f32_16x16x32_bf16 v[110:113], v[224:227], v[166:169], v[110:113]
	v_mfma_f32_16x16x32_bf16 v[106:109], v[232:235], v[166:169], v[106:109]
	v_mfma_f32_16x16x32_bf16 v[94:97], v[224:227], v[174:177], v[94:97]
	v_mfma_f32_16x16x32_bf16 v[90:93], v[232:235], v[174:177], v[90:93]
	v_mfma_f32_16x16x32_bf16 v[78:81], v[224:227], v[196:199], v[78:81]
	v_mfma_f32_16x16x32_bf16 v[74:77], v[232:235], v[196:199], v[74:77]
	v_mfma_f32_16x16x32_bf16 v[70:73], v[224:227], v[204:207], v[70:73]
	v_mfma_f32_16x16x32_bf16 v[66:69], v[232:235], v[204:207], v[66:69]
	s_barrier
	ds_read_b128 v[162:165], v144 offset:16384
	ds_read_b128 v[166:169], v144 offset:17408
	ds_read_b128 v[170:173], v144 offset:18432
	ds_read_b128 v[174:177], v144 offset:19456
	ds_read_b128 v[192:195], v144 offset:20480
	ds_read_b128 v[196:199], v144 offset:21504
	ds_read_b128 v[200:203], v144 offset:22528
	ds_read_b128 v[204:207], v144 offset:23552
	global_load_lds_dwordx4 v[236:237], off
	v_lshl_add_u64 v[238:239], s[22:23], 0, v[132:133]
	s_mov_b32 m0, s28
	s_nop 0
	global_load_lds_dwordx4 v[238:239], off
	s_waitcnt vmcnt(10)
	s_barrier
	s_waitcnt lgkmcnt(0)
	v_mfma_f32_16x16x32_bf16 v[62:65], v[146:149], v[162:165], v[62:65]
	v_mfma_f32_16x16x32_bf16 v[58:61], v[154:157], v[162:165], v[58:61]
	v_mfma_f32_16x16x32_bf16 v[54:57], v[146:149], v[170:173], v[54:57]
	v_mfma_f32_16x16x32_bf16 v[50:53], v[154:157], v[170:173], v[50:53]
	v_mfma_f32_16x16x32_bf16 v[38:41], v[146:149], v[192:195], v[38:41]
	v_mfma_f32_16x16x32_bf16 v[34:37], v[154:157], v[192:195], v[34:37]
	v_mfma_f32_16x16x32_bf16 v[22:25], v[146:149], v[200:203], v[22:25]
	v_mfma_f32_16x16x32_bf16 v[18:21], v[154:157], v[200:203], v[18:21]
	v_mfma_f32_16x16x32_bf16 v[62:65], v[150:153], v[166:169], v[62:65]
	v_mfma_f32_16x16x32_bf16 v[58:61], v[158:161], v[166:169], v[58:61]
	v_mfma_f32_16x16x32_bf16 v[54:57], v[150:153], v[174:177], v[54:57]
	v_mfma_f32_16x16x32_bf16 v[50:53], v[158:161], v[174:177], v[50:53]
	v_mfma_f32_16x16x32_bf16 v[38:41], v[150:153], v[196:199], v[38:41]
	v_mfma_f32_16x16x32_bf16 v[34:37], v[158:161], v[196:199], v[34:37]
	v_mfma_f32_16x16x32_bf16 v[22:25], v[150:153], v[204:207], v[22:25]
	v_mfma_f32_16x16x32_bf16 v[18:21], v[158:161], v[204:207], v[18:21]
	s_barrier
	s_add_u32 s52, s84, 0x20000
	s_addc_u32 s53, s85, 0
	s_add_i32 s54, s54, s26
	v_lshl_add_u64 v[146:147], s[52:53], 0, v[134:135]
	s_mov_b32 m0, s54
	s_nop 0
	global_load_lds_dwordx4 v[146:147], off
	v_lshl_add_u64 v[146:147], s[52:53], 0, v[130:131]
	s_add_i32 m0, s54, 0x2000
	s_nop 0
	global_load_lds_dwordx4 v[146:147], off
	v_add_u32_e32 v145, 0x18000, v142
	ds_read_b128 v[146:149], v145
	ds_read_b128 v[150:153], v145 offset:1024
	ds_read_b128 v[154:157], v145 offset:2048
	ds_read_b128 v[158:161], v145 offset:3072
	s_add_i32 s52, 0, 0x18000
	s_waitcnt vmcnt(6)
	s_barrier
	v_mfma_f32_16x16x32_bf16 v[46:49], v[208:211], v[162:165], v[46:49]
	v_mfma_f32_16x16x32_bf16 v[42:45], v[228:231], v[162:165], v[42:45]
	v_mfma_f32_16x16x32_bf16 v[30:33], v[208:211], v[170:173], v[30:33]
	v_mfma_f32_16x16x32_bf16 v[26:29], v[228:231], v[170:173], v[26:29]
	v_mfma_f32_16x16x32_bf16 v[14:17], v[208:211], v[192:195], v[14:17]
	v_mfma_f32_16x16x32_bf16 v[10:13], v[228:231], v[192:195], v[10:13]
	v_mfma_f32_16x16x32_bf16 v[6:9], v[208:211], v[200:203], v[6:9]
	v_mfma_f32_16x16x32_bf16 v[2:5], v[228:231], v[200:203], v[2:5]
	v_mfma_f32_16x16x32_bf16 v[46:49], v[224:227], v[166:169], v[46:49]
	v_mfma_f32_16x16x32_bf16 v[42:45], v[232:235], v[166:169], v[42:45]
	v_mfma_f32_16x16x32_bf16 v[30:33], v[224:227], v[174:177], v[30:33]
	v_mfma_f32_16x16x32_bf16 v[26:29], v[232:235], v[174:177], v[26:29]
	v_mfma_f32_16x16x32_bf16 v[14:17], v[224:227], v[196:199], v[14:17]
	v_mfma_f32_16x16x32_bf16 v[10:13], v[232:235], v[196:199], v[10:13]
	v_mfma_f32_16x16x32_bf16 v[6:9], v[224:227], v[204:207], v[6:9]
	v_mfma_f32_16x16x32_bf16 v[2:5], v[232:235], v[204:207], v[2:5]
	s_barrier
	ds_read_b128 v[162:165], v144 offset:32768
	ds_read_b128 v[166:169], v144 offset:33792
	ds_read_b128 v[170:173], v144 offset:34816
	ds_read_b128 v[174:177], v144 offset:35840
	ds_read_b128 v[192:195], v144 offset:36864
	ds_read_b128 v[196:199], v144 offset:37888
	ds_read_b128 v[200:203], v144 offset:38912
	ds_read_b128 v[204:207], v144 offset:39936
	s_add_u32 s22, s22, 0x20000
	s_addc_u32 s23, s23, 0
	s_mov_b32 m0, s29
	v_lshl_add_u64 v[208:209], s[22:23], 0, v[136:137]
	global_load_lds_dwordx4 v[208:209], off
	v_lshl_add_u64 v[208:209], s[22:23], 0, v[132:133]
	s_mov_b32 m0, s36
	s_nop 0
	global_load_lds_dwordx4 v[208:209], off
	s_waitcnt lgkmcnt(8)
	s_barrier
	s_waitcnt lgkmcnt(0)
	v_mfma_f32_16x16x32_bf16 v[126:129], v[146:149], v[162:165], v[126:129]
	v_mfma_f32_16x16x32_bf16 v[122:125], v[154:157], v[162:165], v[122:125]
	v_mfma_f32_16x16x32_bf16 v[118:121], v[146:149], v[170:173], v[118:121]
	v_mfma_f32_16x16x32_bf16 v[114:117], v[154:157], v[170:173], v[114:117]
	v_mfma_f32_16x16x32_bf16 v[102:105], v[146:149], v[192:195], v[102:105]
	v_mfma_f32_16x16x32_bf16 v[98:101], v[154:157], v[192:195], v[98:101]
	v_mfma_f32_16x16x32_bf16 v[86:89], v[146:149], v[200:203], v[86:89]
	v_mfma_f32_16x16x32_bf16 v[82:85], v[154:157], v[200:203], v[82:85]
	v_mfma_f32_16x16x32_bf16 v[126:129], v[150:153], v[166:169], v[126:129]
	v_mfma_f32_16x16x32_bf16 v[122:125], v[158:161], v[166:169], v[122:125]
	v_mfma_f32_16x16x32_bf16 v[118:121], v[150:153], v[174:177], v[118:121]
	v_mfma_f32_16x16x32_bf16 v[114:117], v[158:161], v[174:177], v[114:117]
	v_mfma_f32_16x16x32_bf16 v[102:105], v[150:153], v[196:199], v[102:105]
	v_mfma_f32_16x16x32_bf16 v[98:101], v[158:161], v[196:199], v[98:101]
	v_mfma_f32_16x16x32_bf16 v[86:89], v[150:153], v[204:207], v[86:89]
	v_mfma_f32_16x16x32_bf16 v[82:85], v[158:161], v[204:207], v[82:85]
	s_barrier
	s_add_i32 s53, 0, 0x1c000
	s_add_i32 s22, s52, s26
	v_add_u32_e32 v145, s53, v142
	v_lshl_add_u64 v[178:179], v[178:179], 0, s[78:79]
	s_mov_b32 m0, s22
	ds_read_b128 v[208:211], v145
	ds_read_b128 v[224:227], v145 offset:1024
	ds_read_b128 v[228:231], v145 offset:2048
	ds_read_b128 v[232:235], v145 offset:3072
	global_load_lds_dwordx4 v[178:179], off
	v_lshl_add_u64 v[178:179], v[212:213], 0, s[78:79]
	s_add_i32 m0, s22, 0x2000
	s_nop 0
	global_load_lds_dwordx4 v[178:179], off
	s_mov_b32 m0, s42
	v_lshl_add_u64 v[178:179], v[236:237], 0, s[78:79]
	s_barrier
	s_waitcnt lgkmcnt(0)
	v_mfma_f32_16x16x32_bf16 v[110:113], v[208:211], v[162:165], v[110:113]
	v_mfma_f32_16x16x32_bf16 v[106:109], v[228:231], v[162:165], v[106:109]
	v_mfma_f32_16x16x32_bf16 v[94:97], v[208:211], v[170:173], v[94:97]
	v_mfma_f32_16x16x32_bf16 v[90:93], v[228:231], v[170:173], v[90:93]
	v_mfma_f32_16x16x32_bf16 v[78:81], v[208:211], v[192:195], v[78:81]
	v_mfma_f32_16x16x32_bf16 v[74:77], v[228:231], v[192:195], v[74:77]
	v_mfma_f32_16x16x32_bf16 v[70:73], v[208:211], v[200:203], v[70:73]
	v_mfma_f32_16x16x32_bf16 v[66:69], v[228:231], v[200:203], v[66:69]
	v_mfma_f32_16x16x32_bf16 v[110:113], v[224:227], v[166:169], v[110:113]
	v_mfma_f32_16x16x32_bf16 v[106:109], v[232:235], v[166:169], v[106:109]
	v_mfma_f32_16x16x32_bf16 v[94:97], v[224:227], v[174:177], v[94:97]
	v_mfma_f32_16x16x32_bf16 v[90:93], v[232:235], v[174:177], v[90:93]
	v_mfma_f32_16x16x32_bf16 v[78:81], v[224:227], v[196:199], v[78:81]
	v_mfma_f32_16x16x32_bf16 v[74:77], v[232:235], v[196:199], v[74:77]
	v_mfma_f32_16x16x32_bf16 v[70:73], v[224:227], v[204:207], v[70:73]
	v_mfma_f32_16x16x32_bf16 v[66:69], v[232:235], v[204:207], v[66:69]
	s_barrier
	ds_read_b128 v[162:165], v144 offset:49152
	ds_read_b128 v[166:169], v144 offset:50176
	ds_read_b128 v[170:173], v144 offset:51200
	ds_read_b128 v[174:177], v144 offset:52224
	ds_read_b128 v[192:195], v144 offset:53248
	ds_read_b128 v[196:199], v144 offset:54272
	ds_read_b128 v[200:203], v144 offset:55296
	ds_read_b128 v[204:207], v144 offset:56320
	global_load_lds_dwordx4 v[178:179], off
	v_lshl_add_u64 v[178:179], v[238:239], 0, s[78:79]
	s_mov_b32 m0, s43
	s_nop 0
	global_load_lds_dwordx4 v[178:179], off
	s_waitcnt vmcnt(10)
	s_barrier
	s_waitcnt lgkmcnt(0)
	v_mfma_f32_16x16x32_bf16 v[62:65], v[146:149], v[162:165], v[62:65]
	v_mfma_f32_16x16x32_bf16 v[58:61], v[154:157], v[162:165], v[58:61]
	v_mfma_f32_16x16x32_bf16 v[54:57], v[146:149], v[170:173], v[54:57]
	v_mfma_f32_16x16x32_bf16 v[50:53], v[154:157], v[170:173], v[50:53]
	v_mfma_f32_16x16x32_bf16 v[38:41], v[146:149], v[192:195], v[38:41]
	v_mfma_f32_16x16x32_bf16 v[34:37], v[154:157], v[192:195], v[34:37]
	v_mfma_f32_16x16x32_bf16 v[22:25], v[146:149], v[200:203], v[22:25]
	v_mfma_f32_16x16x32_bf16 v[18:21], v[154:157], v[200:203], v[18:21]
	v_mfma_f32_16x16x32_bf16 v[62:65], v[150:153], v[166:169], v[62:65]
	v_mfma_f32_16x16x32_bf16 v[58:61], v[158:161], v[166:169], v[58:61]
	v_mfma_f32_16x16x32_bf16 v[54:57], v[150:153], v[174:177], v[54:57]
	v_mfma_f32_16x16x32_bf16 v[50:53], v[158:161], v[174:177], v[50:53]
	v_mfma_f32_16x16x32_bf16 v[38:41], v[150:153], v[196:199], v[38:41]
	v_mfma_f32_16x16x32_bf16 v[34:37], v[158:161], v[196:199], v[34:37]
	v_mfma_f32_16x16x32_bf16 v[22:25], v[150:153], v[204:207], v[22:25]
	v_mfma_f32_16x16x32_bf16 v[18:21], v[158:161], v[204:207], v[18:21]
	s_barrier
	s_add_u32 s22, s84, 0x20080
	s_addc_u32 s23, s85, 0
	s_add_i32 s52, s53, s26
	v_lshl_add_u64 v[146:147], s[22:23], 0, v[134:135]
	s_mov_b32 m0, s52
	s_nop 0
	global_load_lds_dwordx4 v[146:147], off
	v_lshl_add_u64 v[146:147], s[22:23], 0, v[130:131]
	s_add_i32 m0, s52, 0x2000
	s_nop 0
	global_load_lds_dwordx4 v[146:147], off
	v_add_u32_e32 v145, 0x10000, v142
	ds_read_b128 v[146:149], v145
	ds_read_b128 v[150:153], v145 offset:1024
	ds_read_b128 v[154:157], v145 offset:2048
	ds_read_b128 v[158:161], v145 offset:3072
	s_add_i32 s51, s51, 2
	s_add_u32 s20, s20, 0x100
	s_addc_u32 s21, s21, 0
	s_add_u32 s49, s49, 0x100
	s_addc_u32 s50, s50, 0
	s_cmp_gt_u32 s51, 5
	s_waitcnt vmcnt(6)
	s_barrier
	v_mfma_f32_16x16x32_bf16 v[46:49], v[208:211], v[162:165], v[46:49]
	v_mfma_f32_16x16x32_bf16 v[42:45], v[228:231], v[162:165], v[42:45]
	v_mfma_f32_16x16x32_bf16 v[30:33], v[208:211], v[170:173], v[30:33]
	v_mfma_f32_16x16x32_bf16 v[26:29], v[228:231], v[170:173], v[26:29]
	v_mfma_f32_16x16x32_bf16 v[14:17], v[208:211], v[192:195], v[14:17]
	v_mfma_f32_16x16x32_bf16 v[10:13], v[228:231], v[192:195], v[10:13]
	v_mfma_f32_16x16x32_bf16 v[6:9], v[208:211], v[200:203], v[6:9]
	v_mfma_f32_16x16x32_bf16 v[2:5], v[228:231], v[200:203], v[2:5]
	v_mfma_f32_16x16x32_bf16 v[46:49], v[224:227], v[166:169], v[46:49]
	v_mfma_f32_16x16x32_bf16 v[42:45], v[232:235], v[166:169], v[42:45]
	v_mfma_f32_16x16x32_bf16 v[30:33], v[224:227], v[174:177], v[30:33]
	v_mfma_f32_16x16x32_bf16 v[26:29], v[232:235], v[174:177], v[26:29]
	v_mfma_f32_16x16x32_bf16 v[14:17], v[224:227], v[196:199], v[14:17]
	v_mfma_f32_16x16x32_bf16 v[10:13], v[232:235], v[196:199], v[10:13]
	v_mfma_f32_16x16x32_bf16 v[6:9], v[224:227], v[204:207], v[6:9]
	v_mfma_f32_16x16x32_bf16 v[2:5], v[232:235], v[204:207], v[2:5]
	s_barrier
	s_cbranch_scc0 .LBB0_357
	s_waitcnt lgkmcnt(0)
	v_lshl_add_u32 v146, s46, 8, v1
	v_lshl_or_b32 v148, s45, 8, v143
	v_ashrrev_i32_e32 v147, 31, v146
	v_readlane_b32 s48, v254, 40
	v_ashrrev_i32_e32 v149, 31, v148
	v_lshlrev_b64 v[150:151], 12, v[146:147]
	v_readlane_b32 s60, v254, 52
	v_readlane_b32 s61, v254, 53
	v_lshlrev_b64 v[148:149], 1, v[148:149]
	s_mov_b32 s19, 0x80000
	v_lshl_add_u64 v[150:151], s[60:61], 0, v[150:151]
	v_lshl_add_u64 v[150:151], v[150:151], 0, v[148:149]
	s_mov_b64 s[20:21], 0x80000
	v_cvt_pk_bf16_f32 v62, v62, v63
	v_cvt_pk_bf16_f32 v63, v64, v65
	v_cvt_pk_bf16_f32 v64, v58, v59
	v_add_co_u32_e32 v58, vcc, s19, v150
	v_cvt_pk_bf16_f32 v70, v70, v71
	v_cvt_pk_bf16_f32 v71, v72, v73
	v_cvt_pk_bf16_f32 v72, v66, v67
	v_lshl_add_u64 v[66:67], v[150:151], 0, s[20:21]
	v_addc_co_u32_e32 v59, vcc, 0, v151, vcc
	v_cvt_pk_bf16_f32 v46, v46, v47
	v_cvt_pk_bf16_f32 v47, v48, v49
	v_cvt_pk_bf16_f32 v48, v42, v43
	v_cvt_pk_bf16_f32 v49, v44, v45
	s_mov_b32 s19, 0x90000
	v_cvt_pk_bf16_f32 v110, v110, v111
	v_cvt_pk_bf16_f32 v111, v112, v113
	v_cvt_pk_bf16_f32 v112, v106, v107
	v_or_b32_e32 v106, 16, v146
	global_store_dwordx4 v[66:67], v[46:49], off offset:256
	s_mov_b64 s[20:21], 0x90000
	v_ashrrev_i32_e32 v107, 31, v106
	v_add_co_u32_e32 v48, vcc, s19, v150
	v_cvt_pk_bf16_f32 v94, v94, v95
	v_cvt_pk_bf16_f32 v95, v96, v97
	v_cvt_pk_bf16_f32 v96, v90, v91
	v_or_b32_e32 v90, 32, v146
	v_lshl_add_u64 v[46:47], v[150:151], 0, s[20:21]
	v_addc_co_u32_e32 v49, vcc, 0, v151, vcc
	v_cvt_pk_bf16_f32 v30, v30, v31
	v_cvt_pk_bf16_f32 v31, v32, v33
	v_cvt_pk_bf16_f32 v32, v26, v27
	v_cvt_pk_bf16_f32 v33, v28, v29
	s_mov_b32 s19, 0xa0000
	v_lshlrev_b64 v[106:107], 12, v[106:107]
	v_ashrrev_i32_e32 v91, 31, v90
	v_cvt_pk_bf16_f32 v78, v78, v79
	v_cvt_pk_bf16_f32 v79, v80, v81
	v_cvt_pk_bf16_f32 v80, v74, v75
	v_or_b32_e32 v74, 48, v146
	global_store_dwordx4 v[46:47], v[30:33], off offset:256
	s_mov_b64 s[20:21], 0xa0000
	v_cvt_pk_bf16_f32 v113, v108, v109
	v_add_co_u32_e32 v32, vcc, s19, v150
	v_lshl_add_u64 v[106:107], s[60:61], 0, v[106:107]
	v_lshlrev_b64 v[90:91], 12, v[90:91]
	v_ashrrev_i32_e32 v75, 31, v74
	v_lshl_add_u64 v[30:31], v[150:151], 0, s[20:21]
	v_addc_co_u32_e32 v33, vcc, 0, v151, vcc
	v_cvt_pk_bf16_f32 v14, v14, v15
	v_cvt_pk_bf16_f32 v15, v16, v17
	v_cvt_pk_bf16_f32 v16, v10, v11
	v_cvt_pk_bf16_f32 v17, v12, v13
	s_mov_b32 s19, 0xb0000
	global_store_dwordx4 v[150:151], v[110:113], off offset:256
	v_cvt_pk_bf16_f32 v97, v92, v93
	v_lshl_add_u64 v[90:91], s[60:61], 0, v[90:91]
	v_lshl_add_u64 v[110:111], v[106:107], 0, v[148:149]
	v_lshlrev_b64 v[74:75], 12, v[74:75]
	global_store_dwordx4 v[30:31], v[14:17], off offset:256
	global_store_dwordx4 v[110:111], v[94:97], off offset:256
	v_cvt_pk_bf16_f32 v81, v76, v77
	v_add_co_u32_e32 v16, vcc, s19, v150
	v_lshl_add_u64 v[94:95], v[90:91], 0, v[148:149]
	v_lshl_add_u64 v[74:75], s[60:61], 0, v[74:75]
	s_mov_b64 s[20:21], 0xb0000
	v_addc_co_u32_e32 v17, vcc, 0, v151, vcc
	v_cvt_pk_bf16_f32 v126, v126, v127
	v_cvt_pk_bf16_f32 v127, v128, v129
	v_cvt_pk_bf16_f32 v128, v122, v123
	v_cvt_pk_bf16_f32 v129, v124, v125
	v_cvt_pk_bf16_f32 v106, v118, v119
	v_cvt_pk_bf16_f32 v107, v120, v121
	v_cvt_pk_bf16_f32 v108, v114, v115
	v_cvt_pk_bf16_f32 v109, v116, v117
	v_cvt_pk_bf16_f32 v90, v102, v103
	v_cvt_pk_bf16_f32 v91, v104, v105
	v_cvt_pk_bf16_f32 v92, v98, v99
	v_cvt_pk_bf16_f32 v93, v100, v101
	global_store_dwordx4 v[94:95], v[78:81], off offset:256
	v_cvt_pk_bf16_f32 v76, v82, v83
	v_cvt_pk_bf16_f32 v77, v84, v85
	v_lshl_add_u64 v[78:79], v[74:75], 0, v[148:149]
	v_cvt_pk_bf16_f32 v74, v86, v87
	v_cvt_pk_bf16_f32 v75, v88, v89
	v_cvt_pk_bf16_f32 v73, v68, v69
	v_cvt_pk_bf16_f32 v65, v60, v61
	v_cvt_pk_bf16_f32 v42, v54, v55
	v_cvt_pk_bf16_f32 v43, v56, v57
	v_cvt_pk_bf16_f32 v44, v50, v51
	v_cvt_pk_bf16_f32 v45, v52, v53
	v_cvt_pk_bf16_f32 v26, v38, v39
	v_cvt_pk_bf16_f32 v27, v40, v41
	v_cvt_pk_bf16_f32 v28, v34, v35
	v_cvt_pk_bf16_f32 v29, v36, v37
	v_lshl_add_u64 v[14:15], v[150:151], 0, s[20:21]
	v_cvt_pk_bf16_f32 v10, v22, v23
	v_cvt_pk_bf16_f32 v11, v24, v25
	v_cvt_pk_bf16_f32 v12, v18, v19
	v_cvt_pk_bf16_f32 v13, v20, v21
	v_cvt_pk_bf16_f32 v6, v6, v7
	v_cvt_pk_bf16_f32 v7, v8, v9
	v_cvt_pk_bf16_f32 v8, v2, v3
	v_cvt_pk_bf16_f32 v9, v4, v5
	s_and_b64 vcc, exec, s[38:39]
	s_mov_b32 s45, s18
	s_mov_b32 s46, s30
	s_mov_b64 s[22:23], s[82:83]
	s_mov_b64 s[20:21], s[80:81]
	s_mov_b32 s64, 0x800000
	s_movk_i32 s65, 0x1fff
	v_readlane_b32 s49, v254, 41
	v_readlane_b32 s50, v254, 42
	v_readlane_b32 s51, v254, 43
	v_readlane_b32 s52, v254, 44
	v_readlane_b32 s53, v254, 45
	v_readlane_b32 s54, v254, 46
	v_readlane_b32 s55, v254, 47
	v_readlane_b32 s56, v254, 48
	v_readlane_b32 s57, v254, 49
	v_readlane_b32 s58, v254, 50
	v_readlane_b32 s59, v254, 51
	v_readlane_b32 s62, v254, 54
	v_readlane_b32 s63, v254, 55
	global_store_dwordx4 v[150:151], v[126:129], off
	global_store_dwordx4 v[110:111], v[106:109], off
	global_store_dwordx4 v[94:95], v[90:93], off
	global_store_dwordx4 v[78:79], v[74:77], off
	global_store_dwordx4 v[78:79], v[70:73], off offset:256
	global_store_dwordx4 v[58:59], v[62:65], off
	global_store_dwordx4 v[48:49], v[42:45], off
	global_store_dwordx4 v[32:33], v[26:29], off
	global_store_dwordx4 v[16:17], v[10:13], off
	global_store_dwordx4 v[14:15], v[6:9], off offset:256
	s_cbranch_vccz .LBB0_350
	s_waitcnt vmcnt(0)
	v_readlane_b32 s44, v255, 30
	s_mov_b32 s66, s90
	s_cmpk_gt_u32 s25, 0xff
	v_readlane_b32 s45, v255, 31
	v_readlane_b32 s42, v255, 32
	s_cbranch_scc1 .LBB0_361
	s_barrier

.LBB0_373:
	ds_read_b128 v[162:165], v144
	ds_read_b128 v[166:169], v144 offset:1024
	ds_read_b128 v[170:173], v144 offset:2048
	ds_read_b128 v[174:177], v144 offset:3072
	ds_read_b128 v[192:195], v144 offset:4096
	ds_read_b128 v[196:199], v144 offset:5120
	ds_read_b128 v[200:203], v144 offset:6144
	ds_read_b128 v[204:207], v144 offset:7168
	s_add_u32 s22, s20, 0xfffe0080
	s_addc_u32 s23, s21, -1
	s_add_i32 s52, 0, 0x10000
	s_cmp_eq_u32 s51, 4
	s_cselect_b32 s23, s31, s23
	s_cselect_b32 s22, s47, s22
	s_cselect_b32 s83, s19, s50
	s_cselect_b32 s82, s48, s49
	v_lshl_add_u64 v[178:179], s[20:21], 0, v[138:139]
	s_add_i32 m0, s27, 0xc000
	s_nop 0
	global_load_lds_dwordx4 v[178:179], off
	v_lshl_add_u64 v[178:179], s[20:21], 0, v[140:141]
	s_add_i32 m0, s27, 0xe000
	s_nop 0
	global_load_lds_dwordx4 v[178:179], off
	s_waitcnt lgkmcnt(8)
	s_barrier
	s_waitcnt lgkmcnt(0)
	v_mfma_f32_16x16x32_bf16 v[126:129], v[146:149], v[162:165], v[126:129]
	v_mfma_f32_16x16x32_bf16 v[122:125], v[154:157], v[162:165], v[122:125]
	v_mfma_f32_16x16x32_bf16 v[118:121], v[146:149], v[170:173], v[118:121]
	v_mfma_f32_16x16x32_bf16 v[114:117], v[154:157], v[170:173], v[114:117]
	v_mfma_f32_16x16x32_bf16 v[102:105], v[146:149], v[192:195], v[102:105]
	v_mfma_f32_16x16x32_bf16 v[98:101], v[154:157], v[192:195], v[98:101]
	v_mfma_f32_16x16x32_bf16 v[86:89], v[146:149], v[200:203], v[86:89]
	v_mfma_f32_16x16x32_bf16 v[82:85], v[154:157], v[200:203], v[82:85]
	v_mfma_f32_16x16x32_bf16 v[126:129], v[150:153], v[166:169], v[126:129]
	v_mfma_f32_16x16x32_bf16 v[122:125], v[158:161], v[166:169], v[122:125]
	v_mfma_f32_16x16x32_bf16 v[118:121], v[150:153], v[174:177], v[118:121]
	v_mfma_f32_16x16x32_bf16 v[114:117], v[158:161], v[174:177], v[114:117]
	v_mfma_f32_16x16x32_bf16 v[102:105], v[150:153], v[196:199], v[102:105]
	v_mfma_f32_16x16x32_bf16 v[98:101], v[158:161], v[196:199], v[98:101]
	v_mfma_f32_16x16x32_bf16 v[86:89], v[150:153], v[204:207], v[86:89]
	v_mfma_f32_16x16x32_bf16 v[82:85], v[158:161], v[204:207], v[82:85]
	s_barrier
	s_add_i32 s54, 0, 0x14000
	s_add_i32 s52, s52, s26
	v_add_u32_e32 v145, s54, v142
	v_lshl_add_u64 v[178:179], s[82:83], 0, v[134:135]
	s_mov_b32 m0, s52
	ds_read_b128 v[208:211], v145
	ds_read_b128 v[224:227], v145 offset:1024
	ds_read_b128 v[228:231], v145 offset:2048
	ds_read_b128 v[232:235], v145 offset:3072
	global_load_lds_dwordx4 v[178:179], off
	v_lshl_add_u64 v[212:213], s[82:83], 0, v[130:131]
	s_add_i32 m0, s52, 0x2000
	s_nop 0
	global_load_lds_dwordx4 v[212:213], off
	s_mov_b32 m0, s27
	v_lshl_add_u64 v[236:237], s[22:23], 0, v[136:137]
	s_barrier
	s_waitcnt lgkmcnt(0)
	v_mfma_f32_16x16x32_bf16 v[110:113], v[208:211], v[162:165], v[110:113]
	v_mfma_f32_16x16x32_bf16 v[106:109], v[228:231], v[162:165], v[106:109]
	v_mfma_f32_16x16x32_bf16 v[94:97], v[208:211], v[170:173], v[94:97]
	v_mfma_f32_16x16x32_bf16 v[90:93], v[228:231], v[170:173], v[90:93]
	v_mfma_f32_16x16x32_bf16 v[78:81], v[208:211], v[192:195], v[78:81]
	v_mfma_f32_16x16x32_bf16 v[74:77], v[228:231], v[192:195], v[74:77]
	v_mfma_f32_16x16x32_bf16 v[70:73], v[208:211], v[200:203], v[70:73]
	v_mfma_f32_16x16x32_bf16 v[66:69], v[228:231], v[200:203], v[66:69]
	v_mfma_f32_16x16x32_bf16 v[110:113], v[224:227], v[166:169], v[110:113]
	v_mfma_f32_16x16x32_bf16 v[106:109], v[232:235], v[166:169], v[106:109]
	v_mfma_f32_16x16x32_bf16 v[94:97], v[224:227], v[174:177], v[94:97]
	v_mfma_f32_16x16x32_bf16 v[90:93], v[232:235], v[174:177], v[90:93]
	v_mfma_f32_16x16x32_bf16 v[78:81], v[224:227], v[196:199], v[78:81]
	v_mfma_f32_16x16x32_bf16 v[74:77], v[232:235], v[196:199], v[74:77]
	v_mfma_f32_16x16x32_bf16 v[70:73], v[224:227], v[204:207], v[70:73]
	v_mfma_f32_16x16x32_bf16 v[66:69], v[232:235], v[204:207], v[66:69]
	s_barrier
	ds_read_b128 v[162:165], v144 offset:16384
	ds_read_b128 v[166:169], v144 offset:17408
	ds_read_b128 v[170:173], v144 offset:18432
	ds_read_b128 v[174:177], v144 offset:19456
	ds_read_b128 v[192:195], v144 offset:20480
	ds_read_b128 v[196:199], v144 offset:21504
	ds_read_b128 v[200:203], v144 offset:22528
	ds_read_b128 v[204:207], v144 offset:23552
	global_load_lds_dwordx4 v[236:237], off
	v_lshl_add_u64 v[238:239], s[22:23], 0, v[132:133]
	s_mov_b32 m0, s28
	s_nop 0
	global_load_lds_dwordx4 v[238:239], off
	s_waitcnt vmcnt(10)
	s_barrier
	s_waitcnt lgkmcnt(0)
	v_mfma_f32_16x16x32_bf16 v[62:65], v[146:149], v[162:165], v[62:65]
	v_mfma_f32_16x16x32_bf16 v[58:61], v[154:157], v[162:165], v[58:61]
	v_mfma_f32_16x16x32_bf16 v[54:57], v[146:149], v[170:173], v[54:57]
	v_mfma_f32_16x16x32_bf16 v[50:53], v[154:157], v[170:173], v[50:53]
	v_mfma_f32_16x16x32_bf16 v[38:41], v[146:149], v[192:195], v[38:41]
	v_mfma_f32_16x16x32_bf16 v[34:37], v[154:157], v[192:195], v[34:37]
	v_mfma_f32_16x16x32_bf16 v[22:25], v[146:149], v[200:203], v[22:25]
	v_mfma_f32_16x16x32_bf16 v[18:21], v[154:157], v[200:203], v[18:21]
	v_mfma_f32_16x16x32_bf16 v[62:65], v[150:153], v[166:169], v[62:65]
	v_mfma_f32_16x16x32_bf16 v[58:61], v[158:161], v[166:169], v[58:61]
	v_mfma_f32_16x16x32_bf16 v[54:57], v[150:153], v[174:177], v[54:57]
	v_mfma_f32_16x16x32_bf16 v[50:53], v[158:161], v[174:177], v[50:53]
	v_mfma_f32_16x16x32_bf16 v[38:41], v[150:153], v[196:199], v[38:41]
	v_mfma_f32_16x16x32_bf16 v[34:37], v[158:161], v[196:199], v[34:37]
	v_mfma_f32_16x16x32_bf16 v[22:25], v[150:153], v[204:207], v[22:25]
	v_mfma_f32_16x16x32_bf16 v[18:21], v[158:161], v[204:207], v[18:21]
	s_barrier
	s_add_u32 s52, s82, 0x20000
	s_addc_u32 s53, s83, 0
	s_add_i32 s54, s54, s26
	v_lshl_add_u64 v[146:147], s[52:53], 0, v[134:135]
	s_mov_b32 m0, s54
	s_nop 0
	global_load_lds_dwordx4 v[146:147], off
	v_lshl_add_u64 v[146:147], s[52:53], 0, v[130:131]
	s_add_i32 m0, s54, 0x2000
	s_nop 0
	global_load_lds_dwordx4 v[146:147], off
	v_add_u32_e32 v145, 0x18000, v142
	ds_read_b128 v[146:149], v145
	ds_read_b128 v[150:153], v145 offset:1024
	ds_read_b128 v[154:157], v145 offset:2048
	ds_read_b128 v[158:161], v145 offset:3072
	s_add_i32 s52, 0, 0x18000
	s_waitcnt vmcnt(6)
	s_barrier
	v_mfma_f32_16x16x32_bf16 v[46:49], v[208:211], v[162:165], v[46:49]
	v_mfma_f32_16x16x32_bf16 v[42:45], v[228:231], v[162:165], v[42:45]
	v_mfma_f32_16x16x32_bf16 v[30:33], v[208:211], v[170:173], v[30:33]
	v_mfma_f32_16x16x32_bf16 v[26:29], v[228:231], v[170:173], v[26:29]
	v_mfma_f32_16x16x32_bf16 v[14:17], v[208:211], v[192:195], v[14:17]
	v_mfma_f32_16x16x32_bf16 v[10:13], v[228:231], v[192:195], v[10:13]
	v_mfma_f32_16x16x32_bf16 v[6:9], v[208:211], v[200:203], v[6:9]
	v_mfma_f32_16x16x32_bf16 v[2:5], v[228:231], v[200:203], v[2:5]
	v_mfma_f32_16x16x32_bf16 v[46:49], v[224:227], v[166:169], v[46:49]
	v_mfma_f32_16x16x32_bf16 v[42:45], v[232:235], v[166:169], v[42:45]
	v_mfma_f32_16x16x32_bf16 v[30:33], v[224:227], v[174:177], v[30:33]
	v_mfma_f32_16x16x32_bf16 v[26:29], v[232:235], v[174:177], v[26:29]
	v_mfma_f32_16x16x32_bf16 v[14:17], v[224:227], v[196:199], v[14:17]
	v_mfma_f32_16x16x32_bf16 v[10:13], v[232:235], v[196:199], v[10:13]
	v_mfma_f32_16x16x32_bf16 v[6:9], v[224:227], v[204:207], v[6:9]
	v_mfma_f32_16x16x32_bf16 v[2:5], v[232:235], v[204:207], v[2:5]
	s_barrier
	ds_read_b128 v[162:165], v144 offset:32768
	ds_read_b128 v[166:169], v144 offset:33792
	ds_read_b128 v[170:173], v144 offset:34816
	ds_read_b128 v[174:177], v144 offset:35840
	ds_read_b128 v[192:195], v144 offset:36864
	ds_read_b128 v[196:199], v144 offset:37888
	ds_read_b128 v[200:203], v144 offset:38912
	ds_read_b128 v[204:207], v144 offset:39936
	s_add_u32 s22, s22, 0x20000
	s_addc_u32 s23, s23, 0
	s_mov_b32 m0, s29
	v_lshl_add_u64 v[208:209], s[22:23], 0, v[136:137]
	global_load_lds_dwordx4 v[208:209], off
	v_lshl_add_u64 v[208:209], s[22:23], 0, v[132:133]
	s_mov_b32 m0, s36
	s_nop 0
	global_load_lds_dwordx4 v[208:209], off
	s_waitcnt lgkmcnt(8)
	s_barrier
	s_waitcnt lgkmcnt(0)
	v_mfma_f32_16x16x32_bf16 v[126:129], v[146:149], v[162:165], v[126:129]
	v_mfma_f32_16x16x32_bf16 v[122:125], v[154:157], v[162:165], v[122:125]
	v_mfma_f32_16x16x32_bf16 v[118:121], v[146:149], v[170:173], v[118:121]
	v_mfma_f32_16x16x32_bf16 v[114:117], v[154:157], v[170:173], v[114:117]
	v_mfma_f32_16x16x32_bf16 v[102:105], v[146:149], v[192:195], v[102:105]
	v_mfma_f32_16x16x32_bf16 v[98:101], v[154:157], v[192:195], v[98:101]
	v_mfma_f32_16x16x32_bf16 v[86:89], v[146:149], v[200:203], v[86:89]
	v_mfma_f32_16x16x32_bf16 v[82:85], v[154:157], v[200:203], v[82:85]
	v_mfma_f32_16x16x32_bf16 v[126:129], v[150:153], v[166:169], v[126:129]
	v_mfma_f32_16x16x32_bf16 v[122:125], v[158:161], v[166:169], v[122:125]
	v_mfma_f32_16x16x32_bf16 v[118:121], v[150:153], v[174:177], v[118:121]
	v_mfma_f32_16x16x32_bf16 v[114:117], v[158:161], v[174:177], v[114:117]
	v_mfma_f32_16x16x32_bf16 v[102:105], v[150:153], v[196:199], v[102:105]
	v_mfma_f32_16x16x32_bf16 v[98:101], v[158:161], v[196:199], v[98:101]
	v_mfma_f32_16x16x32_bf16 v[86:89], v[150:153], v[204:207], v[86:89]
	v_mfma_f32_16x16x32_bf16 v[82:85], v[158:161], v[204:207], v[82:85]
	s_barrier
	s_add_i32 s53, 0, 0x1c000
	s_add_i32 s22, s52, s26
	v_add_u32_e32 v145, s53, v142
	v_lshl_add_u64 v[178:179], v[178:179], 0, s[78:79]
	s_mov_b32 m0, s22
	ds_read_b128 v[208:211], v145
	ds_read_b128 v[224:227], v145 offset:1024
	ds_read_b128 v[228:231], v145 offset:2048
	ds_read_b128 v[232:235], v145 offset:3072
	global_load_lds_dwordx4 v[178:179], off
	v_lshl_add_u64 v[178:179], v[212:213], 0, s[78:79]
	s_add_i32 m0, s22, 0x2000
	s_nop 0
	global_load_lds_dwordx4 v[178:179], off
	s_mov_b32 m0, s42
	v_lshl_add_u64 v[178:179], v[236:237], 0, s[78:79]
	s_barrier
	s_waitcnt lgkmcnt(0)
	v_mfma_f32_16x16x32_bf16 v[110:113], v[208:211], v[162:165], v[110:113]
	v_mfma_f32_16x16x32_bf16 v[106:109], v[228:231], v[162:165], v[106:109]
	v_mfma_f32_16x16x32_bf16 v[94:97], v[208:211], v[170:173], v[94:97]
	v_mfma_f32_16x16x32_bf16 v[90:93], v[228:231], v[170:173], v[90:93]
	v_mfma_f32_16x16x32_bf16 v[78:81], v[208:211], v[192:195], v[78:81]
	v_mfma_f32_16x16x32_bf16 v[74:77], v[228:231], v[192:195], v[74:77]
	v_mfma_f32_16x16x32_bf16 v[70:73], v[208:211], v[200:203], v[70:73]
	v_mfma_f32_16x16x32_bf16 v[66:69], v[228:231], v[200:203], v[66:69]
	v_mfma_f32_16x16x32_bf16 v[110:113], v[224:227], v[166:169], v[110:113]
	v_mfma_f32_16x16x32_bf16 v[106:109], v[232:235], v[166:169], v[106:109]
	v_mfma_f32_16x16x32_bf16 v[94:97], v[224:227], v[174:177], v[94:97]
	v_mfma_f32_16x16x32_bf16 v[90:93], v[232:235], v[174:177], v[90:93]
	v_mfma_f32_16x16x32_bf16 v[78:81], v[224:227], v[196:199], v[78:81]
	v_mfma_f32_16x16x32_bf16 v[74:77], v[232:235], v[196:199], v[74:77]
	v_mfma_f32_16x16x32_bf16 v[70:73], v[224:227], v[204:207], v[70:73]
	v_mfma_f32_16x16x32_bf16 v[66:69], v[232:235], v[204:207], v[66:69]
	s_barrier
	ds_read_b128 v[162:165], v144 offset:49152
	ds_read_b128 v[166:169], v144 offset:50176
	ds_read_b128 v[170:173], v144 offset:51200
	ds_read_b128 v[174:177], v144 offset:52224
	ds_read_b128 v[192:195], v144 offset:53248
	ds_read_b128 v[196:199], v144 offset:54272
	ds_read_b128 v[200:203], v144 offset:55296
	ds_read_b128 v[204:207], v144 offset:56320
	global_load_lds_dwordx4 v[178:179], off
	v_lshl_add_u64 v[178:179], v[238:239], 0, s[78:79]
	s_mov_b32 m0, s43
	s_nop 0
	global_load_lds_dwordx4 v[178:179], off
	s_waitcnt vmcnt(10)
	s_barrier
	s_waitcnt lgkmcnt(0)
	v_mfma_f32_16x16x32_bf16 v[62:65], v[146:149], v[162:165], v[62:65]
	v_mfma_f32_16x16x32_bf16 v[58:61], v[154:157], v[162:165], v[58:61]
	v_mfma_f32_16x16x32_bf16 v[54:57], v[146:149], v[170:173], v[54:57]
	v_mfma_f32_16x16x32_bf16 v[50:53], v[154:157], v[170:173], v[50:53]
	v_mfma_f32_16x16x32_bf16 v[38:41], v[146:149], v[192:195], v[38:41]
	v_mfma_f32_16x16x32_bf16 v[34:37], v[154:157], v[192:195], v[34:37]
	v_mfma_f32_16x16x32_bf16 v[22:25], v[146:149], v[200:203], v[22:25]
	v_mfma_f32_16x16x32_bf16 v[18:21], v[154:157], v[200:203], v[18:21]
	v_mfma_f32_16x16x32_bf16 v[62:65], v[150:153], v[166:169], v[62:65]
	v_mfma_f32_16x16x32_bf16 v[58:61], v[158:161], v[166:169], v[58:61]
	v_mfma_f32_16x16x32_bf16 v[54:57], v[150:153], v[174:177], v[54:57]
	v_mfma_f32_16x16x32_bf16 v[50:53], v[158:161], v[174:177], v[50:53]
	v_mfma_f32_16x16x32_bf16 v[38:41], v[150:153], v[196:199], v[38:41]
	v_mfma_f32_16x16x32_bf16 v[34:37], v[158:161], v[196:199], v[34:37]
	v_mfma_f32_16x16x32_bf16 v[22:25], v[150:153], v[204:207], v[22:25]
	v_mfma_f32_16x16x32_bf16 v[18:21], v[158:161], v[204:207], v[18:21]
	s_barrier
	s_add_u32 s22, s82, 0x20080
	s_addc_u32 s23, s83, 0
	s_add_i32 s52, s53, s26
	v_lshl_add_u64 v[146:147], s[22:23], 0, v[134:135]
	s_mov_b32 m0, s52
	s_nop 0
	global_load_lds_dwordx4 v[146:147], off
	v_lshl_add_u64 v[146:147], s[22:23], 0, v[130:131]
	s_add_i32 m0, s52, 0x2000
	s_nop 0
	global_load_lds_dwordx4 v[146:147], off
	v_add_u32_e32 v145, 0x10000, v142
	ds_read_b128 v[146:149], v145
	ds_read_b128 v[150:153], v145 offset:1024
	ds_read_b128 v[154:157], v145 offset:2048
	ds_read_b128 v[158:161], v145 offset:3072
	s_add_i32 s51, s51, 2
	s_add_u32 s20, s20, 0x100
	s_addc_u32 s21, s21, 0
	s_add_u32 s49, s49, 0x100
	s_addc_u32 s50, s50, 0
	s_cmp_gt_u32 s51, 5
	s_waitcnt vmcnt(6)
	s_barrier
	v_mfma_f32_16x16x32_bf16 v[46:49], v[208:211], v[162:165], v[46:49]
	v_mfma_f32_16x16x32_bf16 v[42:45], v[228:231], v[162:165], v[42:45]
	v_mfma_f32_16x16x32_bf16 v[30:33], v[208:211], v[170:173], v[30:33]
	v_mfma_f32_16x16x32_bf16 v[26:29], v[228:231], v[170:173], v[26:29]
	v_mfma_f32_16x16x32_bf16 v[14:17], v[208:211], v[192:195], v[14:17]
	v_mfma_f32_16x16x32_bf16 v[10:13], v[228:231], v[192:195], v[10:13]
	v_mfma_f32_16x16x32_bf16 v[6:9], v[208:211], v[200:203], v[6:9]
	v_mfma_f32_16x16x32_bf16 v[2:5], v[228:231], v[200:203], v[2:5]
	v_mfma_f32_16x16x32_bf16 v[46:49], v[224:227], v[166:169], v[46:49]
	v_mfma_f32_16x16x32_bf16 v[42:45], v[232:235], v[166:169], v[42:45]
	v_mfma_f32_16x16x32_bf16 v[30:33], v[224:227], v[174:177], v[30:33]
	v_mfma_f32_16x16x32_bf16 v[26:29], v[232:235], v[174:177], v[26:29]
	v_mfma_f32_16x16x32_bf16 v[14:17], v[224:227], v[196:199], v[14:17]
	v_mfma_f32_16x16x32_bf16 v[10:13], v[232:235], v[196:199], v[10:13]
	v_mfma_f32_16x16x32_bf16 v[6:9], v[224:227], v[204:207], v[6:9]
	v_mfma_f32_16x16x32_bf16 v[2:5], v[232:235], v[204:207], v[2:5]
	s_barrier
	s_cbranch_scc0 .LBB0_373
	s_waitcnt lgkmcnt(0)
	v_lshl_add_u32 v146, s46, 8, v1
	v_lshl_or_b32 v148, s45, 8, v143
	v_ashrrev_i32_e32 v147, 31, v146
	v_readlane_b32 s48, v254, 40
	v_ashrrev_i32_e32 v149, 31, v148
	v_lshlrev_b64 v[150:151], 14, v[146:147]
	v_readlane_b32 s62, v254, 54
	v_readlane_b32 s63, v254, 55
	v_lshlrev_b64 v[148:149], 1, v[148:149]
	s_mov_b32 s19, 0x200000
	v_lshl_add_u64 v[150:151], s[62:63], 0, v[150:151]
	v_lshl_add_u64 v[150:151], v[150:151], 0, v[148:149]
	s_mov_b64 s[20:21], 0x200000
	v_cvt_pk_bf16_f32 v62, v62, v63
	v_cvt_pk_bf16_f32 v63, v64, v65
	v_cvt_pk_bf16_f32 v64, v58, v59
	v_add_co_u32_e32 v58, vcc, s19, v150
	v_cvt_pk_bf16_f32 v70, v70, v71
	v_cvt_pk_bf16_f32 v71, v72, v73
	v_cvt_pk_bf16_f32 v72, v66, v67
	v_lshl_add_u64 v[66:67], v[150:151], 0, s[20:21]
	v_addc_co_u32_e32 v59, vcc, 0, v151, vcc
	v_cvt_pk_bf16_f32 v46, v46, v47
	v_cvt_pk_bf16_f32 v47, v48, v49
	v_cvt_pk_bf16_f32 v48, v42, v43
	v_cvt_pk_bf16_f32 v49, v44, v45
	s_mov_b32 s19, 0x240000
	v_cvt_pk_bf16_f32 v110, v110, v111
	v_cvt_pk_bf16_f32 v111, v112, v113
	v_cvt_pk_bf16_f32 v112, v106, v107
	v_or_b32_e32 v106, 16, v146
	global_store_dwordx4 v[66:67], v[46:49], off offset:256
	s_mov_b64 s[20:21], 0x240000
	v_ashrrev_i32_e32 v107, 31, v106
	v_add_co_u32_e32 v48, vcc, s19, v150
	v_cvt_pk_bf16_f32 v94, v94, v95
	v_cvt_pk_bf16_f32 v95, v96, v97
	v_cvt_pk_bf16_f32 v96, v90, v91
	v_or_b32_e32 v90, 32, v146
	v_lshl_add_u64 v[46:47], v[150:151], 0, s[20:21]
	v_addc_co_u32_e32 v49, vcc, 0, v151, vcc
	v_cvt_pk_bf16_f32 v30, v30, v31
	v_cvt_pk_bf16_f32 v31, v32, v33
	v_cvt_pk_bf16_f32 v32, v26, v27
	v_cvt_pk_bf16_f32 v33, v28, v29
	s_mov_b32 s19, 0x280000
	v_lshlrev_b64 v[106:107], 14, v[106:107]
	v_ashrrev_i32_e32 v91, 31, v90
	v_cvt_pk_bf16_f32 v78, v78, v79
	v_cvt_pk_bf16_f32 v79, v80, v81
	v_cvt_pk_bf16_f32 v80, v74, v75
	v_or_b32_e32 v74, 48, v146
	global_store_dwordx4 v[46:47], v[30:33], off offset:256
	s_mov_b64 s[20:21], 0x280000
	v_cvt_pk_bf16_f32 v113, v108, v109
	v_add_co_u32_e32 v32, vcc, s19, v150
	v_lshl_add_u64 v[106:107], s[62:63], 0, v[106:107]
	v_lshlrev_b64 v[90:91], 14, v[90:91]
	v_ashrrev_i32_e32 v75, 31, v74
	v_lshl_add_u64 v[30:31], v[150:151], 0, s[20:21]
	v_addc_co_u32_e32 v33, vcc, 0, v151, vcc
	v_cvt_pk_bf16_f32 v14, v14, v15
	v_cvt_pk_bf16_f32 v15, v16, v17
	v_cvt_pk_bf16_f32 v16, v10, v11
	v_cvt_pk_bf16_f32 v17, v12, v13
	s_mov_b32 s19, 0x2c0000
	global_store_dwordx4 v[150:151], v[110:113], off offset:256
	v_cvt_pk_bf16_f32 v97, v92, v93
	v_lshl_add_u64 v[90:91], s[62:63], 0, v[90:91]
	v_lshl_add_u64 v[110:111], v[106:107], 0, v[148:149]
	v_lshlrev_b64 v[74:75], 14, v[74:75]
	global_store_dwordx4 v[30:31], v[14:17], off offset:256
	global_store_dwordx4 v[110:111], v[94:97], off offset:256
	v_cvt_pk_bf16_f32 v81, v76, v77
	v_add_co_u32_e32 v16, vcc, s19, v150
	v_lshl_add_u64 v[94:95], v[90:91], 0, v[148:149]
	v_lshl_add_u64 v[74:75], s[62:63], 0, v[74:75]
	s_mov_b64 s[20:21], 0x2c0000
	v_addc_co_u32_e32 v17, vcc, 0, v151, vcc
	v_cvt_pk_bf16_f32 v126, v126, v127
	v_cvt_pk_bf16_f32 v127, v128, v129
	v_cvt_pk_bf16_f32 v128, v122, v123
	v_cvt_pk_bf16_f32 v129, v124, v125
	v_cvt_pk_bf16_f32 v106, v118, v119
	v_cvt_pk_bf16_f32 v107, v120, v121
	v_cvt_pk_bf16_f32 v108, v114, v115
	v_cvt_pk_bf16_f32 v109, v116, v117
	v_cvt_pk_bf16_f32 v90, v102, v103
	v_cvt_pk_bf16_f32 v91, v104, v105
	v_cvt_pk_bf16_f32 v92, v98, v99
	v_cvt_pk_bf16_f32 v93, v100, v101
	global_store_dwordx4 v[94:95], v[78:81], off offset:256
	v_cvt_pk_bf16_f32 v76, v82, v83
	v_cvt_pk_bf16_f32 v77, v84, v85
	v_lshl_add_u64 v[78:79], v[74:75], 0, v[148:149]
	v_cvt_pk_bf16_f32 v74, v86, v87
	v_cvt_pk_bf16_f32 v75, v88, v89
	v_cvt_pk_bf16_f32 v73, v68, v69
	v_cvt_pk_bf16_f32 v65, v60, v61
	v_cvt_pk_bf16_f32 v42, v54, v55
	v_cvt_pk_bf16_f32 v43, v56, v57
	v_cvt_pk_bf16_f32 v44, v50, v51
	v_cvt_pk_bf16_f32 v45, v52, v53
	v_cvt_pk_bf16_f32 v26, v38, v39
	v_cvt_pk_bf16_f32 v27, v40, v41
	v_cvt_pk_bf16_f32 v28, v34, v35
	v_cvt_pk_bf16_f32 v29, v36, v37
	v_lshl_add_u64 v[14:15], v[150:151], 0, s[20:21]
	v_cvt_pk_bf16_f32 v10, v22, v23
	v_cvt_pk_bf16_f32 v11, v24, v25
	v_cvt_pk_bf16_f32 v12, v18, v19
	v_cvt_pk_bf16_f32 v13, v20, v21
	v_cvt_pk_bf16_f32 v6, v6, v7
	v_cvt_pk_bf16_f32 v7, v8, v9
	v_cvt_pk_bf16_f32 v8, v2, v3
	v_cvt_pk_bf16_f32 v9, v4, v5
	s_and_b64 vcc, exec, s[0:1]
	s_mov_b32 s45, s18
	s_mov_b32 s46, s30
	s_mov_b64 s[22:23], s[80:81]
	s_mov_b64 s[20:21], s[38:39]
	s_mov_b32 s64, 0x800000
	s_movk_i32 s65, 0x1fff
	v_readlane_b32 s49, v254, 41
	v_readlane_b32 s50, v254, 42
	v_readlane_b32 s51, v254, 43
	v_readlane_b32 s52, v254, 44
	v_readlane_b32 s53, v254, 45
	v_readlane_b32 s54, v254, 46
	v_readlane_b32 s55, v254, 47
	v_readlane_b32 s56, v254, 48
	v_readlane_b32 s57, v254, 49
	v_readlane_b32 s58, v254, 50
	v_readlane_b32 s59, v254, 51
	v_readlane_b32 s60, v254, 52
	v_readlane_b32 s61, v254, 53
	global_store_dwordx4 v[150:151], v[126:129], off
	global_store_dwordx4 v[110:111], v[106:109], off
	global_store_dwordx4 v[94:95], v[90:93], off
	global_store_dwordx4 v[78:79], v[74:77], off
	global_store_dwordx4 v[78:79], v[70:73], off offset:256
	global_store_dwordx4 v[58:59], v[62:65], off
	global_store_dwordx4 v[48:49], v[42:45], off
	global_store_dwordx4 v[32:33], v[26:29], off
	global_store_dwordx4 v[16:17], v[10:13], off
	global_store_dwordx4 v[14:15], v[6:9], off offset:256
	s_cbranch_vccz .LBB0_366
	s_waitcnt vmcnt(0)
	v_readlane_b32 s44, v255, 30
	s_mov_b32 s66, s90
	s_cmpk_gt_u32 s25, 0xff
	v_readlane_b32 s45, v255, 31
	v_readlane_b32 s42, v255, 32
	s_cbranch_scc1 .LBB0_377
	s_barrier

.LBB0_386:
	ds_read_b128 v[162:165], v156
	ds_read_b128 v[166:169], v156 offset:1024
	ds_read_b128 v[170:173], v156 offset:2048
	ds_read_b128 v[174:177], v156 offset:3072
	ds_read_b128 v[192:195], v156 offset:4096
	ds_read_b128 v[196:199], v156 offset:5120
	ds_read_b128 v[200:203], v156 offset:6144
	ds_read_b128 v[204:207], v156 offset:7168
	s_add_u32 s20, s18, 0xfffe0080
	s_addc_u32 s21, s19, -1
	s_add_i32 s50, 0, 0x10000
	s_cmp_eq_u32 s49, 4
	s_cselect_b32 s23, s44, s21
	s_cselect_b32 s22, s45, s20
	s_cselect_b32 s21, s39, s48
	s_cselect_b32 s20, s46, s47
	v_lshl_add_u64 v[178:179], s[18:19], 0, v[146:147]
	s_add_i32 m0, s90, 0xc000
	s_nop 0
	global_load_lds_dwordx4 v[178:179], off
	v_lshl_add_u64 v[178:179], s[18:19], 0, v[148:149]
	s_add_i32 m0, s90, 0xe000
	s_nop 0
	global_load_lds_dwordx4 v[178:179], off
	s_waitcnt lgkmcnt(8)
	s_barrier
	s_waitcnt lgkmcnt(0)
	v_mfma_f32_16x16x32_bf16 v[126:129], v[130:133], v[162:165], v[126:129]
	v_mfma_f32_16x16x32_bf16 v[122:125], v[150:153], v[162:165], v[122:125]
	v_mfma_f32_16x16x32_bf16 v[118:121], v[130:133], v[170:173], v[118:121]
	v_mfma_f32_16x16x32_bf16 v[110:113], v[150:153], v[170:173], v[110:113]
	v_mfma_f32_16x16x32_bf16 v[102:105], v[130:133], v[192:195], v[102:105]
	v_mfma_f32_16x16x32_bf16 v[94:97], v[150:153], v[192:195], v[94:97]
	v_mfma_f32_16x16x32_bf16 v[86:89], v[130:133], v[200:203], v[86:89]
	v_mfma_f32_16x16x32_bf16 v[78:81], v[150:153], v[200:203], v[78:81]
	v_mfma_f32_16x16x32_bf16 v[126:129], v[134:137], v[166:169], v[126:129]
	v_mfma_f32_16x16x32_bf16 v[122:125], v[158:161], v[166:169], v[122:125]
	v_mfma_f32_16x16x32_bf16 v[118:121], v[134:137], v[174:177], v[118:121]
	v_mfma_f32_16x16x32_bf16 v[110:113], v[158:161], v[174:177], v[110:113]
	v_mfma_f32_16x16x32_bf16 v[102:105], v[134:137], v[196:199], v[102:105]
	v_mfma_f32_16x16x32_bf16 v[94:97], v[158:161], v[196:199], v[94:97]
	v_mfma_f32_16x16x32_bf16 v[86:89], v[134:137], v[204:207], v[86:89]
	v_mfma_f32_16x16x32_bf16 v[78:81], v[158:161], v[204:207], v[78:81]
	s_barrier
	s_add_i32 s52, 0, 0x14000
	s_add_i32 s50, s50, s36
	v_add_u32_e32 v157, s52, v154
	v_lshl_add_u64 v[178:179], s[20:21], 0, v[142:143]
	s_mov_b32 m0, s50
	ds_read_b128 v[208:211], v157
	ds_read_b128 v[224:227], v157 offset:1024
	ds_read_b128 v[228:231], v157 offset:2048
	ds_read_b128 v[232:235], v157 offset:3072
	global_load_lds_dwordx4 v[178:179], off
	v_lshl_add_u64 v[212:213], s[20:21], 0, v[138:139]
	s_add_i32 m0, s50, 0x2000
	s_nop 0
	global_load_lds_dwordx4 v[212:213], off
	s_mov_b32 m0, s90
	v_lshl_add_u64 v[236:237], s[22:23], 0, v[144:145]
	s_barrier
	s_waitcnt lgkmcnt(0)
	v_mfma_f32_16x16x32_bf16 v[114:117], v[208:211], v[162:165], v[114:117]
	v_mfma_f32_16x16x32_bf16 v[106:109], v[228:231], v[162:165], v[106:109]
	v_mfma_f32_16x16x32_bf16 v[98:101], v[208:211], v[170:173], v[98:101]
	v_mfma_f32_16x16x32_bf16 v[90:93], v[228:231], v[170:173], v[90:93]
	v_mfma_f32_16x16x32_bf16 v[82:85], v[208:211], v[192:195], v[82:85]
	v_mfma_f32_16x16x32_bf16 v[74:77], v[228:231], v[192:195], v[74:77]
	v_mfma_f32_16x16x32_bf16 v[70:73], v[208:211], v[200:203], v[70:73]
	v_mfma_f32_16x16x32_bf16 v[66:69], v[228:231], v[200:203], v[66:69]
	v_mfma_f32_16x16x32_bf16 v[114:117], v[224:227], v[166:169], v[114:117]
	v_mfma_f32_16x16x32_bf16 v[106:109], v[232:235], v[166:169], v[106:109]
	v_mfma_f32_16x16x32_bf16 v[98:101], v[224:227], v[174:177], v[98:101]
	v_mfma_f32_16x16x32_bf16 v[90:93], v[232:235], v[174:177], v[90:93]
	v_mfma_f32_16x16x32_bf16 v[82:85], v[224:227], v[196:199], v[82:85]
	v_mfma_f32_16x16x32_bf16 v[74:77], v[232:235], v[196:199], v[74:77]
	v_mfma_f32_16x16x32_bf16 v[70:73], v[224:227], v[204:207], v[70:73]
	v_mfma_f32_16x16x32_bf16 v[66:69], v[232:235], v[204:207], v[66:69]
	s_barrier
	ds_read_b128 v[162:165], v156 offset:16384
	ds_read_b128 v[166:169], v156 offset:17408
	ds_read_b128 v[170:173], v156 offset:18432
	ds_read_b128 v[174:177], v156 offset:19456
	ds_read_b128 v[192:195], v156 offset:20480
	ds_read_b128 v[196:199], v156 offset:21504
	ds_read_b128 v[200:203], v156 offset:22528
	ds_read_b128 v[204:207], v156 offset:23552
	global_load_lds_dwordx4 v[236:237], off
	v_lshl_add_u64 v[238:239], s[22:23], 0, v[140:141]
	s_mov_b32 m0, s91
	s_nop 0
	global_load_lds_dwordx4 v[238:239], off
	s_waitcnt vmcnt(10)
	s_barrier
	s_waitcnt lgkmcnt(0)
	v_mfma_f32_16x16x32_bf16 v[62:65], v[130:133], v[162:165], v[62:65]
	v_mfma_f32_16x16x32_bf16 v[58:61], v[150:153], v[162:165], v[58:61]
	v_mfma_f32_16x16x32_bf16 v[54:57], v[130:133], v[170:173], v[54:57]
	v_mfma_f32_16x16x32_bf16 v[46:49], v[150:153], v[170:173], v[46:49]
	v_mfma_f32_16x16x32_bf16 v[38:41], v[130:133], v[192:195], v[38:41]
	v_mfma_f32_16x16x32_bf16 v[30:33], v[150:153], v[192:195], v[30:33]
	v_mfma_f32_16x16x32_bf16 v[22:25], v[130:133], v[200:203], v[22:25]
	v_mfma_f32_16x16x32_bf16 v[14:17], v[150:153], v[200:203], v[14:17]
	v_mfma_f32_16x16x32_bf16 v[62:65], v[134:137], v[166:169], v[62:65]
	v_mfma_f32_16x16x32_bf16 v[58:61], v[158:161], v[166:169], v[58:61]
	v_mfma_f32_16x16x32_bf16 v[54:57], v[134:137], v[174:177], v[54:57]
	v_mfma_f32_16x16x32_bf16 v[46:49], v[158:161], v[174:177], v[46:49]
	v_mfma_f32_16x16x32_bf16 v[38:41], v[134:137], v[196:199], v[38:41]
	v_mfma_f32_16x16x32_bf16 v[30:33], v[158:161], v[196:199], v[30:33]
	v_mfma_f32_16x16x32_bf16 v[22:25], v[134:137], v[204:207], v[22:25]
	v_mfma_f32_16x16x32_bf16 v[14:17], v[158:161], v[204:207], v[14:17]
	s_barrier
	s_add_u32 s50, s20, 0x20000
	s_addc_u32 s51, s21, 0
	s_add_i32 s52, s52, s36
	v_lshl_add_u64 v[130:131], s[50:51], 0, v[142:143]
	s_mov_b32 m0, s52
	s_nop 0
	global_load_lds_dwordx4 v[130:131], off
	v_lshl_add_u64 v[130:131], s[50:51], 0, v[138:139]
	s_add_i32 m0, s52, 0x2000
	s_nop 0
	global_load_lds_dwordx4 v[130:131], off
	v_add_u32_e32 v157, 0x18000, v154
	ds_read_b128 v[130:133], v157
	ds_read_b128 v[134:137], v157 offset:1024
	ds_read_b128 v[150:153], v157 offset:2048
	ds_read_b128 v[158:161], v157 offset:3072
	s_add_i32 s50, 0, 0x18000
	s_waitcnt vmcnt(6)
	s_barrier
	v_mfma_f32_16x16x32_bf16 v[50:53], v[208:211], v[162:165], v[50:53]
	v_mfma_f32_16x16x32_bf16 v[42:45], v[228:231], v[162:165], v[42:45]
	v_mfma_f32_16x16x32_bf16 v[34:37], v[208:211], v[170:173], v[34:37]
	v_mfma_f32_16x16x32_bf16 v[26:29], v[228:231], v[170:173], v[26:29]
	v_mfma_f32_16x16x32_bf16 v[18:21], v[208:211], v[192:195], v[18:21]
	v_mfma_f32_16x16x32_bf16 v[10:13], v[228:231], v[192:195], v[10:13]
	v_mfma_f32_16x16x32_bf16 v[6:9], v[208:211], v[200:203], v[6:9]
	v_mfma_f32_16x16x32_bf16 v[2:5], v[228:231], v[200:203], v[2:5]
	v_mfma_f32_16x16x32_bf16 v[50:53], v[224:227], v[166:169], v[50:53]
	v_mfma_f32_16x16x32_bf16 v[42:45], v[232:235], v[166:169], v[42:45]
	v_mfma_f32_16x16x32_bf16 v[34:37], v[224:227], v[174:177], v[34:37]
	v_mfma_f32_16x16x32_bf16 v[26:29], v[232:235], v[174:177], v[26:29]
	v_mfma_f32_16x16x32_bf16 v[18:21], v[224:227], v[196:199], v[18:21]
	v_mfma_f32_16x16x32_bf16 v[10:13], v[232:235], v[196:199], v[10:13]
	v_mfma_f32_16x16x32_bf16 v[6:9], v[224:227], v[204:207], v[6:9]
	v_mfma_f32_16x16x32_bf16 v[2:5], v[232:235], v[204:207], v[2:5]
	s_barrier
	ds_read_b128 v[162:165], v156 offset:32768
	ds_read_b128 v[166:169], v156 offset:33792
	ds_read_b128 v[170:173], v156 offset:34816
	ds_read_b128 v[174:177], v156 offset:35840
	ds_read_b128 v[192:195], v156 offset:36864
	ds_read_b128 v[196:199], v156 offset:37888
	ds_read_b128 v[200:203], v156 offset:38912
	ds_read_b128 v[204:207], v156 offset:39936
	s_add_u32 s22, s22, 0x20000
	s_addc_u32 s23, s23, 0
	s_mov_b32 m0, s42
	v_lshl_add_u64 v[208:209], s[22:23], 0, v[144:145]
	global_load_lds_dwordx4 v[208:209], off
	v_lshl_add_u64 v[208:209], s[22:23], 0, v[140:141]
	s_mov_b32 m0, s43
	s_nop 0
	global_load_lds_dwordx4 v[208:209], off
	s_waitcnt lgkmcnt(8)
	s_barrier
	s_waitcnt lgkmcnt(0)
	v_mfma_f32_16x16x32_bf16 v[126:129], v[130:133], v[162:165], v[126:129]
	v_mfma_f32_16x16x32_bf16 v[122:125], v[150:153], v[162:165], v[122:125]
	v_mfma_f32_16x16x32_bf16 v[118:121], v[130:133], v[170:173], v[118:121]
	v_mfma_f32_16x16x32_bf16 v[110:113], v[150:153], v[170:173], v[110:113]
	v_mfma_f32_16x16x32_bf16 v[102:105], v[130:133], v[192:195], v[102:105]
	v_mfma_f32_16x16x32_bf16 v[94:97], v[150:153], v[192:195], v[94:97]
	v_mfma_f32_16x16x32_bf16 v[86:89], v[130:133], v[200:203], v[86:89]
	v_mfma_f32_16x16x32_bf16 v[78:81], v[150:153], v[200:203], v[78:81]
	v_mfma_f32_16x16x32_bf16 v[126:129], v[134:137], v[166:169], v[126:129]
	v_mfma_f32_16x16x32_bf16 v[122:125], v[158:161], v[166:169], v[122:125]
	v_mfma_f32_16x16x32_bf16 v[118:121], v[134:137], v[174:177], v[118:121]
	v_mfma_f32_16x16x32_bf16 v[110:113], v[158:161], v[174:177], v[110:113]
	v_mfma_f32_16x16x32_bf16 v[102:105], v[134:137], v[196:199], v[102:105]
	v_mfma_f32_16x16x32_bf16 v[94:97], v[158:161], v[196:199], v[94:97]
	v_mfma_f32_16x16x32_bf16 v[86:89], v[134:137], v[204:207], v[86:89]
	v_mfma_f32_16x16x32_bf16 v[78:81], v[158:161], v[204:207], v[78:81]
	s_barrier
	s_add_i32 s22, 0, 0x1c000
	s_add_i32 s23, s50, s36
	v_add_u32_e32 v157, s22, v154
	v_lshl_add_u64 v[178:179], v[178:179], 0, s[78:79]
	s_mov_b32 m0, s23
	ds_read_b128 v[208:211], v157
	ds_read_b128 v[224:227], v157 offset:1024
	ds_read_b128 v[228:231], v157 offset:2048
	ds_read_b128 v[232:235], v157 offset:3072
	global_load_lds_dwordx4 v[178:179], off
	v_lshl_add_u64 v[178:179], v[212:213], 0, s[78:79]
	s_add_i32 m0, s23, 0x2000
	s_nop 0
	global_load_lds_dwordx4 v[178:179], off
	s_mov_b32 m0, s25
	v_lshl_add_u64 v[178:179], v[236:237], 0, s[78:79]
	s_barrier
	s_waitcnt lgkmcnt(0)
	v_mfma_f32_16x16x32_bf16 v[114:117], v[208:211], v[162:165], v[114:117]
	v_mfma_f32_16x16x32_bf16 v[106:109], v[228:231], v[162:165], v[106:109]
	v_mfma_f32_16x16x32_bf16 v[98:101], v[208:211], v[170:173], v[98:101]
	v_mfma_f32_16x16x32_bf16 v[90:93], v[228:231], v[170:173], v[90:93]
	v_mfma_f32_16x16x32_bf16 v[82:85], v[208:211], v[192:195], v[82:85]
	v_mfma_f32_16x16x32_bf16 v[74:77], v[228:231], v[192:195], v[74:77]
	v_mfma_f32_16x16x32_bf16 v[70:73], v[208:211], v[200:203], v[70:73]
	v_mfma_f32_16x16x32_bf16 v[66:69], v[228:231], v[200:203], v[66:69]
	v_mfma_f32_16x16x32_bf16 v[114:117], v[224:227], v[166:169], v[114:117]
	v_mfma_f32_16x16x32_bf16 v[106:109], v[232:235], v[166:169], v[106:109]
	v_mfma_f32_16x16x32_bf16 v[98:101], v[224:227], v[174:177], v[98:101]
	v_mfma_f32_16x16x32_bf16 v[90:93], v[232:235], v[174:177], v[90:93]
	v_mfma_f32_16x16x32_bf16 v[82:85], v[224:227], v[196:199], v[82:85]
	v_mfma_f32_16x16x32_bf16 v[74:77], v[232:235], v[196:199], v[74:77]
	v_mfma_f32_16x16x32_bf16 v[70:73], v[224:227], v[204:207], v[70:73]
	v_mfma_f32_16x16x32_bf16 v[66:69], v[232:235], v[204:207], v[66:69]
	s_barrier
	ds_read_b128 v[162:165], v156 offset:49152
	ds_read_b128 v[166:169], v156 offset:50176
	ds_read_b128 v[170:173], v156 offset:51200
	ds_read_b128 v[174:177], v156 offset:52224
	ds_read_b128 v[192:195], v156 offset:53248
	ds_read_b128 v[196:199], v156 offset:54272
	ds_read_b128 v[200:203], v156 offset:55296
	ds_read_b128 v[204:207], v156 offset:56320
	global_load_lds_dwordx4 v[178:179], off
	v_lshl_add_u64 v[178:179], v[238:239], 0, s[78:79]
	s_mov_b32 m0, s26
	s_nop 0
	global_load_lds_dwordx4 v[178:179], off
	s_waitcnt vmcnt(10)
	s_barrier
	s_waitcnt lgkmcnt(0)
	v_mfma_f32_16x16x32_bf16 v[62:65], v[130:133], v[162:165], v[62:65]
	v_mfma_f32_16x16x32_bf16 v[58:61], v[150:153], v[162:165], v[58:61]
	v_mfma_f32_16x16x32_bf16 v[54:57], v[130:133], v[170:173], v[54:57]
	v_mfma_f32_16x16x32_bf16 v[46:49], v[150:153], v[170:173], v[46:49]
	v_mfma_f32_16x16x32_bf16 v[38:41], v[130:133], v[192:195], v[38:41]
	v_mfma_f32_16x16x32_bf16 v[30:33], v[150:153], v[192:195], v[30:33]
	v_mfma_f32_16x16x32_bf16 v[22:25], v[130:133], v[200:203], v[22:25]
	v_mfma_f32_16x16x32_bf16 v[14:17], v[150:153], v[200:203], v[14:17]
	v_mfma_f32_16x16x32_bf16 v[62:65], v[134:137], v[166:169], v[62:65]
	v_mfma_f32_16x16x32_bf16 v[58:61], v[158:161], v[166:169], v[58:61]
	v_mfma_f32_16x16x32_bf16 v[54:57], v[134:137], v[174:177], v[54:57]
	v_mfma_f32_16x16x32_bf16 v[46:49], v[158:161], v[174:177], v[46:49]
	v_mfma_f32_16x16x32_bf16 v[38:41], v[134:137], v[196:199], v[38:41]
	v_mfma_f32_16x16x32_bf16 v[30:33], v[158:161], v[196:199], v[30:33]
	v_mfma_f32_16x16x32_bf16 v[22:25], v[134:137], v[204:207], v[22:25]
	v_mfma_f32_16x16x32_bf16 v[14:17], v[158:161], v[204:207], v[14:17]
	s_barrier
	s_add_u32 s20, s20, 0x20080
	s_addc_u32 s21, s21, 0
	s_add_i32 s22, s22, s36
	v_lshl_add_u64 v[130:131], s[20:21], 0, v[142:143]
	s_mov_b32 m0, s22
	s_nop 0
	global_load_lds_dwordx4 v[130:131], off
	v_lshl_add_u64 v[130:131], s[20:21], 0, v[138:139]
	s_add_i32 m0, s22, 0x2000
	s_nop 0
	global_load_lds_dwordx4 v[130:131], off
	v_add_u32_e32 v157, 0x10000, v154
	ds_read_b128 v[130:133], v157
	ds_read_b128 v[134:137], v157 offset:1024
	ds_read_b128 v[150:153], v157 offset:2048
	ds_read_b128 v[158:161], v157 offset:3072
	s_add_i32 s49, s49, 2
	s_add_u32 s18, s18, 0x100
	s_addc_u32 s19, s19, 0
	s_add_u32 s47, s47, 0x100
	s_addc_u32 s48, s48, 0
	s_cmp_gt_u32 s49, 5
	s_waitcnt vmcnt(6)
	s_barrier
	v_mfma_f32_16x16x32_bf16 v[50:53], v[208:211], v[162:165], v[50:53]
	v_mfma_f32_16x16x32_bf16 v[42:45], v[228:231], v[162:165], v[42:45]
	v_mfma_f32_16x16x32_bf16 v[34:37], v[208:211], v[170:173], v[34:37]
	v_mfma_f32_16x16x32_bf16 v[26:29], v[228:231], v[170:173], v[26:29]
	v_mfma_f32_16x16x32_bf16 v[18:21], v[208:211], v[192:195], v[18:21]
	v_mfma_f32_16x16x32_bf16 v[10:13], v[228:231], v[192:195], v[10:13]
	v_mfma_f32_16x16x32_bf16 v[6:9], v[208:211], v[200:203], v[6:9]
	v_mfma_f32_16x16x32_bf16 v[2:5], v[228:231], v[200:203], v[2:5]
	v_mfma_f32_16x16x32_bf16 v[50:53], v[224:227], v[166:169], v[50:53]
	v_mfma_f32_16x16x32_bf16 v[42:45], v[232:235], v[166:169], v[42:45]
	v_mfma_f32_16x16x32_bf16 v[34:37], v[224:227], v[174:177], v[34:37]
	v_mfma_f32_16x16x32_bf16 v[26:29], v[232:235], v[174:177], v[26:29]
	v_mfma_f32_16x16x32_bf16 v[18:21], v[224:227], v[196:199], v[18:21]
	v_mfma_f32_16x16x32_bf16 v[10:13], v[232:235], v[196:199], v[10:13]
	v_mfma_f32_16x16x32_bf16 v[6:9], v[224:227], v[204:207], v[6:9]
	v_mfma_f32_16x16x32_bf16 v[2:5], v[232:235], v[204:207], v[2:5]
	s_barrier
	s_cbranch_scc0 .LBB0_386
	s_waitcnt lgkmcnt(0)
	v_lshl_add_u32 v164, s29, 8, v1
	v_lshl_or_b32 v150, s28, 8, v155
	s_mov_b64 s[18:19], -1
	s_cmp_lt_i32 s28, 8
	v_or_b32_e32 v163, 16, v164
	v_or_b32_e32 v162, 32, v164
	v_or_b32_e32 v161, 48, v164
	v_add_u32_e32 v160, 0x80, v164
	v_add_u32_e32 v159, 0x90, v164
	v_add_u32_e32 v158, 0xa0, v164
	v_add_u32_e32 v157, 0xb0, v164
	s_cbranch_scc1 .LBB0_389
	v_lshlrev_b32_e32 v130, 7, v164
	v_readlane_b32 s4, v255, 4
	v_and_b32_e32 v132, 0x3e780, v130
	v_mov_b32_e32 v133, v0
	v_readlane_b32 s5, v255, 5
	v_readlane_b32 s6, v255, 6
	v_readlane_b32 s7, v255, 7
	v_lshlrev_b32_e32 v130, 1, v150
	v_lshl_add_u64 v[134:135], s[4:5], 0, v[132:133]
	v_and_b32_e32 v130, 0x70, v130
	v_mov_b32_e32 v131, v0
	v_lshl_add_u64 v[132:133], s[6:7], 0, v[132:133]
	v_lshl_add_u64 v[152:153], v[132:133], 0, v[130:131]
	v_lshl_add_u64 v[136:137], v[134:135], 0, v[130:131]
	global_load_dwordx4 v[170:173], v[152:153], off
	global_load_dwordx4 v[166:169], v[136:137], off
	v_readlane_b32 s8, v255, 8
	v_readlane_b32 s9, v255, 9
	v_mov_b32_e32 v151, v0
	v_lshlrev_b64 v[134:135], 1, v[150:151]
	v_mov_b64_e32 v[132:133], s[8:9]
	v_mad_i64_i32 v[174:175], s[18:19], v164, s24, v[132:133]
	v_lshl_add_u64 v[174:175], v[174:175], 0, v[134:135]
	v_readlane_b32 s10, v255, 10
	v_readlane_b32 s11, v255, 11
	s_waitcnt vmcnt(0)
	v_pk_mul_f32 v[172:173], v[172:173], s[86:87] op_sel_hi:[1,0]
	v_pk_mul_f32 v[170:171], v[170:171], s[86:87] op_sel_hi:[1,0]
	v_pk_mul_f32 v[168:169], v[168:169], s[86:87] op_sel_hi:[1,0]
	v_pk_mul_f32 v[166:167], v[166:167], s[86:87] op_sel_hi:[1,0]
	v_pk_mul_f32 v[176:177], v[124:125], v[172:173]
	v_pk_mul_f32 v[178:179], v[122:123], v[170:171]
	v_pk_mul_f32 v[172:173], v[128:129], v[172:173]
	v_pk_mul_f32 v[170:171], v[126:127], v[170:171]
	v_pk_fma_f32 v[176:177], v[128:129], v[168:169], v[176:177] neg_lo:[0,0,1] neg_hi:[0,0,1]
	v_pk_fma_f32 v[178:179], v[126:127], v[166:167], v[178:179] neg_lo:[0,0,1] neg_hi:[0,0,1]
	v_pk_fma_f32 v[172:173], v[124:125], v[168:169], v[172:173]
	v_pk_fma_f32 v[168:169], v[122:123], v[166:167], v[170:171]
	v_cvt_pk_bf16_f32 v166, v178, v179
	v_cvt_pk_bf16_f32 v167, v176, v177
	v_cvt_pk_bf16_f32 v168, v168, v169
	v_cvt_pk_bf16_f32 v169, v172, v173
	global_store_dwordx4 v[174:175], v[166:169], off
	global_load_dwordx4 v[166:169], v[136:137], off
	s_nop 0
	global_load_dwordx4 v[170:173], v[152:153], off
	v_lshlrev_b32_e32 v136, 7, v163
	v_mov_b32_e32 v137, v0
	v_and_b32_e32 v136, 0x3ef80, v136
	v_lshl_add_u64 v[152:153], s[4:5], 0, v[136:137]
	v_lshl_add_u64 v[136:137], s[6:7], 0, v[136:137]
	v_lshl_add_u64 v[136:137], v[136:137], 0, v[130:131]
	v_lshl_add_u64 v[152:153], v[152:153], 0, v[130:131]
	s_waitcnt vmcnt(0)
	v_pk_mul_f32 v[168:169], v[168:169], s[86:87] op_sel_hi:[1,0]
	v_pk_mul_f32 v[172:173], v[172:173], s[86:87] op_sel_hi:[1,0]
	v_pk_mul_f32 v[170:171], v[170:171], s[86:87] op_sel_hi:[1,0]
	v_pk_mul_f32 v[166:167], v[166:167], s[86:87] op_sel_hi:[1,0]
	v_pk_mul_f32 v[176:177], v[108:109], v[172:173]
	v_pk_mul_f32 v[178:179], v[106:107], v[170:171]
	v_pk_mul_f32 v[172:173], v[116:117], v[172:173]
	v_pk_mul_f32 v[170:171], v[114:115], v[170:171]
	v_pk_fma_f32 v[176:177], v[116:117], v[168:169], v[176:177] neg_lo:[0,0,1] neg_hi:[0,0,1]
	v_pk_fma_f32 v[178:179], v[114:115], v[166:167], v[178:179] neg_lo:[0,0,1] neg_hi:[0,0,1]
	v_pk_fma_f32 v[172:173], v[108:109], v[168:169], v[172:173]
	v_pk_fma_f32 v[168:169], v[106:107], v[166:167], v[170:171]
	v_cvt_pk_bf16_f32 v166, v178, v179
	v_cvt_pk_bf16_f32 v167, v176, v177
	v_cvt_pk_bf16_f32 v168, v168, v169
	v_cvt_pk_bf16_f32 v169, v172, v173
	global_store_dwordx4 v[174:175], v[166:169], off offset:256
	global_load_dwordx4 v[170:173], v[136:137], off
	v_mad_i64_i32 v[174:175], s[18:19], v163, s24, v[132:133]
	global_load_dwordx4 v[166:169], v[152:153], off
	v_lshl_add_u64 v[174:175], v[174:175], 0, v[134:135]
	s_waitcnt vmcnt(0)
	v_pk_mul_f32 v[172:173], v[172:173], s[86:87] op_sel_hi:[1,0]
	v_pk_mul_f32 v[170:171], v[170:171], s[86:87] op_sel_hi:[1,0]
	v_pk_mul_f32 v[176:177], v[112:113], v[172:173]
	v_pk_mul_f32 v[168:169], v[168:169], s[86:87] op_sel_hi:[1,0]
	v_pk_mul_f32 v[166:167], v[166:167], s[86:87] op_sel_hi:[1,0]
	v_pk_mul_f32 v[178:179], v[110:111], v[170:171]
	v_pk_mul_f32 v[172:173], v[120:121], v[172:173]
	v_pk_mul_f32 v[170:171], v[118:119], v[170:171]
	v_pk_fma_f32 v[176:177], v[120:121], v[168:169], v[176:177] neg_lo:[0,0,1] neg_hi:[0,0,1]
	v_pk_fma_f32 v[178:179], v[118:119], v[166:167], v[178:179] neg_lo:[0,0,1] neg_hi:[0,0,1]
	v_pk_fma_f32 v[172:173], v[112:113], v[168:169], v[172:173]
	v_pk_fma_f32 v[168:169], v[110:111], v[166:167], v[170:171]
	v_cvt_pk_bf16_f32 v166, v178, v179
	v_cvt_pk_bf16_f32 v167, v176, v177
	v_cvt_pk_bf16_f32 v168, v168, v169
	v_cvt_pk_bf16_f32 v169, v172, v173
	global_store_dwordx4 v[174:175], v[166:169], off
	global_load_dwordx4 v[166:169], v[152:153], off
	s_nop 0
	global_load_dwordx4 v[170:173], v[136:137], off
	v_lshlrev_b32_e32 v136, 7, v162
	v_mov_b32_e32 v137, v0
	v_and_b32_e32 v136, 0x3f780, v136
	v_lshl_add_u64 v[152:153], s[4:5], 0, v[136:137]
	v_lshl_add_u64 v[136:137], s[6:7], 0, v[136:137]
	v_lshl_add_u64 v[136:137], v[136:137], 0, v[130:131]
	v_lshl_add_u64 v[152:153], v[152:153], 0, v[130:131]
	s_waitcnt vmcnt(0)
	v_pk_mul_f32 v[168:169], v[168:169], s[86:87] op_sel_hi:[1,0]
	v_pk_mul_f32 v[172:173], v[172:173], s[86:87] op_sel_hi:[1,0]
	v_pk_mul_f32 v[170:171], v[170:171], s[86:87] op_sel_hi:[1,0]
	v_pk_mul_f32 v[166:167], v[166:167], s[86:87] op_sel_hi:[1,0]
	v_pk_mul_f32 v[176:177], v[92:93], v[172:173]
	v_pk_mul_f32 v[178:179], v[90:91], v[170:171]
	v_pk_mul_f32 v[172:173], v[100:101], v[172:173]
	v_pk_mul_f32 v[170:171], v[98:99], v[170:171]
	v_pk_fma_f32 v[176:177], v[100:101], v[168:169], v[176:177] neg_lo:[0,0,1] neg_hi:[0,0,1]
	v_pk_fma_f32 v[178:179], v[98:99], v[166:167], v[178:179] neg_lo:[0,0,1] neg_hi:[0,0,1]
	v_pk_fma_f32 v[172:173], v[92:93], v[168:169], v[172:173]
	v_pk_fma_f32 v[168:169], v[90:91], v[166:167], v[170:171]
	v_cvt_pk_bf16_f32 v166, v178, v179
	v_cvt_pk_bf16_f32 v167, v176, v177
	v_cvt_pk_bf16_f32 v168, v168, v169
	v_cvt_pk_bf16_f32 v169, v172, v173
	global_store_dwordx4 v[174:175], v[166:169], off offset:256
	global_load_dwordx4 v[170:173], v[136:137], off
	v_mad_i64_i32 v[174:175], s[18:19], v162, s24, v[132:133]
	global_load_dwordx4 v[166:169], v[152:153], off
	v_lshl_add_u64 v[174:175], v[174:175], 0, v[134:135]
	s_waitcnt vmcnt(0)
	v_pk_mul_f32 v[172:173], v[172:173], s[86:87] op_sel_hi:[1,0]
	v_pk_mul_f32 v[170:171], v[170:171], s[86:87] op_sel_hi:[1,0]
	v_pk_mul_f32 v[176:177], v[96:97], v[172:173]
	v_pk_mul_f32 v[168:169], v[168:169], s[86:87] op_sel_hi:[1,0]
	v_pk_mul_f32 v[166:167], v[166:167], s[86:87] op_sel_hi:[1,0]
	v_pk_mul_f32 v[178:179], v[94:95], v[170:171]
	v_pk_mul_f32 v[172:173], v[104:105], v[172:173]
	v_pk_mul_f32 v[170:171], v[102:103], v[170:171]
	v_pk_fma_f32 v[176:177], v[104:105], v[168:169], v[176:177] neg_lo:[0,0,1] neg_hi:[0,0,1]
	v_pk_fma_f32 v[178:179], v[102:103], v[166:167], v[178:179] neg_lo:[0,0,1] neg_hi:[0,0,1]
	v_pk_fma_f32 v[172:173], v[96:97], v[168:169], v[172:173]
	v_pk_fma_f32 v[168:169], v[94:95], v[166:167], v[170:171]
	v_cvt_pk_bf16_f32 v166, v178, v179
	v_cvt_pk_bf16_f32 v167, v176, v177
	v_cvt_pk_bf16_f32 v168, v168, v169
	v_cvt_pk_bf16_f32 v169, v172, v173
	global_store_dwordx4 v[174:175], v[166:169], off
	global_load_dwordx4 v[166:169], v[152:153], off
	s_nop 0
	global_load_dwordx4 v[170:173], v[136:137], off
	v_lshlrev_b32_e32 v136, 7, v161
	v_mov_b32_e32 v137, v0
	v_and_b32_e32 v136, 0x3ff80, v136
	v_lshl_add_u64 v[152:153], s[4:5], 0, v[136:137]
	v_lshl_add_u64 v[136:137], s[6:7], 0, v[136:137]
	v_lshl_add_u64 v[136:137], v[136:137], 0, v[130:131]
	v_lshl_add_u64 v[152:153], v[152:153], 0, v[130:131]
	s_waitcnt vmcnt(0)
	v_pk_mul_f32 v[168:169], v[168:169], s[86:87] op_sel_hi:[1,0]
	v_pk_mul_f32 v[172:173], v[172:173], s[86:87] op_sel_hi:[1,0]
	v_pk_mul_f32 v[170:171], v[170:171], s[86:87] op_sel_hi:[1,0]
	v_pk_mul_f32 v[166:167], v[166:167], s[86:87] op_sel_hi:[1,0]
	v_pk_mul_f32 v[176:177], v[76:77], v[172:173]
	v_pk_mul_f32 v[178:179], v[74:75], v[170:171]
	v_pk_mul_f32 v[172:173], v[84:85], v[172:173]
	v_pk_mul_f32 v[170:171], v[82:83], v[170:171]
	v_pk_fma_f32 v[176:177], v[84:85], v[168:169], v[176:177] neg_lo:[0,0,1] neg_hi:[0,0,1]
	v_pk_fma_f32 v[178:179], v[82:83], v[166:167], v[178:179] neg_lo:[0,0,1] neg_hi:[0,0,1]
	v_pk_fma_f32 v[172:173], v[76:77], v[168:169], v[172:173]
	v_pk_fma_f32 v[168:169], v[74:75], v[166:167], v[170:171]
	v_cvt_pk_bf16_f32 v166, v178, v179
	v_cvt_pk_bf16_f32 v167, v176, v177
	v_cvt_pk_bf16_f32 v168, v168, v169
	v_cvt_pk_bf16_f32 v169, v172, v173
	global_store_dwordx4 v[174:175], v[166:169], off offset:256
	global_load_dwordx4 v[170:173], v[136:137], off
	v_mad_i64_i32 v[174:175], s[18:19], v161, s24, v[132:133]
	global_load_dwordx4 v[166:169], v[152:153], off
	v_lshl_add_u64 v[174:175], v[174:175], 0, v[134:135]
	s_waitcnt vmcnt(0)
	v_pk_mul_f32 v[172:173], v[172:173], s[86:87] op_sel_hi:[1,0]
	v_pk_mul_f32 v[170:171], v[170:171], s[86:87] op_sel_hi:[1,0]
	v_pk_mul_f32 v[176:177], v[80:81], v[172:173]
	v_pk_mul_f32 v[168:169], v[168:169], s[86:87] op_sel_hi:[1,0]
	v_pk_mul_f32 v[166:167], v[166:167], s[86:87] op_sel_hi:[1,0]
	v_pk_mul_f32 v[178:179], v[78:79], v[170:171]
	v_pk_mul_f32 v[172:173], v[88:89], v[172:173]
	v_pk_mul_f32 v[170:171], v[86:87], v[170:171]
	v_pk_fma_f32 v[176:177], v[88:89], v[168:169], v[176:177] neg_lo:[0,0,1] neg_hi:[0,0,1]
	v_pk_fma_f32 v[178:179], v[86:87], v[166:167], v[178:179] neg_lo:[0,0,1] neg_hi:[0,0,1]
	v_pk_fma_f32 v[172:173], v[80:81], v[168:169], v[172:173]
	v_pk_fma_f32 v[168:169], v[78:79], v[166:167], v[170:171]
	v_cvt_pk_bf16_f32 v166, v178, v179
	v_cvt_pk_bf16_f32 v167, v176, v177
	v_cvt_pk_bf16_f32 v168, v168, v169
	v_cvt_pk_bf16_f32 v169, v172, v173
	global_store_dwordx4 v[174:175], v[166:169], off
	global_load_dwordx4 v[166:169], v[152:153], off
	s_nop 0
	global_load_dwordx4 v[170:173], v[136:137], off
	v_lshlrev_b32_e32 v136, 7, v160
	v_mov_b32_e32 v137, v0
	v_and_b32_e32 v136, 0x3e780, v136
	v_lshl_add_u64 v[152:153], s[4:5], 0, v[136:137]
	v_lshl_add_u64 v[136:137], s[6:7], 0, v[136:137]
	v_lshl_add_u64 v[136:137], v[136:137], 0, v[130:131]
	v_lshl_add_u64 v[152:153], v[152:153], 0, v[130:131]
	s_waitcnt vmcnt(0)
	v_pk_mul_f32 v[168:169], v[168:169], s[86:87] op_sel_hi:[1,0]
	v_pk_mul_f32 v[172:173], v[172:173], s[86:87] op_sel_hi:[1,0]
	v_pk_mul_f32 v[170:171], v[170:171], s[86:87] op_sel_hi:[1,0]
	v_pk_mul_f32 v[166:167], v[166:167], s[86:87] op_sel_hi:[1,0]
	v_pk_mul_f32 v[176:177], v[68:69], v[172:173]
	v_pk_mul_f32 v[178:179], v[66:67], v[170:171]
	v_pk_mul_f32 v[172:173], v[72:73], v[172:173]
	v_pk_mul_f32 v[170:171], v[70:71], v[170:171]
	v_pk_fma_f32 v[176:177], v[72:73], v[168:169], v[176:177] neg_lo:[0,0,1] neg_hi:[0,0,1]
	v_pk_fma_f32 v[178:179], v[70:71], v[166:167], v[178:179] neg_lo:[0,0,1] neg_hi:[0,0,1]
	v_pk_fma_f32 v[172:173], v[68:69], v[168:169], v[172:173]
	v_pk_fma_f32 v[168:169], v[66:67], v[166:167], v[170:171]
	v_cvt_pk_bf16_f32 v166, v178, v179
	v_cvt_pk_bf16_f32 v167, v176, v177
	v_cvt_pk_bf16_f32 v168, v168, v169
	v_cvt_pk_bf16_f32 v169, v172, v173
	global_store_dwordx4 v[174:175], v[166:169], off offset:256
	global_load_dwordx4 v[170:173], v[136:137], off
	v_mad_i64_i32 v[174:175], s[18:19], v160, s24, v[132:133]
	global_load_dwordx4 v[166:169], v[152:153], off
	v_lshl_add_u64 v[174:175], v[174:175], 0, v[134:135]
	s_waitcnt vmcnt(0)
	v_pk_mul_f32 v[172:173], v[172:173], s[86:87] op_sel_hi:[1,0]
	v_pk_mul_f32 v[170:171], v[170:171], s[86:87] op_sel_hi:[1,0]
	v_pk_mul_f32 v[176:177], v[60:61], v[172:173]
	v_pk_mul_f32 v[168:169], v[168:169], s[86:87] op_sel_hi:[1,0]
	v_pk_mul_f32 v[166:167], v[166:167], s[86:87] op_sel_hi:[1,0]
	v_pk_mul_f32 v[178:179], v[58:59], v[170:171]
	v_pk_mul_f32 v[172:173], v[64:65], v[172:173]
	v_pk_mul_f32 v[170:171], v[62:63], v[170:171]
	v_pk_fma_f32 v[176:177], v[64:65], v[168:169], v[176:177] neg_lo:[0,0,1] neg_hi:[0,0,1]
	v_pk_fma_f32 v[178:179], v[62:63], v[166:167], v[178:179] neg_lo:[0,0,1] neg_hi:[0,0,1]
	v_pk_fma_f32 v[172:173], v[60:61], v[168:169], v[172:173]
	v_pk_fma_f32 v[168:169], v[58:59], v[166:167], v[170:171]
	v_cvt_pk_bf16_f32 v166, v178, v179
	v_cvt_pk_bf16_f32 v167, v176, v177
	v_cvt_pk_bf16_f32 v168, v168, v169
	v_cvt_pk_bf16_f32 v169, v172, v173
	global_store_dwordx4 v[174:175], v[166:169], off
	global_load_dwordx4 v[166:169], v[152:153], off
	s_nop 0
	global_load_dwordx4 v[170:173], v[136:137], off
	v_lshlrev_b32_e32 v136, 7, v159
	v_mov_b32_e32 v137, v0
	v_and_b32_e32 v136, 0x3ef80, v136
	v_lshl_add_u64 v[152:153], s[4:5], 0, v[136:137]
	v_lshl_add_u64 v[136:137], s[6:7], 0, v[136:137]
	v_lshl_add_u64 v[136:137], v[136:137], 0, v[130:131]
	v_lshl_add_u64 v[152:153], v[152:153], 0, v[130:131]
	s_waitcnt vmcnt(0)
	v_pk_mul_f32 v[168:169], v[168:169], s[86:87] op_sel_hi:[1,0]
	v_pk_mul_f32 v[172:173], v[172:173], s[86:87] op_sel_hi:[1,0]
	v_pk_mul_f32 v[170:171], v[170:171], s[86:87] op_sel_hi:[1,0]
	v_pk_mul_f32 v[166:167], v[166:167], s[86:87] op_sel_hi:[1,0]
	v_pk_mul_f32 v[176:177], v[44:45], v[172:173]
	v_pk_mul_f32 v[178:179], v[42:43], v[170:171]
	v_pk_mul_f32 v[172:173], v[52:53], v[172:173]
	v_pk_mul_f32 v[170:171], v[50:51], v[170:171]
	v_pk_fma_f32 v[176:177], v[52:53], v[168:169], v[176:177] neg_lo:[0,0,1] neg_hi:[0,0,1]
	v_pk_fma_f32 v[178:179], v[50:51], v[166:167], v[178:179] neg_lo:[0,0,1] neg_hi:[0,0,1]
	v_pk_fma_f32 v[172:173], v[44:45], v[168:169], v[172:173]
	v_pk_fma_f32 v[168:169], v[42:43], v[166:167], v[170:171]
	v_cvt_pk_bf16_f32 v166, v178, v179
	v_cvt_pk_bf16_f32 v167, v176, v177
	v_cvt_pk_bf16_f32 v168, v168, v169
	v_cvt_pk_bf16_f32 v169, v172, v173
	global_store_dwordx4 v[174:175], v[166:169], off offset:256
	global_load_dwordx4 v[170:173], v[136:137], off
	v_mad_i64_i32 v[174:175], s[18:19], v159, s24, v[132:133]
	global_load_dwordx4 v[166:169], v[152:153], off
	v_lshl_add_u64 v[174:175], v[174:175], 0, v[134:135]
	s_waitcnt vmcnt(0)
	v_pk_mul_f32 v[172:173], v[172:173], s[86:87] op_sel_hi:[1,0]
	v_pk_mul_f32 v[170:171], v[170:171], s[86:87] op_sel_hi:[1,0]
	v_pk_mul_f32 v[176:177], v[48:49], v[172:173]
	v_pk_mul_f32 v[168:169], v[168:169], s[86:87] op_sel_hi:[1,0]
	v_pk_mul_f32 v[166:167], v[166:167], s[86:87] op_sel_hi:[1,0]
	v_pk_mul_f32 v[178:179], v[46:47], v[170:171]
	v_pk_mul_f32 v[172:173], v[56:57], v[172:173]
	v_pk_mul_f32 v[170:171], v[54:55], v[170:171]
	v_pk_fma_f32 v[176:177], v[56:57], v[168:169], v[176:177] neg_lo:[0,0,1] neg_hi:[0,0,1]
	v_pk_fma_f32 v[178:179], v[54:55], v[166:167], v[178:179] neg_lo:[0,0,1] neg_hi:[0,0,1]
	v_pk_fma_f32 v[172:173], v[48:49], v[168:169], v[172:173]
	v_pk_fma_f32 v[168:169], v[46:47], v[166:167], v[170:171]
	v_cvt_pk_bf16_f32 v166, v178, v179
	v_cvt_pk_bf16_f32 v167, v176, v177
	v_cvt_pk_bf16_f32 v168, v168, v169
	v_cvt_pk_bf16_f32 v169, v172, v173
	global_store_dwordx4 v[174:175], v[166:169], off
	global_load_dwordx4 v[166:169], v[152:153], off
	s_nop 0
	global_load_dwordx4 v[170:173], v[136:137], off
	v_lshlrev_b32_e32 v136, 7, v158
	v_mov_b32_e32 v137, v0
	v_and_b32_e32 v136, 0x3f780, v136
	v_lshl_add_u64 v[152:153], s[4:5], 0, v[136:137]
	v_lshl_add_u64 v[136:137], s[6:7], 0, v[136:137]
	v_lshl_add_u64 v[136:137], v[136:137], 0, v[130:131]
	v_lshl_add_u64 v[152:153], v[152:153], 0, v[130:131]
	s_waitcnt vmcnt(0)
	v_pk_mul_f32 v[168:169], v[168:169], s[86:87] op_sel_hi:[1,0]
	v_pk_mul_f32 v[172:173], v[172:173], s[86:87] op_sel_hi:[1,0]
	v_pk_mul_f32 v[170:171], v[170:171], s[86:87] op_sel_hi:[1,0]
	v_pk_mul_f32 v[166:167], v[166:167], s[86:87] op_sel_hi:[1,0]
	v_pk_mul_f32 v[176:177], v[28:29], v[172:173]
	v_pk_mul_f32 v[178:179], v[26:27], v[170:171]
	v_pk_mul_f32 v[172:173], v[36:37], v[172:173]
	v_pk_mul_f32 v[170:171], v[34:35], v[170:171]
	v_pk_fma_f32 v[176:177], v[36:37], v[168:169], v[176:177] neg_lo:[0,0,1] neg_hi:[0,0,1]
	v_pk_fma_f32 v[178:179], v[34:35], v[166:167], v[178:179] neg_lo:[0,0,1] neg_hi:[0,0,1]
	v_pk_fma_f32 v[172:173], v[28:29], v[168:169], v[172:173]
	v_pk_fma_f32 v[168:169], v[26:27], v[166:167], v[170:171]
	v_cvt_pk_bf16_f32 v166, v178, v179
	v_cvt_pk_bf16_f32 v167, v176, v177
	v_cvt_pk_bf16_f32 v168, v168, v169
	v_cvt_pk_bf16_f32 v169, v172, v173
	global_store_dwordx4 v[174:175], v[166:169], off offset:256
	global_load_dwordx4 v[170:173], v[136:137], off
	v_mad_i64_i32 v[174:175], s[18:19], v158, s24, v[132:133]
	global_load_dwordx4 v[166:169], v[152:153], off
	v_lshl_add_u64 v[174:175], v[174:175], 0, v[134:135]
	s_waitcnt vmcnt(0)
	v_pk_mul_f32 v[172:173], v[172:173], s[86:87] op_sel_hi:[1,0]
	v_pk_mul_f32 v[170:171], v[170:171], s[86:87] op_sel_hi:[1,0]
	v_pk_mul_f32 v[176:177], v[32:33], v[172:173]
	v_pk_mul_f32 v[168:169], v[168:169], s[86:87] op_sel_hi:[1,0]
	v_pk_mul_f32 v[166:167], v[166:167], s[86:87] op_sel_hi:[1,0]
	v_pk_mul_f32 v[178:179], v[30:31], v[170:171]
	v_pk_mul_f32 v[172:173], v[40:41], v[172:173]
	v_pk_mul_f32 v[170:171], v[38:39], v[170:171]
	v_pk_fma_f32 v[176:177], v[40:41], v[168:169], v[176:177] neg_lo:[0,0,1] neg_hi:[0,0,1]
	v_pk_fma_f32 v[178:179], v[38:39], v[166:167], v[178:179] neg_lo:[0,0,1] neg_hi:[0,0,1]
	v_pk_fma_f32 v[172:173], v[32:33], v[168:169], v[172:173]
	v_pk_fma_f32 v[168:169], v[30:31], v[166:167], v[170:171]
	v_cvt_pk_bf16_f32 v166, v178, v179
	v_cvt_pk_bf16_f32 v167, v176, v177
	v_cvt_pk_bf16_f32 v168, v168, v169
	v_cvt_pk_bf16_f32 v169, v172, v173
	global_store_dwordx4 v[174:175], v[166:169], off
	global_load_dwordx4 v[166:169], v[152:153], off
	s_nop 0
	global_load_dwordx4 v[170:173], v[136:137], off
	v_lshlrev_b32_e32 v136, 7, v157
	v_mov_b32_e32 v137, v0
	v_and_b32_e32 v136, 0x3ff80, v136
	v_lshl_add_u64 v[152:153], s[4:5], 0, v[136:137]
	v_lshl_add_u64 v[176:177], v[152:153], 0, v[130:131]
	v_lshl_add_u64 v[136:137], s[6:7], 0, v[136:137]
	v_lshl_add_u64 v[136:137], v[136:137], 0, v[130:131]
	v_mad_i64_i32 v[130:131], s[18:19], v157, s24, v[132:133]
	s_mov_b64 s[18:19], 0
	s_waitcnt vmcnt(0)
	v_pk_mul_f32 v[152:153], v[168:169], s[86:87] op_sel_hi:[1,0]
	v_pk_mul_f32 v[168:169], v[172:173], s[86:87] op_sel_hi:[1,0]
	v_pk_mul_f32 v[170:171], v[170:171], s[86:87] op_sel_hi:[1,0]
	v_pk_mul_f32 v[166:167], v[166:167], s[86:87] op_sel_hi:[1,0]
	v_pk_mul_f32 v[172:173], v[12:13], v[168:169]
	v_pk_mul_f32 v[178:179], v[10:11], v[170:171]
	v_pk_mul_f32 v[168:169], v[20:21], v[168:169]
	v_pk_mul_f32 v[170:171], v[18:19], v[170:171]
	v_pk_fma_f32 v[172:173], v[20:21], v[152:153], v[172:173] neg_lo:[0,0,1] neg_hi:[0,0,1]
	v_pk_fma_f32 v[178:179], v[18:19], v[166:167], v[178:179] neg_lo:[0,0,1] neg_hi:[0,0,1]
	v_pk_fma_f32 v[152:153], v[12:13], v[152:153], v[168:169]
	v_pk_fma_f32 v[168:169], v[10:11], v[166:167], v[170:171]
	v_cvt_pk_bf16_f32 v166, v178, v179
	v_cvt_pk_bf16_f32 v167, v172, v173
	v_cvt_pk_bf16_f32 v168, v168, v169
	v_cvt_pk_bf16_f32 v169, v152, v153
	global_store_dwordx4 v[174:175], v[166:169], off offset:256
	global_load_dwordx4 v[166:169], v[176:177], off
	v_lshl_add_u64 v[152:153], v[130:131], 0, v[134:135]
	global_load_dwordx4 v[170:173], v[136:137], off
	s_waitcnt vmcnt(0)
	v_pk_mul_f32 v[132:133], v[166:167], s[86:87] op_sel_hi:[1,0]
	v_pk_mul_f32 v[130:131], v[168:169], s[86:87] op_sel_hi:[1,0]
	v_pk_mul_f32 v[134:135], v[172:173], s[86:87] op_sel_hi:[1,0]
	v_pk_mul_f32 v[166:167], v[170:171], s[86:87] op_sel_hi:[1,0]
	v_pk_mul_f32 v[168:169], v[16:17], v[134:135]
	v_pk_mul_f32 v[170:171], v[14:15], v[166:167]
	v_pk_mul_f32 v[134:135], v[24:25], v[134:135]
	v_pk_mul_f32 v[166:167], v[22:23], v[166:167]
	v_pk_fma_f32 v[168:169], v[24:25], v[130:131], v[168:169] neg_lo:[0,0,1] neg_hi:[0,0,1]
	v_pk_fma_f32 v[170:171], v[22:23], v[132:133], v[170:171] neg_lo:[0,0,1] neg_hi:[0,0,1]
	v_pk_fma_f32 v[134:135], v[16:17], v[130:131], v[134:135]
	v_pk_fma_f32 v[132:133], v[14:15], v[132:133], v[166:167]
	v_cvt_pk_bf16_f32 v130, v170, v171
	v_cvt_pk_bf16_f32 v131, v168, v169
	v_cvt_pk_bf16_f32 v132, v132, v133
	v_cvt_pk_bf16_f32 v133, v134, v135
	global_store_dwordx4 v[152:153], v[130:133], off
	global_load_dwordx4 v[130:133], v[176:177], off
	s_nop 0
	global_load_dwordx4 v[134:137], v[136:137], off
	s_waitcnt vmcnt(0)
	v_pk_mul_f32 v[166:167], v[132:133], s[86:87] op_sel_hi:[1,0]
	v_pk_mul_f32 v[168:169], v[130:131], s[86:87] op_sel_hi:[1,0]
	v_pk_mul_f32 v[130:131], v[136:137], s[86:87] op_sel_hi:[1,0]
	v_pk_mul_f32 v[132:133], v[134:135], s[86:87] op_sel_hi:[1,0]
	v_pk_mul_f32 v[134:135], v[4:5], v[130:131]
	v_pk_mul_f32 v[136:137], v[2:3], v[132:133]
	v_pk_mul_f32 v[170:171], v[8:9], v[130:131]
	v_pk_mul_f32 v[172:173], v[6:7], v[132:133]
	v_pk_fma_f32 v[132:133], v[8:9], v[166:167], v[134:135] neg_lo:[0,0,1] neg_hi:[0,0,1]
	v_pk_fma_f32 v[130:131], v[6:7], v[168:169], v[136:137] neg_lo:[0,0,1] neg_hi:[0,0,1]
	v_pk_fma_f32 v[136:137], v[4:5], v[166:167], v[170:171]
	v_pk_fma_f32 v[134:135], v[2:3], v[168:169], v[172:173]

.LBB0_526:
	ds_read_b128 v[164:167], v154
	ds_read_b128 v[168:171], v154 offset:1024
	ds_read_b128 v[172:175], v154 offset:2048
	ds_read_b128 v[176:179], v154 offset:3072
	ds_read_b128 v[192:195], v154 offset:4096
	ds_read_b128 v[196:199], v154 offset:5120
	ds_read_b128 v[200:203], v154 offset:6144
	ds_read_b128 v[204:207], v154 offset:7168
	s_add_u32 s20, s18, 0xfff80080
	s_addc_u32 s21, s19, -1
	s_add_i32 s56, 0, 0x10000
	s_cmp_eq_u32 s55, 28
	s_cselect_b32 s23, s39, s21
	s_cselect_b32 s22, s51, s20
	s_cselect_b32 s21, s31, s54
	s_cselect_b32 s20, s52, s53
	v_lshl_add_u64 v[152:153], s[18:19], 0, v[140:141]
	s_add_i32 m0, s29, 0xc000
	s_nop 0
	global_load_lds_dwordx4 v[152:153], off
	v_lshl_add_u64 v[152:153], s[18:19], 0, v[142:143]
	s_add_i32 m0, s29, 0xe000
	s_nop 0
	global_load_lds_dwordx4 v[152:153], off
	s_waitcnt lgkmcnt(8)
	s_barrier
	s_waitcnt lgkmcnt(0)
	v_mfma_f32_16x16x32_bf16 v[126:129], v[144:147], v[164:167], v[126:129]
	v_mfma_f32_16x16x32_bf16 v[122:125], v[156:159], v[164:167], v[122:125]
	v_mfma_f32_16x16x32_bf16 v[118:121], v[144:147], v[172:175], v[118:121]
	v_mfma_f32_16x16x32_bf16 v[114:117], v[156:159], v[172:175], v[114:117]
	v_mfma_f32_16x16x32_bf16 v[102:105], v[144:147], v[192:195], v[102:105]
	v_mfma_f32_16x16x32_bf16 v[98:101], v[156:159], v[192:195], v[98:101]
	v_mfma_f32_16x16x32_bf16 v[86:89], v[144:147], v[200:203], v[86:89]
	v_mfma_f32_16x16x32_bf16 v[82:85], v[156:159], v[200:203], v[82:85]
	v_mfma_f32_16x16x32_bf16 v[126:129], v[148:151], v[168:171], v[126:129]
	v_mfma_f32_16x16x32_bf16 v[122:125], v[160:163], v[168:171], v[122:125]
	v_mfma_f32_16x16x32_bf16 v[118:121], v[148:151], v[176:179], v[118:121]
	v_mfma_f32_16x16x32_bf16 v[114:117], v[160:163], v[176:179], v[114:117]
	v_mfma_f32_16x16x32_bf16 v[102:105], v[148:151], v[196:199], v[102:105]
	v_mfma_f32_16x16x32_bf16 v[98:101], v[160:163], v[196:199], v[98:101]
	v_mfma_f32_16x16x32_bf16 v[86:89], v[148:151], v[204:207], v[86:89]
	v_mfma_f32_16x16x32_bf16 v[82:85], v[160:163], v[204:207], v[82:85]
	s_barrier
	s_add_i32 s58, 0, 0x14000
	v_add_u32_e32 v152, s58, v139
	s_add_i32 s56, s56, s28
	ds_read_b128 v[208:211], v152
	ds_read_b128 v[224:227], v152 offset:1024
	ds_read_b128 v[228:231], v152 offset:2048
	ds_read_b128 v[232:235], v152 offset:3072
	v_lshl_add_u64 v[152:153], s[20:21], 0, v[134:135]
	s_mov_b32 m0, s56
	v_lshl_add_u64 v[212:213], s[20:21], 0, v[130:131]
	global_load_lds_dwordx4 v[152:153], off
	s_add_i32 m0, s56, 0x2000
	s_nop 0
	global_load_lds_dwordx4 v[212:213], off
	s_mov_b32 m0, s29
	v_lshl_add_u64 v[236:237], s[22:23], 0, v[136:137]
	s_barrier
	s_waitcnt lgkmcnt(0)
	v_mfma_f32_16x16x32_bf16 v[110:113], v[208:211], v[164:167], v[110:113]
	v_mfma_f32_16x16x32_bf16 v[106:109], v[228:231], v[164:167], v[106:109]
	v_mfma_f32_16x16x32_bf16 v[94:97], v[208:211], v[172:175], v[94:97]
	v_mfma_f32_16x16x32_bf16 v[90:93], v[228:231], v[172:175], v[90:93]
	v_mfma_f32_16x16x32_bf16 v[78:81], v[208:211], v[192:195], v[78:81]
	v_mfma_f32_16x16x32_bf16 v[74:77], v[228:231], v[192:195], v[74:77]
	v_mfma_f32_16x16x32_bf16 v[70:73], v[208:211], v[200:203], v[70:73]
	v_mfma_f32_16x16x32_bf16 v[66:69], v[228:231], v[200:203], v[66:69]
	v_mfma_f32_16x16x32_bf16 v[110:113], v[224:227], v[168:171], v[110:113]
	v_mfma_f32_16x16x32_bf16 v[106:109], v[232:235], v[168:171], v[106:109]
	v_mfma_f32_16x16x32_bf16 v[94:97], v[224:227], v[176:179], v[94:97]
	v_mfma_f32_16x16x32_bf16 v[90:93], v[232:235], v[176:179], v[90:93]
	v_mfma_f32_16x16x32_bf16 v[78:81], v[224:227], v[196:199], v[78:81]
	v_mfma_f32_16x16x32_bf16 v[74:77], v[232:235], v[196:199], v[74:77]
	v_mfma_f32_16x16x32_bf16 v[70:73], v[224:227], v[204:207], v[70:73]
	v_mfma_f32_16x16x32_bf16 v[66:69], v[232:235], v[204:207], v[66:69]
	s_barrier
	ds_read_b128 v[164:167], v154 offset:16384
	ds_read_b128 v[168:171], v154 offset:17408
	ds_read_b128 v[172:175], v154 offset:18432
	ds_read_b128 v[176:179], v154 offset:19456
	ds_read_b128 v[192:195], v154 offset:20480
	ds_read_b128 v[196:199], v154 offset:21504
	ds_read_b128 v[200:203], v154 offset:22528
	ds_read_b128 v[204:207], v154 offset:23552
	global_load_lds_dwordx4 v[236:237], off
	v_lshl_add_u64 v[238:239], s[22:23], 0, v[132:133]
	s_mov_b32 m0, s44
	s_nop 0
	global_load_lds_dwordx4 v[238:239], off
	s_waitcnt vmcnt(10)
	s_barrier
	s_waitcnt lgkmcnt(0)
	v_mfma_f32_16x16x32_bf16 v[62:65], v[144:147], v[164:167], v[62:65]
	v_mfma_f32_16x16x32_bf16 v[58:61], v[156:159], v[164:167], v[58:61]
	v_mfma_f32_16x16x32_bf16 v[54:57], v[144:147], v[172:175], v[54:57]
	v_mfma_f32_16x16x32_bf16 v[50:53], v[156:159], v[172:175], v[50:53]
	v_mfma_f32_16x16x32_bf16 v[38:41], v[144:147], v[192:195], v[38:41]
	v_mfma_f32_16x16x32_bf16 v[34:37], v[156:159], v[192:195], v[34:37]
	v_mfma_f32_16x16x32_bf16 v[22:25], v[144:147], v[200:203], v[22:25]
	v_mfma_f32_16x16x32_bf16 v[18:21], v[156:159], v[200:203], v[18:21]
	v_mfma_f32_16x16x32_bf16 v[62:65], v[148:151], v[168:171], v[62:65]
	v_mfma_f32_16x16x32_bf16 v[58:61], v[160:163], v[168:171], v[58:61]
	v_mfma_f32_16x16x32_bf16 v[54:57], v[148:151], v[176:179], v[54:57]
	v_mfma_f32_16x16x32_bf16 v[50:53], v[160:163], v[176:179], v[50:53]
	v_mfma_f32_16x16x32_bf16 v[38:41], v[148:151], v[196:199], v[38:41]
	v_mfma_f32_16x16x32_bf16 v[34:37], v[160:163], v[196:199], v[34:37]
	v_mfma_f32_16x16x32_bf16 v[22:25], v[148:151], v[204:207], v[22:25]
	v_mfma_f32_16x16x32_bf16 v[18:21], v[160:163], v[204:207], v[18:21]
	s_barrier
	s_add_u32 s56, s20, 0x80000
	s_addc_u32 s57, s21, 0
	s_add_i32 s58, s58, s28
	v_lshl_add_u64 v[144:145], s[56:57], 0, v[134:135]
	s_mov_b32 m0, s58
	s_nop 0
	global_load_lds_dwordx4 v[144:145], off
	v_lshl_add_u64 v[144:145], s[56:57], 0, v[130:131]
	s_add_i32 m0, s58, 0x2000
	s_nop 0
	global_load_lds_dwordx4 v[144:145], off
	v_add_u32_e32 v155, 0x18000, v139
	ds_read_b128 v[144:147], v155
	ds_read_b128 v[148:151], v155 offset:1024
	ds_read_b128 v[156:159], v155 offset:2048
	ds_read_b128 v[160:163], v155 offset:3072
	s_add_i32 s56, 0, 0x18000
	s_waitcnt vmcnt(6)
	s_barrier
	v_mfma_f32_16x16x32_bf16 v[46:49], v[208:211], v[164:167], v[46:49]
	v_mfma_f32_16x16x32_bf16 v[42:45], v[228:231], v[164:167], v[42:45]
	v_mfma_f32_16x16x32_bf16 v[30:33], v[208:211], v[172:175], v[30:33]
	v_mfma_f32_16x16x32_bf16 v[26:29], v[228:231], v[172:175], v[26:29]
	v_mfma_f32_16x16x32_bf16 v[14:17], v[208:211], v[192:195], v[14:17]
	v_mfma_f32_16x16x32_bf16 v[10:13], v[228:231], v[192:195], v[10:13]
	v_mfma_f32_16x16x32_bf16 v[6:9], v[208:211], v[200:203], v[6:9]
	v_mfma_f32_16x16x32_bf16 v[2:5], v[228:231], v[200:203], v[2:5]
	v_mfma_f32_16x16x32_bf16 v[46:49], v[224:227], v[168:171], v[46:49]
	v_mfma_f32_16x16x32_bf16 v[42:45], v[232:235], v[168:171], v[42:45]
	v_mfma_f32_16x16x32_bf16 v[30:33], v[224:227], v[176:179], v[30:33]
	v_mfma_f32_16x16x32_bf16 v[26:29], v[232:235], v[176:179], v[26:29]
	v_mfma_f32_16x16x32_bf16 v[14:17], v[224:227], v[196:199], v[14:17]
	v_mfma_f32_16x16x32_bf16 v[10:13], v[232:235], v[196:199], v[10:13]
	v_mfma_f32_16x16x32_bf16 v[6:9], v[224:227], v[204:207], v[6:9]
	v_mfma_f32_16x16x32_bf16 v[2:5], v[232:235], v[204:207], v[2:5]
	s_barrier
	ds_read_b128 v[164:167], v154 offset:32768
	ds_read_b128 v[168:171], v154 offset:33792
	ds_read_b128 v[172:175], v154 offset:34816
	ds_read_b128 v[176:179], v154 offset:35840
	ds_read_b128 v[192:195], v154 offset:36864
	ds_read_b128 v[196:199], v154 offset:37888
	ds_read_b128 v[200:203], v154 offset:38912
	ds_read_b128 v[204:207], v154 offset:39936
	s_add_u32 s22, s22, 0x80000
	s_addc_u32 s23, s23, 0
	s_mov_b32 m0, s45
	v_lshl_add_u64 v[208:209], s[22:23], 0, v[136:137]
	global_load_lds_dwordx4 v[208:209], off
	v_lshl_add_u64 v[208:209], s[22:23], 0, v[132:133]
	s_mov_b32 m0, s46
	s_nop 0
	global_load_lds_dwordx4 v[208:209], off
	s_waitcnt lgkmcnt(8)
	s_barrier
	s_waitcnt lgkmcnt(0)
	v_mfma_f32_16x16x32_bf16 v[126:129], v[144:147], v[164:167], v[126:129]
	v_mfma_f32_16x16x32_bf16 v[122:125], v[156:159], v[164:167], v[122:125]
	v_mfma_f32_16x16x32_bf16 v[118:121], v[144:147], v[172:175], v[118:121]
	v_mfma_f32_16x16x32_bf16 v[114:117], v[156:159], v[172:175], v[114:117]
	v_mfma_f32_16x16x32_bf16 v[102:105], v[144:147], v[192:195], v[102:105]
	v_mfma_f32_16x16x32_bf16 v[98:101], v[156:159], v[192:195], v[98:101]
	v_mfma_f32_16x16x32_bf16 v[86:89], v[144:147], v[200:203], v[86:89]
	v_mfma_f32_16x16x32_bf16 v[82:85], v[156:159], v[200:203], v[82:85]
	v_mfma_f32_16x16x32_bf16 v[126:129], v[148:151], v[168:171], v[126:129]
	v_mfma_f32_16x16x32_bf16 v[122:125], v[160:163], v[168:171], v[122:125]
	v_mfma_f32_16x16x32_bf16 v[118:121], v[148:151], v[176:179], v[118:121]
	v_mfma_f32_16x16x32_bf16 v[114:117], v[160:163], v[176:179], v[114:117]
	v_mfma_f32_16x16x32_bf16 v[102:105], v[148:151], v[196:199], v[102:105]
	v_mfma_f32_16x16x32_bf16 v[98:101], v[160:163], v[196:199], v[98:101]
	v_mfma_f32_16x16x32_bf16 v[86:89], v[148:151], v[204:207], v[86:89]
	v_mfma_f32_16x16x32_bf16 v[82:85], v[160:163], v[204:207], v[82:85]
	s_barrier
	s_add_i32 s22, 0, 0x1c000
	s_add_i32 s23, s56, s28
	v_add_u32_e32 v155, s22, v139
	v_lshl_add_u64 v[152:153], v[152:153], 0, s[78:79]
	s_mov_b32 m0, s23
	ds_read_b128 v[208:211], v155
	ds_read_b128 v[224:227], v155 offset:1024
	ds_read_b128 v[228:231], v155 offset:2048
	ds_read_b128 v[232:235], v155 offset:3072
	global_load_lds_dwordx4 v[152:153], off
	v_lshl_add_u64 v[152:153], v[212:213], 0, s[78:79]
	s_add_i32 m0, s23, 0x2000
	s_nop 0
	global_load_lds_dwordx4 v[152:153], off
	s_mov_b32 m0, s47
	v_lshl_add_u64 v[152:153], v[236:237], 0, s[78:79]
	s_barrier
	s_waitcnt lgkmcnt(0)
	v_mfma_f32_16x16x32_bf16 v[110:113], v[208:211], v[164:167], v[110:113]
	v_mfma_f32_16x16x32_bf16 v[106:109], v[228:231], v[164:167], v[106:109]
	v_mfma_f32_16x16x32_bf16 v[94:97], v[208:211], v[172:175], v[94:97]
	v_mfma_f32_16x16x32_bf16 v[90:93], v[228:231], v[172:175], v[90:93]
	v_mfma_f32_16x16x32_bf16 v[78:81], v[208:211], v[192:195], v[78:81]
	v_mfma_f32_16x16x32_bf16 v[74:77], v[228:231], v[192:195], v[74:77]
	v_mfma_f32_16x16x32_bf16 v[70:73], v[208:211], v[200:203], v[70:73]
	v_mfma_f32_16x16x32_bf16 v[66:69], v[228:231], v[200:203], v[66:69]
	v_mfma_f32_16x16x32_bf16 v[110:113], v[224:227], v[168:171], v[110:113]
	v_mfma_f32_16x16x32_bf16 v[106:109], v[232:235], v[168:171], v[106:109]
	v_mfma_f32_16x16x32_bf16 v[94:97], v[224:227], v[176:179], v[94:97]
	v_mfma_f32_16x16x32_bf16 v[90:93], v[232:235], v[176:179], v[90:93]
	v_mfma_f32_16x16x32_bf16 v[78:81], v[224:227], v[196:199], v[78:81]
	v_mfma_f32_16x16x32_bf16 v[74:77], v[232:235], v[196:199], v[74:77]
	v_mfma_f32_16x16x32_bf16 v[70:73], v[224:227], v[204:207], v[70:73]
	v_mfma_f32_16x16x32_bf16 v[66:69], v[232:235], v[204:207], v[66:69]
	s_barrier
	ds_read_b128 v[164:167], v154 offset:49152
	ds_read_b128 v[168:171], v154 offset:50176
	ds_read_b128 v[172:175], v154 offset:51200
	ds_read_b128 v[176:179], v154 offset:52224
	ds_read_b128 v[192:195], v154 offset:53248
	ds_read_b128 v[196:199], v154 offset:54272
	ds_read_b128 v[200:203], v154 offset:55296
	ds_read_b128 v[204:207], v154 offset:56320
	global_load_lds_dwordx4 v[152:153], off
	v_lshl_add_u64 v[152:153], v[238:239], 0, s[78:79]
	s_mov_b32 m0, s48
	s_nop 0
	global_load_lds_dwordx4 v[152:153], off
	s_waitcnt vmcnt(10)
	s_barrier
	s_waitcnt lgkmcnt(0)
	v_mfma_f32_16x16x32_bf16 v[62:65], v[144:147], v[164:167], v[62:65]
	v_mfma_f32_16x16x32_bf16 v[58:61], v[156:159], v[164:167], v[58:61]
	v_mfma_f32_16x16x32_bf16 v[54:57], v[144:147], v[172:175], v[54:57]
	v_mfma_f32_16x16x32_bf16 v[50:53], v[156:159], v[172:175], v[50:53]
	v_mfma_f32_16x16x32_bf16 v[38:41], v[144:147], v[192:195], v[38:41]
	v_mfma_f32_16x16x32_bf16 v[34:37], v[156:159], v[192:195], v[34:37]
	v_mfma_f32_16x16x32_bf16 v[22:25], v[144:147], v[200:203], v[22:25]
	v_mfma_f32_16x16x32_bf16 v[18:21], v[156:159], v[200:203], v[18:21]
	v_mfma_f32_16x16x32_bf16 v[62:65], v[148:151], v[168:171], v[62:65]
	v_mfma_f32_16x16x32_bf16 v[58:61], v[160:163], v[168:171], v[58:61]
	v_mfma_f32_16x16x32_bf16 v[54:57], v[148:151], v[176:179], v[54:57]
	v_mfma_f32_16x16x32_bf16 v[50:53], v[160:163], v[176:179], v[50:53]
	v_mfma_f32_16x16x32_bf16 v[38:41], v[148:151], v[196:199], v[38:41]
	v_mfma_f32_16x16x32_bf16 v[34:37], v[160:163], v[196:199], v[34:37]
	v_mfma_f32_16x16x32_bf16 v[22:25], v[148:151], v[204:207], v[22:25]
	v_mfma_f32_16x16x32_bf16 v[18:21], v[160:163], v[204:207], v[18:21]
	s_barrier
	s_add_u32 s20, s20, 0x80080
	s_addc_u32 s21, s21, 0
	s_add_i32 s22, s22, s28
	v_lshl_add_u64 v[144:145], s[20:21], 0, v[134:135]
	s_mov_b32 m0, s22
	s_nop 0
	global_load_lds_dwordx4 v[144:145], off
	v_lshl_add_u64 v[144:145], s[20:21], 0, v[130:131]
	s_add_i32 m0, s22, 0x2000
	s_nop 0
	global_load_lds_dwordx4 v[144:145], off
	v_add_u32_e32 v152, 0x10000, v139
	ds_read_b128 v[144:147], v152
	ds_read_b128 v[148:151], v152 offset:1024
	ds_read_b128 v[156:159], v152 offset:2048
	ds_read_b128 v[160:163], v152 offset:3072
	s_add_i32 s55, s55, 2
	s_add_u32 s18, s18, 0x100
	s_addc_u32 s19, s19, 0
	s_add_u32 s53, s53, 0x100
	s_addc_u32 s54, s54, 0
	s_cmp_gt_u32 s55, 29
	s_waitcnt vmcnt(6)
	s_barrier
	v_mfma_f32_16x16x32_bf16 v[46:49], v[208:211], v[164:167], v[46:49]
	v_mfma_f32_16x16x32_bf16 v[42:45], v[228:231], v[164:167], v[42:45]
	v_mfma_f32_16x16x32_bf16 v[30:33], v[208:211], v[172:175], v[30:33]
	v_mfma_f32_16x16x32_bf16 v[26:29], v[228:231], v[172:175], v[26:29]
	v_mfma_f32_16x16x32_bf16 v[14:17], v[208:211], v[192:195], v[14:17]
	v_mfma_f32_16x16x32_bf16 v[10:13], v[228:231], v[192:195], v[10:13]
	v_mfma_f32_16x16x32_bf16 v[6:9], v[208:211], v[200:203], v[6:9]
	v_mfma_f32_16x16x32_bf16 v[2:5], v[228:231], v[200:203], v[2:5]
	v_mfma_f32_16x16x32_bf16 v[46:49], v[224:227], v[168:171], v[46:49]
	v_mfma_f32_16x16x32_bf16 v[42:45], v[232:235], v[168:171], v[42:45]
	v_mfma_f32_16x16x32_bf16 v[30:33], v[224:227], v[176:179], v[30:33]
	v_mfma_f32_16x16x32_bf16 v[26:29], v[232:235], v[176:179], v[26:29]
	v_mfma_f32_16x16x32_bf16 v[14:17], v[224:227], v[196:199], v[14:17]
	v_mfma_f32_16x16x32_bf16 v[10:13], v[232:235], v[196:199], v[10:13]
	v_mfma_f32_16x16x32_bf16 v[6:9], v[224:227], v[204:207], v[6:9]
	v_mfma_f32_16x16x32_bf16 v[2:5], v[232:235], v[204:207], v[2:5]
	s_barrier
	s_cbranch_scc0 .LBB0_526
	s_waitcnt lgkmcnt(0)
	v_lshl_add_u32 v152, s36, 8, v1
	v_or_b32_e32 v150, 16, v152
	v_or_b32_e32 v148, 32, v152
	v_or_b32_e32 v146, 48, v152
	s_mov_b64 s[18:19], -1
	s_cmp_lt_i32 s50, 8
	v_ashrrev_i32_e32 v153, 31, v152
	v_lshlrev_b32_e32 v144, 1, v138
	v_ashrrev_i32_e32 v151, 31, v150
	v_ashrrev_i32_e32 v149, 31, v148
	v_ashrrev_i32_e32 v147, 31, v146
	s_cbranch_scc1 .LBB0_529
	s_lshl_b32 s18, s50, 7
	s_add_i32 s36, s18, 0xfffffc00
	v_lshlrev_b64 v[156:157], 12, v[152:153]
	v_lshl_add_u64 v[156:157], s[72:73], 0, v[156:157]
	s_lshl_b64 s[18:19], s[36:37], 1
	v_lshl_add_u64 v[156:157], v[156:157], 0, s[18:19]
	v_mov_b32_e32 v145, v0
	v_lshl_add_u64 v[160:161], v[156:157], 0, v[144:145]
	v_pk_mul_f32 v[158:159], v[128:129], v[112:113]
	v_pk_mul_f32 v[156:157], v[126:127], v[110:111]
	v_pk_mul_f32 v[162:163], v[124:125], v[108:109]
	v_pk_mul_f32 v[164:165], v[122:123], v[106:107]
	v_cvt_pk_bf16_f32 v156, v156, v157
	v_cvt_pk_bf16_f32 v157, v158, v159
	v_cvt_pk_bf16_f32 v158, v164, v165
	v_cvt_pk_bf16_f32 v159, v162, v163
	global_store_dwordx4 v[160:161], v[156:159], off
	v_pk_mul_f32 v[164:165], v[116:117], v[92:93]
	v_pk_mul_f32 v[166:167], v[114:115], v[90:91]
	v_lshlrev_b64 v[156:157], 12, v[150:151]
	v_lshl_add_u64 v[156:157], s[72:73], 0, v[156:157]
	v_lshl_add_u64 v[156:157], v[156:157], 0, s[18:19]
	v_lshl_add_u64 v[162:163], v[156:157], 0, v[144:145]
	v_pk_mul_f32 v[158:159], v[120:121], v[96:97]
	v_pk_mul_f32 v[156:157], v[118:119], v[94:95]
	s_nop 0
	v_cvt_pk_bf16_f32 v156, v156, v157
	v_cvt_pk_bf16_f32 v157, v158, v159
	v_cvt_pk_bf16_f32 v158, v166, v167
	v_cvt_pk_bf16_f32 v159, v164, v165
	global_store_dwordx4 v[162:163], v[156:159], off
	v_pk_mul_f32 v[164:165], v[100:101], v[76:77]
	v_pk_mul_f32 v[166:167], v[98:99], v[74:75]
	v_lshlrev_b64 v[156:157], 12, v[148:149]
	v_lshl_add_u64 v[156:157], s[72:73], 0, v[156:157]
	v_lshl_add_u64 v[156:157], v[156:157], 0, s[18:19]
	v_lshl_add_u64 v[162:163], v[156:157], 0, v[144:145]
	v_pk_mul_f32 v[158:159], v[104:105], v[80:81]
	v_pk_mul_f32 v[156:157], v[102:103], v[78:79]
	s_nop 0
	v_cvt_pk_bf16_f32 v156, v156, v157
	v_cvt_pk_bf16_f32 v157, v158, v159
	v_cvt_pk_bf16_f32 v158, v166, v167
	v_cvt_pk_bf16_f32 v159, v164, v165
	global_store_dwordx4 v[162:163], v[156:159], off
	v_pk_mul_f32 v[164:165], v[84:85], v[68:69]
	v_pk_mul_f32 v[166:167], v[82:83], v[66:67]
	v_lshlrev_b64 v[156:157], 12, v[146:147]
	v_lshl_add_u64 v[156:157], s[72:73], 0, v[156:157]
	v_lshl_add_u64 v[156:157], v[156:157], 0, s[18:19]
	v_lshl_add_u64 v[162:163], v[156:157], 0, v[144:145]
	v_pk_mul_f32 v[158:159], v[88:89], v[72:73]
	v_pk_mul_f32 v[156:157], v[86:87], v[70:71]
	s_mov_b32 s18, 0x80000
	v_cvt_pk_bf16_f32 v156, v156, v157
	v_cvt_pk_bf16_f32 v157, v158, v159
	v_cvt_pk_bf16_f32 v158, v166, v167
	v_cvt_pk_bf16_f32 v159, v164, v165
	global_store_dwordx4 v[162:163], v[156:159], off
	v_pk_mul_f32 v[162:163], v[60:61], v[44:45]
	v_pk_mul_f32 v[164:165], v[58:59], v[42:43]
	v_pk_mul_f32 v[158:159], v[64:65], v[48:49]
	v_pk_mul_f32 v[156:157], v[62:63], v[46:47]
	s_nop 0
	v_cvt_pk_bf16_f32 v156, v156, v157
	v_cvt_pk_bf16_f32 v157, v158, v159
	v_cvt_pk_bf16_f32 v159, v162, v163
	v_add_co_u32_e32 v162, vcc, s18, v160
	v_cvt_pk_bf16_f32 v158, v164, v165
	s_nop 0
	v_addc_co_u32_e32 v163, vcc, 0, v161, vcc
	global_store_dwordx4 v[162:163], v[156:159], off
	v_pk_mul_f32 v[162:163], v[52:53], v[28:29]
	s_mov_b32 s18, 0x90000
	v_pk_mul_f32 v[158:159], v[56:57], v[32:33]
	v_pk_mul_f32 v[156:157], v[54:55], v[30:31]
	v_pk_mul_f32 v[164:165], v[50:51], v[26:27]
	v_cvt_pk_bf16_f32 v156, v156, v157
	v_cvt_pk_bf16_f32 v157, v158, v159
	v_cvt_pk_bf16_f32 v159, v162, v163
	v_add_co_u32_e32 v162, vcc, s18, v160
	v_cvt_pk_bf16_f32 v158, v164, v165
	s_nop 0
	v_addc_co_u32_e32 v163, vcc, 0, v161, vcc
	global_store_dwordx4 v[162:163], v[156:159], off
	v_pk_mul_f32 v[162:163], v[36:37], v[12:13]
	s_mov_b32 s18, 0xa0000
	v_pk_mul_f32 v[158:159], v[40:41], v[16:17]
	v_pk_mul_f32 v[156:157], v[38:39], v[14:15]
	v_pk_mul_f32 v[164:165], v[34:35], v[10:11]
	v_cvt_pk_bf16_f32 v156, v156, v157
	v_cvt_pk_bf16_f32 v157, v158, v159
	v_cvt_pk_bf16_f32 v159, v162, v163
	v_add_co_u32_e32 v162, vcc, s18, v160
	v_cvt_pk_bf16_f32 v158, v164, v165
	s_nop 0
	v_addc_co_u32_e32 v163, vcc, 0, v161, vcc
	global_store_dwordx4 v[162:163], v[156:159], off
	v_pk_mul_f32 v[162:163], v[20:21], v[4:5]
	v_pk_mul_f32 v[164:165], v[18:19], v[2:3]
	v_pk_mul_f32 v[158:159], v[24:25], v[8:9]
	v_pk_mul_f32 v[156:157], v[22:23], v[6:7]
	v_add_co_u32_e32 v160, vcc, 0xb0000, v160
	v_cvt_pk_bf16_f32 v156, v156, v157
	v_cvt_pk_bf16_f32 v157, v158, v159
	v_cvt_pk_bf16_f32 v158, v164, v165
	v_cvt_pk_bf16_f32 v159, v162, v163
	v_addc_co_u32_e32 v161, vcc, 0, v161, vcc
	s_mov_b64 s[18:19], 0
	global_store_dwordx4 v[160:161], v[156:159], off

.LBB0_649:
	ds_read_b128 v[170:173], v148
	ds_read_b128 v[174:177], v148 offset:1024
	ds_read_b128 v[192:195], v148 offset:2048
	ds_read_b128 v[196:199], v148 offset:3072
	ds_read_b128 v[200:203], v148 offset:4096
	ds_read_b128 v[204:207], v148 offset:5120
	ds_read_b128 v[208:211], v148 offset:6144
	ds_read_b128 v[224:227], v148 offset:7168
	s_add_u32 s18, s38, vcc_lo
	s_addc_u32 s19, s39, vcc_hi
	s_add_u32 s18, s18, 0x100
	s_addc_u32 s19, s19, 0
	s_add_u32 s57, s50, vcc_lo
	s_addc_u32 s58, s51, vcc_hi
	s_add_i32 s59, 0, 0x10000
	s_cmpk_eq_i32 vcc_lo, 0xf00
	s_cselect_b32 s23, s52, s19
	s_cselect_b32 s22, s53, s18
	s_cselect_b32 s19, s54, s58
	s_cselect_b32 s18, s55, s57
	v_lshl_add_u64 v[162:163], v[142:143], 0, vcc
	s_add_i32 m0, s28, 0xc000
	s_nop 0
	global_load_lds_dwordx4 v[162:163], off
	v_lshl_add_u64 v[162:163], v[144:145], 0, vcc
	s_add_i32 m0, s28, 0xe000
	s_nop 0
	global_load_lds_dwordx4 v[162:163], off
	s_waitcnt lgkmcnt(8)
	s_barrier
	s_waitcnt lgkmcnt(0)
	v_mfma_f32_16x16x32_bf16 v[90:93], v[150:153], v[170:173], v[90:93]
	v_mfma_f32_16x16x32_bf16 v[94:97], v[158:161], v[170:173], v[94:97]
	v_mfma_f32_16x16x32_bf16 v[102:105], v[150:153], v[192:195], v[102:105]
	v_mfma_f32_16x16x32_bf16 v[106:109], v[158:161], v[192:195], v[106:109]
	v_mfma_f32_16x16x32_bf16 v[114:117], v[150:153], v[200:203], v[114:117]
	v_mfma_f32_16x16x32_bf16 v[118:121], v[158:161], v[200:203], v[118:121]
	v_mfma_f32_16x16x32_bf16 v[122:125], v[150:153], v[208:211], v[122:125]
	v_mfma_f32_16x16x32_bf16 v[126:129], v[158:161], v[208:211], v[126:129]
	v_mfma_f32_16x16x32_bf16 v[90:93], v[154:157], v[174:177], v[90:93]
	v_mfma_f32_16x16x32_bf16 v[94:97], v[166:169], v[174:177], v[94:97]
	v_mfma_f32_16x16x32_bf16 v[102:105], v[154:157], v[196:199], v[102:105]
	v_mfma_f32_16x16x32_bf16 v[106:109], v[166:169], v[196:199], v[106:109]
	v_mfma_f32_16x16x32_bf16 v[114:117], v[154:157], v[204:207], v[114:117]
	v_mfma_f32_16x16x32_bf16 v[118:121], v[166:169], v[204:207], v[118:121]
	v_mfma_f32_16x16x32_bf16 v[122:125], v[154:157], v[224:227], v[122:125]
	v_mfma_f32_16x16x32_bf16 v[126:129], v[166:169], v[224:227], v[126:129]
	s_barrier
	s_add_i32 s57, 0, 0x14000
	s_add_i32 s58, s59, s85
	v_add_u32_e32 v149, s57, v147
	v_lshl_add_u64 v[162:163], s[18:19], 0, v[134:135]
	s_mov_b32 m0, s58
	ds_read_b128 v[228:231], v149
	ds_read_b128 v[232:235], v149 offset:1024
	ds_read_b128 v[236:239], v149 offset:2048
	ds_read_b128 v[240:243], v149 offset:3072
	global_load_lds_dwordx4 v[162:163], off
	v_lshl_add_u64 v[178:179], s[18:19], 0, v[130:131]
	s_add_i32 m0, s58, 0x2000
	s_nop 0
	global_load_lds_dwordx4 v[178:179], off
	s_mov_b32 m0, s28
	v_lshl_add_u64 v[212:213], s[22:23], 0, v[136:137]
	s_barrier
	s_waitcnt lgkmcnt(0)
	v_mfma_f32_16x16x32_bf16 v[10:13], v[228:231], v[170:173], v[10:13]
	v_mfma_f32_16x16x32_bf16 v[14:17], v[236:239], v[170:173], v[14:17]
	v_mfma_f32_16x16x32_bf16 v[26:29], v[228:231], v[192:195], v[26:29]
	v_mfma_f32_16x16x32_bf16 v[38:41], v[236:239], v[192:195], v[38:41]
	v_mfma_f32_16x16x32_bf16 v[58:61], v[228:231], v[200:203], v[58:61]
	v_mfma_f32_16x16x32_bf16 v[62:65], v[236:239], v[200:203], v[62:65]
	v_mfma_f32_16x16x32_bf16 v[74:77], v[228:231], v[208:211], v[74:77]
	v_mfma_f32_16x16x32_bf16 v[78:81], v[236:239], v[208:211], v[78:81]
	v_mfma_f32_16x16x32_bf16 v[10:13], v[232:235], v[174:177], v[10:13]
	v_mfma_f32_16x16x32_bf16 v[14:17], v[240:243], v[174:177], v[14:17]
	v_mfma_f32_16x16x32_bf16 v[26:29], v[232:235], v[196:199], v[26:29]
	v_mfma_f32_16x16x32_bf16 v[38:41], v[240:243], v[196:199], v[38:41]
	v_mfma_f32_16x16x32_bf16 v[58:61], v[232:235], v[204:207], v[58:61]
	v_mfma_f32_16x16x32_bf16 v[62:65], v[240:243], v[204:207], v[62:65]
	v_mfma_f32_16x16x32_bf16 v[74:77], v[232:235], v[224:227], v[74:77]
	v_mfma_f32_16x16x32_bf16 v[78:81], v[240:243], v[224:227], v[78:81]
	s_barrier
	ds_read_b128 v[170:173], v148 offset:16384
	ds_read_b128 v[174:177], v148 offset:17408
	ds_read_b128 v[192:195], v148 offset:18432
	ds_read_b128 v[196:199], v148 offset:19456
	ds_read_b128 v[200:203], v148 offset:20480
	ds_read_b128 v[204:207], v148 offset:21504
	ds_read_b128 v[208:211], v148 offset:22528
	ds_read_b128 v[224:227], v148 offset:23552
	global_load_lds_dwordx4 v[212:213], off
	v_lshl_add_u64 v[244:245], s[22:23], 0, v[132:133]
	s_mov_b32 m0, s29
	s_nop 0
	global_load_lds_dwordx4 v[244:245], off
	s_waitcnt vmcnt(10)
	s_barrier
	s_waitcnt lgkmcnt(0)
	v_mfma_f32_16x16x32_bf16 v[110:113], v[150:153], v[170:173], v[110:113]
	v_mfma_f32_16x16x32_bf16 v[98:101], v[158:161], v[170:173], v[98:101]
	v_mfma_f32_16x16x32_bf16 v[82:85], v[150:153], v[192:195], v[82:85]
	v_mfma_f32_16x16x32_bf16 v[66:69], v[158:161], v[192:195], v[66:69]
	v_mfma_f32_16x16x32_bf16 v[50:53], v[150:153], v[200:203], v[50:53]
	v_mfma_f32_16x16x32_bf16 v[42:45], v[158:161], v[200:203], v[42:45]
	v_mfma_f32_16x16x32_bf16 v[30:33], v[150:153], v[208:211], v[30:33]
	v_mfma_f32_16x16x32_bf16 v[18:21], v[158:161], v[208:211], v[18:21]
	v_mfma_f32_16x16x32_bf16 v[110:113], v[154:157], v[174:177], v[110:113]
	v_mfma_f32_16x16x32_bf16 v[98:101], v[166:169], v[174:177], v[98:101]
	v_mfma_f32_16x16x32_bf16 v[82:85], v[154:157], v[196:199], v[82:85]
	v_mfma_f32_16x16x32_bf16 v[66:69], v[166:169], v[196:199], v[66:69]
	v_mfma_f32_16x16x32_bf16 v[50:53], v[154:157], v[204:207], v[50:53]
	v_mfma_f32_16x16x32_bf16 v[42:45], v[166:169], v[204:207], v[42:45]
	v_mfma_f32_16x16x32_bf16 v[30:33], v[154:157], v[224:227], v[30:33]
	v_mfma_f32_16x16x32_bf16 v[18:21], v[166:169], v[224:227], v[18:21]
	s_barrier
	s_add_u32 s58, s18, 0x80000
	s_addc_u32 s59, s19, 0
	s_add_i32 s57, s57, s85
	v_lshl_add_u64 v[150:151], s[58:59], 0, v[134:135]
	s_mov_b32 m0, s57
	s_nop 0
	global_load_lds_dwordx4 v[150:151], off
	v_lshl_add_u64 v[150:151], s[58:59], 0, v[130:131]
	s_add_i32 m0, s57, 0x2000
	s_nop 0
	global_load_lds_dwordx4 v[150:151], off
	v_add_u32_e32 v149, 0x18000, v147
	ds_read_b128 v[150:153], v149
	ds_read_b128 v[154:157], v149 offset:1024
	ds_read_b128 v[158:161], v149 offset:2048
	ds_read_b128 v[166:169], v149 offset:3072
	s_add_i32 s57, 0, 0x18000
	s_waitcnt vmcnt(6)
	s_barrier
	v_mfma_f32_16x16x32_bf16 v[86:89], v[228:231], v[170:173], v[86:89]
	v_mfma_f32_16x16x32_bf16 v[70:73], v[236:239], v[170:173], v[70:73]
	v_mfma_f32_16x16x32_bf16 v[54:57], v[228:231], v[192:195], v[54:57]
	v_mfma_f32_16x16x32_bf16 v[46:49], v[236:239], v[192:195], v[46:49]
	v_mfma_f32_16x16x32_bf16 v[34:37], v[228:231], v[200:203], v[34:37]
	v_mfma_f32_16x16x32_bf16 v[22:25], v[236:239], v[200:203], v[22:25]
	v_mfma_f32_16x16x32_bf16 v[6:9], v[228:231], v[208:211], v[6:9]
	v_mfma_f32_16x16x32_bf16 v[2:5], v[236:239], v[208:211], v[2:5]
	v_mfma_f32_16x16x32_bf16 v[86:89], v[232:235], v[174:177], v[86:89]
	v_mfma_f32_16x16x32_bf16 v[70:73], v[240:243], v[174:177], v[70:73]
	v_mfma_f32_16x16x32_bf16 v[54:57], v[232:235], v[196:199], v[54:57]
	v_mfma_f32_16x16x32_bf16 v[46:49], v[240:243], v[196:199], v[46:49]
	v_mfma_f32_16x16x32_bf16 v[34:37], v[232:235], v[204:207], v[34:37]
	v_mfma_f32_16x16x32_bf16 v[22:25], v[240:243], v[204:207], v[22:25]
	v_mfma_f32_16x16x32_bf16 v[6:9], v[232:235], v[224:227], v[6:9]
	v_mfma_f32_16x16x32_bf16 v[2:5], v[240:243], v[224:227], v[2:5]
	s_barrier
	ds_read_b128 v[170:173], v148 offset:32768
	ds_read_b128 v[174:177], v148 offset:33792
	ds_read_b128 v[192:195], v148 offset:34816
	ds_read_b128 v[196:199], v148 offset:35840
	ds_read_b128 v[200:203], v148 offset:36864
	ds_read_b128 v[204:207], v148 offset:37888
	ds_read_b128 v[208:211], v148 offset:38912
	ds_read_b128 v[224:227], v148 offset:39936
	s_add_u32 s22, s22, 0x80000
	s_addc_u32 s23, s23, 0
	s_mov_b32 m0, s97
	v_lshl_add_u64 v[228:229], s[22:23], 0, v[136:137]
	global_load_lds_dwordx4 v[228:229], off
	v_lshl_add_u64 v[228:229], s[22:23], 0, v[132:133]
	s_mov_b32 m0, s44
	s_nop 0
	global_load_lds_dwordx4 v[228:229], off
	s_waitcnt lgkmcnt(8)
	s_barrier
	s_waitcnt lgkmcnt(0)
	v_mfma_f32_16x16x32_bf16 v[90:93], v[150:153], v[170:173], v[90:93]
	v_mfma_f32_16x16x32_bf16 v[94:97], v[158:161], v[170:173], v[94:97]
	v_mfma_f32_16x16x32_bf16 v[102:105], v[150:153], v[192:195], v[102:105]
	v_mfma_f32_16x16x32_bf16 v[106:109], v[158:161], v[192:195], v[106:109]
	v_mfma_f32_16x16x32_bf16 v[114:117], v[150:153], v[200:203], v[114:117]
	v_mfma_f32_16x16x32_bf16 v[118:121], v[158:161], v[200:203], v[118:121]
	v_mfma_f32_16x16x32_bf16 v[122:125], v[150:153], v[208:211], v[122:125]
	v_mfma_f32_16x16x32_bf16 v[126:129], v[158:161], v[208:211], v[126:129]
	v_mfma_f32_16x16x32_bf16 v[90:93], v[154:157], v[174:177], v[90:93]
	v_mfma_f32_16x16x32_bf16 v[94:97], v[166:169], v[174:177], v[94:97]
	v_mfma_f32_16x16x32_bf16 v[102:105], v[154:157], v[196:199], v[102:105]
	v_mfma_f32_16x16x32_bf16 v[106:109], v[166:169], v[196:199], v[106:109]
	v_mfma_f32_16x16x32_bf16 v[114:117], v[154:157], v[204:207], v[114:117]
	v_mfma_f32_16x16x32_bf16 v[118:121], v[166:169], v[204:207], v[118:121]
	v_mfma_f32_16x16x32_bf16 v[122:125], v[154:157], v[224:227], v[122:125]
	v_mfma_f32_16x16x32_bf16 v[126:129], v[166:169], v[224:227], v[126:129]
	s_barrier
	s_add_i32 s22, 0, 0x1c000
	s_add_i32 s23, s57, s85
	v_add_u32_e32 v149, s22, v147
	v_lshl_add_u64 v[162:163], v[162:163], 0, s[78:79]
	s_mov_b32 m0, s23
	ds_read_b128 v[228:231], v149
	ds_read_b128 v[232:235], v149 offset:1024
	ds_read_b128 v[236:239], v149 offset:2048
	ds_read_b128 v[240:243], v149 offset:3072
	global_load_lds_dwordx4 v[162:163], off
	v_lshl_add_u64 v[162:163], v[178:179], 0, s[78:79]
	s_add_i32 m0, s23, 0x2000
	s_nop 0
	global_load_lds_dwordx4 v[162:163], off
	s_mov_b32 m0, s46
	v_lshl_add_u64 v[162:163], v[212:213], 0, s[78:79]
	s_barrier
	s_waitcnt lgkmcnt(0)
	v_mfma_f32_16x16x32_bf16 v[10:13], v[228:231], v[170:173], v[10:13]
	v_mfma_f32_16x16x32_bf16 v[14:17], v[236:239], v[170:173], v[14:17]
	v_mfma_f32_16x16x32_bf16 v[26:29], v[228:231], v[192:195], v[26:29]
	v_mfma_f32_16x16x32_bf16 v[38:41], v[236:239], v[192:195], v[38:41]
	v_mfma_f32_16x16x32_bf16 v[58:61], v[228:231], v[200:203], v[58:61]
	v_mfma_f32_16x16x32_bf16 v[62:65], v[236:239], v[200:203], v[62:65]
	v_mfma_f32_16x16x32_bf16 v[74:77], v[228:231], v[208:211], v[74:77]
	v_mfma_f32_16x16x32_bf16 v[78:81], v[236:239], v[208:211], v[78:81]
	v_mfma_f32_16x16x32_bf16 v[10:13], v[232:235], v[174:177], v[10:13]
	v_mfma_f32_16x16x32_bf16 v[14:17], v[240:243], v[174:177], v[14:17]
	v_mfma_f32_16x16x32_bf16 v[26:29], v[232:235], v[196:199], v[26:29]
	v_mfma_f32_16x16x32_bf16 v[38:41], v[240:243], v[196:199], v[38:41]
	v_mfma_f32_16x16x32_bf16 v[58:61], v[232:235], v[204:207], v[58:61]
	v_mfma_f32_16x16x32_bf16 v[62:65], v[240:243], v[204:207], v[62:65]
	v_mfma_f32_16x16x32_bf16 v[74:77], v[232:235], v[224:227], v[74:77]
	v_mfma_f32_16x16x32_bf16 v[78:81], v[240:243], v[224:227], v[78:81]
	s_barrier
	ds_read_b128 v[170:173], v148 offset:49152
	ds_read_b128 v[174:177], v148 offset:50176
	ds_read_b128 v[192:195], v148 offset:51200
	ds_read_b128 v[196:199], v148 offset:52224
	ds_read_b128 v[200:203], v148 offset:53248
	ds_read_b128 v[204:207], v148 offset:54272
	ds_read_b128 v[208:211], v148 offset:55296
	ds_read_b128 v[224:227], v148 offset:56320
	global_load_lds_dwordx4 v[162:163], off
	v_lshl_add_u64 v[162:163], v[244:245], 0, s[78:79]
	s_mov_b32 m0, s47
	s_nop 0
	global_load_lds_dwordx4 v[162:163], off
	s_waitcnt vmcnt(10)
	s_barrier
	s_waitcnt lgkmcnt(0)
	v_mfma_f32_16x16x32_bf16 v[110:113], v[150:153], v[170:173], v[110:113]
	v_mfma_f32_16x16x32_bf16 v[98:101], v[158:161], v[170:173], v[98:101]
	v_mfma_f32_16x16x32_bf16 v[82:85], v[150:153], v[192:195], v[82:85]
	v_mfma_f32_16x16x32_bf16 v[66:69], v[158:161], v[192:195], v[66:69]
	v_mfma_f32_16x16x32_bf16 v[50:53], v[150:153], v[200:203], v[50:53]
	v_mfma_f32_16x16x32_bf16 v[42:45], v[158:161], v[200:203], v[42:45]
	v_mfma_f32_16x16x32_bf16 v[30:33], v[150:153], v[208:211], v[30:33]
	v_mfma_f32_16x16x32_bf16 v[18:21], v[158:161], v[208:211], v[18:21]
	v_mfma_f32_16x16x32_bf16 v[110:113], v[154:157], v[174:177], v[110:113]
	v_mfma_f32_16x16x32_bf16 v[98:101], v[166:169], v[174:177], v[98:101]
	v_mfma_f32_16x16x32_bf16 v[82:85], v[154:157], v[196:199], v[82:85]
	v_mfma_f32_16x16x32_bf16 v[66:69], v[166:169], v[196:199], v[66:69]
	v_mfma_f32_16x16x32_bf16 v[50:53], v[154:157], v[204:207], v[50:53]
	v_mfma_f32_16x16x32_bf16 v[42:45], v[166:169], v[204:207], v[42:45]
	v_mfma_f32_16x16x32_bf16 v[30:33], v[154:157], v[224:227], v[30:33]
	v_mfma_f32_16x16x32_bf16 v[18:21], v[166:169], v[224:227], v[18:21]
	s_barrier
	s_add_u32 s18, s18, 0x80080
	s_addc_u32 s19, s19, 0
	s_add_i32 s22, s22, s85
	v_lshl_add_u64 v[150:151], s[18:19], 0, v[134:135]
	s_mov_b32 m0, s22
	s_nop 0
	global_load_lds_dwordx4 v[150:151], off
	v_lshl_add_u64 v[150:151], s[18:19], 0, v[130:131]
	s_add_i32 m0, s22, 0x2000
	s_nop 0
	global_load_lds_dwordx4 v[150:151], off
	v_add_u32_e32 v149, 0x10000, v147
	ds_read_b128 v[150:153], v149
	ds_read_b128 v[154:157], v149 offset:1024
	ds_read_b128 v[158:161], v149 offset:2048
	ds_read_b128 v[166:169], v149 offset:3072
	s_add_i32 s56, s56, 2
	s_add_u32 vcc_lo, vcc_lo, 0x100
	s_addc_u32 vcc_hi, vcc_hi, 0
	s_cmp_gt_u32 s56, 29
	s_waitcnt vmcnt(6)
	s_barrier
	v_mfma_f32_16x16x32_bf16 v[86:89], v[228:231], v[170:173], v[86:89]
	v_mfma_f32_16x16x32_bf16 v[70:73], v[236:239], v[170:173], v[70:73]
	v_mfma_f32_16x16x32_bf16 v[54:57], v[228:231], v[192:195], v[54:57]
	v_mfma_f32_16x16x32_bf16 v[46:49], v[236:239], v[192:195], v[46:49]
	v_mfma_f32_16x16x32_bf16 v[34:37], v[228:231], v[200:203], v[34:37]
	v_mfma_f32_16x16x32_bf16 v[22:25], v[236:239], v[200:203], v[22:25]
	v_mfma_f32_16x16x32_bf16 v[6:9], v[228:231], v[208:211], v[6:9]
	v_mfma_f32_16x16x32_bf16 v[2:5], v[236:239], v[208:211], v[2:5]
	v_mfma_f32_16x16x32_bf16 v[86:89], v[232:235], v[174:177], v[86:89]
	v_mfma_f32_16x16x32_bf16 v[70:73], v[240:243], v[174:177], v[70:73]
	v_mfma_f32_16x16x32_bf16 v[54:57], v[232:235], v[196:199], v[54:57]
	v_mfma_f32_16x16x32_bf16 v[46:49], v[240:243], v[196:199], v[46:49]
	v_mfma_f32_16x16x32_bf16 v[34:37], v[232:235], v[204:207], v[34:37]
	v_mfma_f32_16x16x32_bf16 v[22:25], v[240:243], v[204:207], v[22:25]
	v_mfma_f32_16x16x32_bf16 v[6:9], v[232:235], v[224:227], v[6:9]
	v_mfma_f32_16x16x32_bf16 v[2:5], v[240:243], v[224:227], v[2:5]
	s_barrier
	s_cbranch_scc0 .LBB0_649
	s_waitcnt lgkmcnt(0)
	s_add_u32 s18, s50, 0xffffff00
	s_addc_u32 s19, s51, -1
	s_andn2_b64 vcc, exec, s[42:43]
	s_cbranch_vccnz .LBB0_652
	v_mov_b32_e32 v2, 0
	s_mov_b32 s84, s80
	s_mov_b32 s25, s82
	s_mov_b64 s[38:39], s[20:21]
	s_mov_b32 s48, s49
	v_mov_b32_e32 v3, v2
	v_mov_b32_e32 v4, v2
	v_mov_b32_e32 v5, v2
	v_mov_b32_e32 v6, v2
	v_mov_b32_e32 v7, v2
	v_mov_b32_e32 v8, v2
	v_mov_b32_e32 v9, v2
	v_mov_b32_e32 v22, v2
	v_mov_b32_e32 v23, v2
	v_mov_b32_e32 v24, v2
	v_mov_b32_e32 v25, v2
	v_mov_b32_e32 v34, v2
	v_mov_b32_e32 v35, v2
	v_mov_b32_e32 v36, v2
	v_mov_b32_e32 v37, v2
	v_mov_b32_e32 v46, v2
	v_mov_b32_e32 v47, v2
	v_mov_b32_e32 v48, v2
	v_mov_b32_e32 v49, v2
	v_mov_b32_e32 v54, v2
	v_mov_b32_e32 v55, v2
	v_mov_b32_e32 v56, v2
	v_mov_b32_e32 v57, v2
	v_mov_b32_e32 v70, v2
	v_mov_b32_e32 v71, v2
	v_mov_b32_e32 v72, v2
	v_mov_b32_e32 v73, v2
	v_mov_b32_e32 v86, v2
	v_mov_b32_e32 v87, v2
	v_mov_b32_e32 v88, v2
	v_mov_b32_e32 v89, v2
	v_mov_b32_e32 v18, v2
	v_mov_b32_e32 v19, v2
	v_mov_b32_e32 v20, v2
	v_mov_b32_e32 v21, v2
	v_mov_b32_e32 v30, v2
	v_mov_b32_e32 v31, v2
	v_mov_b32_e32 v32, v2
	v_mov_b32_e32 v33, v2
	v_mov_b32_e32 v42, v2
	v_mov_b32_e32 v43, v2
	v_mov_b32_e32 v44, v2
	v_mov_b32_e32 v45, v2
	v_mov_b32_e32 v50, v2
	v_mov_b32_e32 v51, v2
	v_mov_b32_e32 v52, v2
	v_mov_b32_e32 v53, v2
	v_mov_b32_e32 v66, v2
	v_mov_b32_e32 v67, v2
	v_mov_b32_e32 v68, v2
	v_mov_b32_e32 v69, v2
	v_mov_b32_e32 v82, v2
	v_mov_b32_e32 v83, v2
	v_mov_b32_e32 v84, v2
	v_mov_b32_e32 v85, v2
	v_mov_b32_e32 v98, v2
	v_mov_b32_e32 v99, v2
	v_mov_b32_e32 v100, v2
	v_mov_b32_e32 v101, v2
	v_mov_b32_e32 v110, v2
	v_mov_b32_e32 v111, v2
	v_mov_b32_e32 v112, v2
	v_mov_b32_e32 v113, v2
	v_mov_b32_e32 v78, v2
	v_mov_b32_e32 v79, v2
	v_mov_b32_e32 v80, v2
	v_mov_b32_e32 v81, v2
	v_mov_b32_e32 v74, v2
	v_mov_b32_e32 v75, v2
	v_mov_b32_e32 v76, v2
	v_mov_b32_e32 v77, v2
	v_mov_b32_e32 v62, v2
	v_mov_b32_e32 v63, v2
	v_mov_b32_e32 v64, v2
	v_mov_b32_e32 v65, v2
	v_mov_b32_e32 v58, v2
	v_mov_b32_e32 v59, v2
	v_mov_b32_e32 v60, v2
	v_mov_b32_e32 v61, v2
	v_mov_b32_e32 v38, v2
	v_mov_b32_e32 v39, v2
	v_mov_b32_e32 v40, v2
	v_mov_b32_e32 v41, v2
	v_mov_b32_e32 v26, v2
	v_mov_b32_e32 v27, v2
	v_mov_b32_e32 v28, v2
	v_mov_b32_e32 v29, v2
	v_mov_b32_e32 v14, v2
	v_mov_b32_e32 v15, v2
	v_mov_b32_e32 v16, v2
	v_mov_b32_e32 v17, v2
	v_mov_b32_e32 v10, v2
	v_mov_b32_e32 v11, v2
	v_mov_b32_e32 v12, v2
	v_mov_b32_e32 v13, v2
	v_mov_b32_e32 v126, v2
	v_mov_b32_e32 v127, v2
	v_mov_b32_e32 v128, v2
	v_mov_b32_e32 v129, v2
	v_mov_b32_e32 v122, v2
	v_mov_b32_e32 v123, v2
	v_mov_b32_e32 v124, v2
	v_mov_b32_e32 v125, v2
	v_mov_b32_e32 v118, v2
	v_mov_b32_e32 v119, v2
	v_mov_b32_e32 v120, v2
	v_mov_b32_e32 v121, v2
	v_mov_b32_e32 v114, v2
	v_mov_b32_e32 v115, v2
	v_mov_b32_e32 v116, v2
	v_mov_b32_e32 v117, v2
	v_mov_b32_e32 v106, v2
	v_mov_b32_e32 v107, v2
	v_mov_b32_e32 v108, v2
	v_mov_b32_e32 v109, v2
	v_mov_b32_e32 v102, v2
	v_mov_b32_e32 v103, v2
	v_mov_b32_e32 v104, v2
	v_mov_b32_e32 v105, v2
	v_mov_b32_e32 v94, v2
	v_mov_b32_e32 v95, v2
	v_mov_b32_e32 v96, v2
	v_mov_b32_e32 v97, v2
	v_mov_b32_e32 v90, v2
	v_mov_b32_e32 v91, v2
	v_mov_b32_e32 v92, v2
	v_mov_b32_e32 v93, v2
	s_andn2_b64 vcc, exec, s[0:1]
	s_cbranch_vccnz .LBB0_653
	s_branch .LBB0_654

.LBB0_749:
	ds_read_b128 v[176:179], v158
	ds_read_b128 v[192:195], v158 offset:1024
	ds_read_b128 v[196:199], v158 offset:2048
	ds_read_b128 v[200:203], v158 offset:3072
	ds_read_b128 v[204:207], v158 offset:4096
	ds_read_b128 v[208:211], v158 offset:5120
	ds_read_b128 v[224:227], v158 offset:6144
	ds_read_b128 v[228:231], v158 offset:7168
	s_add_u32 s20, s18, 0xfff80080
	s_addc_u32 s21, s19, -1
	s_add_i32 s58, 0, 0x10000
	s_cmp_eq_u32 s57, 28
	s_cselect_b32 s23, s39, s21
	s_cselect_b32 s22, s53, s20
	s_cselect_b32 s21, s31, s56
	s_cselect_b32 s20, s54, s55
	v_lshl_add_u64 v[212:213], s[18:19], 0, v[154:155]
	s_add_i32 m0, s44, 0xc000
	s_nop 0
	global_load_lds_dwordx4 v[212:213], off
	v_lshl_add_u64 v[212:213], s[18:19], 0, v[156:157]
	s_add_i32 m0, s44, 0xe000
	s_nop 0
	global_load_lds_dwordx4 v[212:213], off
	s_waitcnt lgkmcnt(8)
	s_barrier
	s_waitcnt lgkmcnt(0)
	v_mfma_f32_16x16x32_bf16 v[126:129], v[160:163], v[176:179], v[126:129]
	v_mfma_f32_16x16x32_bf16 v[122:125], v[168:171], v[176:179], v[122:125]
	v_mfma_f32_16x16x32_bf16 v[110:113], v[160:163], v[196:199], v[110:113]
	v_mfma_f32_16x16x32_bf16 v[106:109], v[168:171], v[196:199], v[106:109]
	v_mfma_f32_16x16x32_bf16 v[94:97], v[160:163], v[204:207], v[94:97]
	v_mfma_f32_16x16x32_bf16 v[90:93], v[168:171], v[204:207], v[90:93]
	v_mfma_f32_16x16x32_bf16 v[78:81], v[160:163], v[224:227], v[78:81]
	v_mfma_f32_16x16x32_bf16 v[74:77], v[168:171], v[224:227], v[74:77]
	v_mfma_f32_16x16x32_bf16 v[126:129], v[164:167], v[192:195], v[126:129]
	v_mfma_f32_16x16x32_bf16 v[122:125], v[172:175], v[192:195], v[122:125]
	v_mfma_f32_16x16x32_bf16 v[110:113], v[164:167], v[200:203], v[110:113]
	v_mfma_f32_16x16x32_bf16 v[106:109], v[172:175], v[200:203], v[106:109]
	v_mfma_f32_16x16x32_bf16 v[94:97], v[164:167], v[208:211], v[94:97]
	v_mfma_f32_16x16x32_bf16 v[90:93], v[172:175], v[208:211], v[90:93]
	v_mfma_f32_16x16x32_bf16 v[78:81], v[164:167], v[228:231], v[78:81]
	v_mfma_f32_16x16x32_bf16 v[74:77], v[172:175], v[228:231], v[74:77]
	s_barrier
	s_add_i32 s82, 0, 0x14000
	s_add_i32 s58, s58, s29
	v_add_u32_e32 v159, s82, v1
	v_lshl_add_u64 v[212:213], s[20:21], 0, v[134:135]
	s_mov_b32 m0, s58
	ds_read_b128 v[232:235], v159
	ds_read_b128 v[236:239], v159 offset:1024
	ds_read_b128 v[240:243], v159 offset:2048
	ds_read_b128 v[244:247], v159 offset:3072
	global_load_lds_dwordx4 v[212:213], off
	v_lshl_add_u64 v[248:249], s[20:21], 0, v[130:131]
	s_add_i32 m0, s58, 0x2000
	s_nop 0
	global_load_lds_dwordx4 v[248:249], off
	s_mov_b32 m0, s44
	v_lshl_add_u64 v[250:251], s[22:23], 0, v[136:137]
	s_barrier
	s_waitcnt lgkmcnt(0)
	v_mfma_f32_16x16x32_bf16 v[118:121], v[232:235], v[176:179], v[118:121]
	v_mfma_f32_16x16x32_bf16 v[114:117], v[240:243], v[176:179], v[114:117]
	v_mfma_f32_16x16x32_bf16 v[102:105], v[232:235], v[196:199], v[102:105]
	v_mfma_f32_16x16x32_bf16 v[98:101], v[240:243], v[196:199], v[98:101]
	v_mfma_f32_16x16x32_bf16 v[86:89], v[232:235], v[204:207], v[86:89]
	v_mfma_f32_16x16x32_bf16 v[82:85], v[240:243], v[204:207], v[82:85]
	v_mfma_f32_16x16x32_bf16 v[70:73], v[232:235], v[224:227], v[70:73]
	v_mfma_f32_16x16x32_bf16 v[66:69], v[240:243], v[224:227], v[66:69]
	v_mfma_f32_16x16x32_bf16 v[118:121], v[236:239], v[192:195], v[118:121]
	v_mfma_f32_16x16x32_bf16 v[114:117], v[244:247], v[192:195], v[114:117]
	v_mfma_f32_16x16x32_bf16 v[102:105], v[236:239], v[200:203], v[102:105]
	v_mfma_f32_16x16x32_bf16 v[98:101], v[244:247], v[200:203], v[98:101]
	v_mfma_f32_16x16x32_bf16 v[86:89], v[236:239], v[208:211], v[86:89]
	v_mfma_f32_16x16x32_bf16 v[82:85], v[244:247], v[208:211], v[82:85]
	v_mfma_f32_16x16x32_bf16 v[70:73], v[236:239], v[228:231], v[70:73]
	v_mfma_f32_16x16x32_bf16 v[66:69], v[244:247], v[228:231], v[66:69]
	s_barrier
	ds_read_b128 v[176:179], v158 offset:16384
	ds_read_b128 v[192:195], v158 offset:17408
	ds_read_b128 v[196:199], v158 offset:18432
	ds_read_b128 v[200:203], v158 offset:19456
	ds_read_b128 v[204:207], v158 offset:20480
	ds_read_b128 v[208:211], v158 offset:21504
	ds_read_b128 v[224:227], v158 offset:22528
	ds_read_b128 v[228:231], v158 offset:23552
	global_load_lds_dwordx4 v[250:251], off
	v_lshl_add_u64 v[222:223], s[22:23], 0, v[132:133]
	s_mov_b32 m0, s45
	s_nop 0
	global_load_lds_dwordx4 v[222:223], off
	s_waitcnt vmcnt(10)
	s_barrier
	s_waitcnt lgkmcnt(0)
	v_mfma_f32_16x16x32_bf16 v[62:65], v[160:163], v[176:179], v[62:65]
	v_mfma_f32_16x16x32_bf16 v[58:61], v[168:171], v[176:179], v[58:61]
	v_mfma_f32_16x16x32_bf16 v[46:49], v[160:163], v[196:199], v[46:49]
	v_mfma_f32_16x16x32_bf16 v[42:45], v[168:171], v[196:199], v[42:45]
	v_mfma_f32_16x16x32_bf16 v[30:33], v[160:163], v[204:207], v[30:33]
	v_mfma_f32_16x16x32_bf16 v[26:29], v[168:171], v[204:207], v[26:29]
	v_mfma_f32_16x16x32_bf16 v[14:17], v[160:163], v[224:227], v[14:17]
	v_mfma_f32_16x16x32_bf16 v[10:13], v[168:171], v[224:227], v[10:13]
	v_mfma_f32_16x16x32_bf16 v[62:65], v[164:167], v[192:195], v[62:65]
	v_mfma_f32_16x16x32_bf16 v[58:61], v[172:175], v[192:195], v[58:61]
	v_mfma_f32_16x16x32_bf16 v[46:49], v[164:167], v[200:203], v[46:49]
	v_mfma_f32_16x16x32_bf16 v[42:45], v[172:175], v[200:203], v[42:45]
	v_mfma_f32_16x16x32_bf16 v[30:33], v[164:167], v[208:211], v[30:33]
	v_mfma_f32_16x16x32_bf16 v[26:29], v[172:175], v[208:211], v[26:29]
	v_mfma_f32_16x16x32_bf16 v[14:17], v[164:167], v[228:231], v[14:17]
	v_mfma_f32_16x16x32_bf16 v[10:13], v[172:175], v[228:231], v[10:13]
	s_barrier
	s_add_u32 s58, s20, 0x80000
	s_addc_u32 s59, s21, 0
	s_add_i32 s82, s82, s29
	v_lshl_add_u64 v[160:161], s[58:59], 0, v[134:135]
	s_mov_b32 m0, s82
	s_nop 0
	global_load_lds_dwordx4 v[160:161], off
	v_lshl_add_u64 v[160:161], s[58:59], 0, v[130:131]
	s_add_i32 m0, s82, 0x2000
	s_nop 0
	global_load_lds_dwordx4 v[160:161], off
	v_add_u32_e32 v159, 0x18000, v1
	ds_read_b128 v[160:163], v159
	ds_read_b128 v[164:167], v159 offset:1024
	ds_read_b128 v[168:171], v159 offset:2048
	ds_read_b128 v[172:175], v159 offset:3072
	s_add_i32 s58, 0, 0x18000
	s_waitcnt vmcnt(6)
	s_barrier
	v_mfma_f32_16x16x32_bf16 v[54:57], v[232:235], v[176:179], v[54:57]
	v_mfma_f32_16x16x32_bf16 v[50:53], v[240:243], v[176:179], v[50:53]
	v_mfma_f32_16x16x32_bf16 v[38:41], v[232:235], v[196:199], v[38:41]
	v_mfma_f32_16x16x32_bf16 v[34:37], v[240:243], v[196:199], v[34:37]
	v_mfma_f32_16x16x32_bf16 v[22:25], v[232:235], v[204:207], v[22:25]
	v_mfma_f32_16x16x32_bf16 v[18:21], v[240:243], v[204:207], v[18:21]
	v_mfma_f32_16x16x32_bf16 v[6:9], v[232:235], v[224:227], v[6:9]
	v_mfma_f32_16x16x32_bf16 v[2:5], v[240:243], v[224:227], v[2:5]
	v_mfma_f32_16x16x32_bf16 v[54:57], v[236:239], v[192:195], v[54:57]
	v_mfma_f32_16x16x32_bf16 v[50:53], v[244:247], v[192:195], v[50:53]
	v_mfma_f32_16x16x32_bf16 v[38:41], v[236:239], v[200:203], v[38:41]
	v_mfma_f32_16x16x32_bf16 v[34:37], v[244:247], v[200:203], v[34:37]
	v_mfma_f32_16x16x32_bf16 v[22:25], v[236:239], v[208:211], v[22:25]
	v_mfma_f32_16x16x32_bf16 v[18:21], v[244:247], v[208:211], v[18:21]
	v_mfma_f32_16x16x32_bf16 v[6:9], v[236:239], v[228:231], v[6:9]
	v_mfma_f32_16x16x32_bf16 v[2:5], v[244:247], v[228:231], v[2:5]
	s_barrier
	ds_read_b128 v[176:179], v158 offset:32768
	ds_read_b128 v[192:195], v158 offset:33792
	ds_read_b128 v[196:199], v158 offset:34816
	ds_read_b128 v[200:203], v158 offset:35840
	ds_read_b128 v[204:207], v158 offset:36864
	ds_read_b128 v[208:211], v158 offset:37888
	ds_read_b128 v[224:227], v158 offset:38912
	ds_read_b128 v[228:231], v158 offset:39936
	s_add_u32 s22, s22, 0x80000
	s_addc_u32 s23, s23, 0
	s_mov_b32 m0, s46
	v_lshl_add_u64 v[232:233], s[22:23], 0, v[136:137]
	global_load_lds_dwordx4 v[232:233], off
	v_lshl_add_u64 v[232:233], s[22:23], 0, v[132:133]
	s_mov_b32 m0, s47
	s_nop 0
	global_load_lds_dwordx4 v[232:233], off
	s_waitcnt lgkmcnt(8)
	s_barrier
	s_waitcnt lgkmcnt(0)
	v_mfma_f32_16x16x32_bf16 v[126:129], v[160:163], v[176:179], v[126:129]
	v_mfma_f32_16x16x32_bf16 v[122:125], v[168:171], v[176:179], v[122:125]
	v_mfma_f32_16x16x32_bf16 v[110:113], v[160:163], v[196:199], v[110:113]
	v_mfma_f32_16x16x32_bf16 v[106:109], v[168:171], v[196:199], v[106:109]
	v_mfma_f32_16x16x32_bf16 v[94:97], v[160:163], v[204:207], v[94:97]
	v_mfma_f32_16x16x32_bf16 v[90:93], v[168:171], v[204:207], v[90:93]
	v_mfma_f32_16x16x32_bf16 v[78:81], v[160:163], v[224:227], v[78:81]
	v_mfma_f32_16x16x32_bf16 v[74:77], v[168:171], v[224:227], v[74:77]
	v_mfma_f32_16x16x32_bf16 v[126:129], v[164:167], v[192:195], v[126:129]
	v_mfma_f32_16x16x32_bf16 v[122:125], v[172:175], v[192:195], v[122:125]
	v_mfma_f32_16x16x32_bf16 v[110:113], v[164:167], v[200:203], v[110:113]
	v_mfma_f32_16x16x32_bf16 v[106:109], v[172:175], v[200:203], v[106:109]
	v_mfma_f32_16x16x32_bf16 v[94:97], v[164:167], v[208:211], v[94:97]
	v_mfma_f32_16x16x32_bf16 v[90:93], v[172:175], v[208:211], v[90:93]
	v_mfma_f32_16x16x32_bf16 v[78:81], v[164:167], v[228:231], v[78:81]
	v_mfma_f32_16x16x32_bf16 v[74:77], v[172:175], v[228:231], v[74:77]
	s_barrier
	s_add_i32 s22, 0, 0x1c000
	s_add_i32 s23, s58, s29
	v_add_u32_e32 v159, s22, v1
	v_lshl_add_u64 v[212:213], v[212:213], 0, s[78:79]
	s_mov_b32 m0, s23
	ds_read_b128 v[232:235], v159
	ds_read_b128 v[236:239], v159 offset:1024
	ds_read_b128 v[240:243], v159 offset:2048
	ds_read_b128 v[244:247], v159 offset:3072
	global_load_lds_dwordx4 v[212:213], off
	v_lshl_add_u64 v[212:213], v[248:249], 0, s[78:79]
	s_add_i32 m0, s23, 0x2000
	s_nop 0
	global_load_lds_dwordx4 v[212:213], off
	s_mov_b32 m0, s48
	v_lshl_add_u64 v[212:213], v[250:251], 0, s[78:79]
	s_barrier
	s_waitcnt lgkmcnt(0)
	v_mfma_f32_16x16x32_bf16 v[118:121], v[232:235], v[176:179], v[118:121]
	v_mfma_f32_16x16x32_bf16 v[114:117], v[240:243], v[176:179], v[114:117]
	v_mfma_f32_16x16x32_bf16 v[102:105], v[232:235], v[196:199], v[102:105]
	v_mfma_f32_16x16x32_bf16 v[98:101], v[240:243], v[196:199], v[98:101]
	v_mfma_f32_16x16x32_bf16 v[86:89], v[232:235], v[204:207], v[86:89]
	v_mfma_f32_16x16x32_bf16 v[82:85], v[240:243], v[204:207], v[82:85]
	v_mfma_f32_16x16x32_bf16 v[70:73], v[232:235], v[224:227], v[70:73]
	v_mfma_f32_16x16x32_bf16 v[66:69], v[240:243], v[224:227], v[66:69]
	v_mfma_f32_16x16x32_bf16 v[118:121], v[236:239], v[192:195], v[118:121]
	v_mfma_f32_16x16x32_bf16 v[114:117], v[244:247], v[192:195], v[114:117]
	v_mfma_f32_16x16x32_bf16 v[102:105], v[236:239], v[200:203], v[102:105]
	v_mfma_f32_16x16x32_bf16 v[98:101], v[244:247], v[200:203], v[98:101]
	v_mfma_f32_16x16x32_bf16 v[86:89], v[236:239], v[208:211], v[86:89]
	v_mfma_f32_16x16x32_bf16 v[82:85], v[244:247], v[208:211], v[82:85]
	v_mfma_f32_16x16x32_bf16 v[70:73], v[236:239], v[228:231], v[70:73]
	v_mfma_f32_16x16x32_bf16 v[66:69], v[244:247], v[228:231], v[66:69]
	s_barrier
	ds_read_b128 v[176:179], v158 offset:49152
	ds_read_b128 v[192:195], v158 offset:50176
	ds_read_b128 v[196:199], v158 offset:51200
	ds_read_b128 v[200:203], v158 offset:52224
	ds_read_b128 v[204:207], v158 offset:53248
	ds_read_b128 v[208:211], v158 offset:54272
	ds_read_b128 v[224:227], v158 offset:55296
	ds_read_b128 v[228:231], v158 offset:56320
	global_load_lds_dwordx4 v[212:213], off
	v_lshl_add_u64 v[212:213], v[222:223], 0, s[78:79]
	s_mov_b32 m0, s49
	s_nop 0
	global_load_lds_dwordx4 v[212:213], off
	s_waitcnt vmcnt(10)
	s_barrier
	s_waitcnt lgkmcnt(0)
	v_mfma_f32_16x16x32_bf16 v[62:65], v[160:163], v[176:179], v[62:65]
	v_mfma_f32_16x16x32_bf16 v[58:61], v[168:171], v[176:179], v[58:61]
	v_mfma_f32_16x16x32_bf16 v[46:49], v[160:163], v[196:199], v[46:49]
	v_mfma_f32_16x16x32_bf16 v[42:45], v[168:171], v[196:199], v[42:45]
	v_mfma_f32_16x16x32_bf16 v[30:33], v[160:163], v[204:207], v[30:33]
	v_mfma_f32_16x16x32_bf16 v[26:29], v[168:171], v[204:207], v[26:29]
	v_mfma_f32_16x16x32_bf16 v[14:17], v[160:163], v[224:227], v[14:17]
	v_mfma_f32_16x16x32_bf16 v[10:13], v[168:171], v[224:227], v[10:13]
	v_mfma_f32_16x16x32_bf16 v[62:65], v[164:167], v[192:195], v[62:65]
	v_mfma_f32_16x16x32_bf16 v[58:61], v[172:175], v[192:195], v[58:61]
	v_mfma_f32_16x16x32_bf16 v[46:49], v[164:167], v[200:203], v[46:49]
	v_mfma_f32_16x16x32_bf16 v[42:45], v[172:175], v[200:203], v[42:45]
	v_mfma_f32_16x16x32_bf16 v[30:33], v[164:167], v[208:211], v[30:33]
	v_mfma_f32_16x16x32_bf16 v[26:29], v[172:175], v[208:211], v[26:29]
	v_mfma_f32_16x16x32_bf16 v[14:17], v[164:167], v[228:231], v[14:17]
	v_mfma_f32_16x16x32_bf16 v[10:13], v[172:175], v[228:231], v[10:13]
	s_barrier
	s_add_u32 s20, s20, 0x80080
	s_addc_u32 s21, s21, 0
	s_add_i32 s22, s22, s29
	v_lshl_add_u64 v[160:161], s[20:21], 0, v[134:135]
	s_mov_b32 m0, s22
	s_nop 0
	global_load_lds_dwordx4 v[160:161], off
	v_lshl_add_u64 v[160:161], s[20:21], 0, v[130:131]
	s_add_i32 m0, s22, 0x2000
	s_nop 0
	global_load_lds_dwordx4 v[160:161], off
	v_add_u32_e32 v159, 0x10000, v1
	ds_read_b128 v[160:163], v159
	ds_read_b128 v[164:167], v159 offset:1024
	ds_read_b128 v[168:171], v159 offset:2048
	ds_read_b128 v[172:175], v159 offset:3072
	s_add_i32 s57, s57, 2
	s_add_u32 s18, s18, 0x100
	s_addc_u32 s19, s19, 0
	s_add_u32 s55, s55, 0x100
	s_addc_u32 s56, s56, 0
	s_cmp_gt_u32 s57, 29
	s_waitcnt vmcnt(6)
	s_barrier
	v_mfma_f32_16x16x32_bf16 v[54:57], v[232:235], v[176:179], v[54:57]
	v_mfma_f32_16x16x32_bf16 v[50:53], v[240:243], v[176:179], v[50:53]
	v_mfma_f32_16x16x32_bf16 v[38:41], v[232:235], v[196:199], v[38:41]
	v_mfma_f32_16x16x32_bf16 v[34:37], v[240:243], v[196:199], v[34:37]
	v_mfma_f32_16x16x32_bf16 v[22:25], v[232:235], v[204:207], v[22:25]
	v_mfma_f32_16x16x32_bf16 v[18:21], v[240:243], v[204:207], v[18:21]
	v_mfma_f32_16x16x32_bf16 v[6:9], v[232:235], v[224:227], v[6:9]
	v_mfma_f32_16x16x32_bf16 v[2:5], v[240:243], v[224:227], v[2:5]
	v_mfma_f32_16x16x32_bf16 v[54:57], v[236:239], v[192:195], v[54:57]
	v_mfma_f32_16x16x32_bf16 v[50:53], v[244:247], v[192:195], v[50:53]
	v_mfma_f32_16x16x32_bf16 v[38:41], v[236:239], v[200:203], v[38:41]
	v_mfma_f32_16x16x32_bf16 v[34:37], v[244:247], v[200:203], v[34:37]
	v_mfma_f32_16x16x32_bf16 v[22:25], v[236:239], v[208:211], v[22:25]
	v_mfma_f32_16x16x32_bf16 v[18:21], v[244:247], v[208:211], v[18:21]
	v_mfma_f32_16x16x32_bf16 v[6:9], v[236:239], v[228:231], v[6:9]
	v_mfma_f32_16x16x32_bf16 v[2:5], v[244:247], v[228:231], v[2:5]
	s_barrier
	s_cbranch_scc0 .LBB0_749
	s_waitcnt lgkmcnt(0)
	s_lshl_b32 s18, s52, 5
	s_add_i32 s18, s18, s51
	v_max_f32_e32 v122, 0, v122
	v_max_f32_e32 v123, 0, v123
	s_ashr_i32 s19, s18, 31
	v_pk_mul_f32 v[162:163], v[122:123], v[122:123]
	v_max_f32_e32 v123, v124, v124
	s_lshl_b64 s[18:19], s[18:19], 17
	v_max_f32_e32 v122, v128, v128
	v_max_f32_e32 v124, 0, v123
	v_max_f32_e32 v123, v129, v129
	s_add_u32 s18, s68, s18
	v_max_f32_e32 v126, 0, v126
	v_max_f32_e32 v127, 0, v127
	v_max_f32_e32 v122, 0, v122
	v_max_f32_e32 v123, 0, v123
	v_max_f32_e32 v125, 0, v125
	s_addc_u32 s19, s69, s19
	v_pk_mul_f32 v[126:127], v[126:127], v[126:127]
	v_pk_mul_f32 v[128:129], v[122:123], v[122:123]
	v_pk_mul_f32 v[164:165], v[124:125], v[124:125]
	v_lshl_add_u64 v[160:161], v[138:139], 1, s[18:19]
	v_cvt_pk_bf16_f32 v122, v126, v127
	v_cvt_pk_bf16_f32 v123, v128, v129
	v_cvt_pk_bf16_f32 v124, v162, v163
	v_cvt_pk_bf16_f32 v125, v164, v165
	v_max_f32_e32 v114, 0, v114
	v_max_f32_e32 v115, 0, v115
	global_store_dwordx4 v[160:161], v[122:125], off
	v_max_f32_e32 v118, v118, v118
	v_max_f32_e32 v119, v119, v119
	v_pk_mul_f32 v[122:123], v[114:115], v[114:115]
	v_max_f32_e32 v115, v116, v116
	v_max_f32_e32 v114, v120, v120
	v_max_f32_e32 v116, 0, v115
	v_max_f32_e32 v115, v121, v121
	v_max_f32_e32 v118, 0, v118
	v_max_f32_e32 v119, 0, v119
	v_max_f32_e32 v114, 0, v114
	v_max_f32_e32 v115, 0, v115
	v_max_f32_e32 v117, 0, v117
	v_pk_mul_f32 v[118:119], v[118:119], v[118:119]
	v_pk_mul_f32 v[120:121], v[114:115], v[114:115]
	v_pk_mul_f32 v[124:125], v[116:117], v[116:117]
	v_cvt_pk_bf16_f32 v114, v118, v119
	v_cvt_pk_bf16_f32 v115, v120, v121
	v_cvt_pk_bf16_f32 v116, v122, v123
	v_cvt_pk_bf16_f32 v117, v124, v125
	v_max_f32_e32 v106, 0, v106
	v_max_f32_e32 v107, 0, v107
	global_store_dwordx4 v[160:161], v[114:117], off offset:256
	v_max_f32_e32 v110, v110, v110
	v_max_f32_e32 v111, v111, v111
	v_pk_mul_f32 v[116:117], v[106:107], v[106:107]
	v_max_f32_e32 v107, v108, v108
	v_max_f32_e32 v106, v112, v112
	v_max_f32_e32 v108, 0, v107
	v_max_f32_e32 v107, v113, v113
	v_max_f32_e32 v110, 0, v110
	v_max_f32_e32 v111, 0, v111
	v_max_f32_e32 v106, 0, v106
	v_max_f32_e32 v107, 0, v107
	v_max_f32_e32 v109, 0, v109
	v_pk_mul_f32 v[110:111], v[110:111], v[110:111]
	v_pk_mul_f32 v[112:113], v[106:107], v[106:107]
	v_pk_mul_f32 v[118:119], v[108:109], v[108:109]
	v_lshl_add_u64 v[114:115], v[140:141], 1, s[18:19]
	v_cvt_pk_bf16_f32 v106, v110, v111
	v_cvt_pk_bf16_f32 v107, v112, v113
	v_cvt_pk_bf16_f32 v108, v116, v117
	v_cvt_pk_bf16_f32 v109, v118, v119
	v_max_f32_e32 v98, 0, v98
	v_max_f32_e32 v99, 0, v99
	global_store_dwordx4 v[114:115], v[106:109], off
	v_max_f32_e32 v102, v102, v102
	v_max_f32_e32 v103, v103, v103
	v_pk_mul_f32 v[106:107], v[98:99], v[98:99]
	v_max_f32_e32 v99, v100, v100
	v_max_f32_e32 v98, v104, v104
	v_max_f32_e32 v100, 0, v99
	v_max_f32_e32 v99, v105, v105
	v_max_f32_e32 v102, 0, v102
	v_max_f32_e32 v103, 0, v103
	v_max_f32_e32 v98, 0, v98
	v_max_f32_e32 v99, 0, v99
	v_max_f32_e32 v101, 0, v101
	v_pk_mul_f32 v[102:103], v[102:103], v[102:103]
	v_pk_mul_f32 v[104:105], v[98:99], v[98:99]
	v_pk_mul_f32 v[108:109], v[100:101], v[100:101]
	v_cvt_pk_bf16_f32 v98, v102, v103
	v_cvt_pk_bf16_f32 v99, v104, v105
	v_cvt_pk_bf16_f32 v100, v106, v107
	v_cvt_pk_bf16_f32 v101, v108, v109
	v_max_f32_e32 v90, 0, v90
	v_max_f32_e32 v91, 0, v91
	global_store_dwordx4 v[114:115], v[98:101], off offset:256
	v_max_f32_e32 v94, v94, v94
	v_max_f32_e32 v95, v95, v95
	v_pk_mul_f32 v[100:101], v[90:91], v[90:91]
	v_max_f32_e32 v91, v92, v92
	v_max_f32_e32 v90, v96, v96
	v_max_f32_e32 v92, 0, v91
	v_max_f32_e32 v91, v97, v97
	v_max_f32_e32 v94, 0, v94
	v_max_f32_e32 v95, 0, v95
	v_max_f32_e32 v90, 0, v90
	v_max_f32_e32 v91, 0, v91
	v_max_f32_e32 v93, 0, v93
	v_pk_mul_f32 v[94:95], v[94:95], v[94:95]
	v_pk_mul_f32 v[96:97], v[90:91], v[90:91]
	v_pk_mul_f32 v[102:103], v[92:93], v[92:93]
	v_lshl_add_u64 v[98:99], v[142:143], 1, s[18:19]
	v_cvt_pk_bf16_f32 v90, v94, v95
	v_cvt_pk_bf16_f32 v91, v96, v97
	v_cvt_pk_bf16_f32 v92, v100, v101
	v_cvt_pk_bf16_f32 v93, v102, v103
	v_max_f32_e32 v82, 0, v82
	v_max_f32_e32 v83, 0, v83
	global_store_dwordx4 v[98:99], v[90:93], off
	v_max_f32_e32 v86, v86, v86
	v_max_f32_e32 v87, v87, v87
	v_pk_mul_f32 v[90:91], v[82:83], v[82:83]
	v_max_f32_e32 v83, v84, v84
	v_max_f32_e32 v82, v88, v88
	v_max_f32_e32 v84, 0, v83
	v_max_f32_e32 v83, v89, v89
	v_max_f32_e32 v86, 0, v86
	v_max_f32_e32 v87, 0, v87
	v_max_f32_e32 v82, 0, v82
	v_max_f32_e32 v83, 0, v83
	v_max_f32_e32 v85, 0, v85
	v_pk_mul_f32 v[86:87], v[86:87], v[86:87]
	v_pk_mul_f32 v[88:89], v[82:83], v[82:83]
	v_pk_mul_f32 v[92:93], v[84:85], v[84:85]
	v_cvt_pk_bf16_f32 v82, v86, v87
	v_cvt_pk_bf16_f32 v83, v88, v89
	v_cvt_pk_bf16_f32 v84, v90, v91
	v_cvt_pk_bf16_f32 v85, v92, v93
	v_max_f32_e32 v74, 0, v74
	v_max_f32_e32 v75, 0, v75
	global_store_dwordx4 v[98:99], v[82:85], off offset:256
	v_max_f32_e32 v78, v78, v78
	v_max_f32_e32 v79, v79, v79
	v_pk_mul_f32 v[84:85], v[74:75], v[74:75]
	v_max_f32_e32 v75, v76, v76
	v_max_f32_e32 v74, v80, v80
	v_max_f32_e32 v76, 0, v75
	v_max_f32_e32 v75, v81, v81
	v_max_f32_e32 v78, 0, v78
	v_max_f32_e32 v79, 0, v79
	v_max_f32_e32 v74, 0, v74
	v_max_f32_e32 v75, 0, v75
	v_max_f32_e32 v77, 0, v77
	v_pk_mul_f32 v[78:79], v[78:79], v[78:79]
	v_pk_mul_f32 v[80:81], v[74:75], v[74:75]
	v_pk_mul_f32 v[86:87], v[76:77], v[76:77]
	v_lshl_add_u64 v[82:83], v[144:145], 1, s[18:19]
	v_cvt_pk_bf16_f32 v74, v78, v79
	v_cvt_pk_bf16_f32 v75, v80, v81
	v_cvt_pk_bf16_f32 v76, v84, v85
	v_cvt_pk_bf16_f32 v77, v86, v87
	v_max_f32_e32 v66, 0, v66
	v_max_f32_e32 v67, 0, v67
	global_store_dwordx4 v[82:83], v[74:77], off
	v_max_f32_e32 v70, v70, v70
	v_max_f32_e32 v71, v71, v71
	v_pk_mul_f32 v[74:75], v[66:67], v[66:67]
	v_max_f32_e32 v67, v68, v68
	v_max_f32_e32 v66, v72, v72
	v_max_f32_e32 v68, 0, v67
	v_max_f32_e32 v67, v73, v73
	v_max_f32_e32 v70, 0, v70
	v_max_f32_e32 v71, 0, v71
	v_max_f32_e32 v66, 0, v66
	v_max_f32_e32 v67, 0, v67
	v_max_f32_e32 v69, 0, v69
	v_pk_mul_f32 v[70:71], v[70:71], v[70:71]
	v_pk_mul_f32 v[72:73], v[66:67], v[66:67]
	v_pk_mul_f32 v[76:77], v[68:69], v[68:69]
	v_cvt_pk_bf16_f32 v66, v70, v71
	v_cvt_pk_bf16_f32 v67, v72, v73
	v_cvt_pk_bf16_f32 v68, v74, v75
	v_cvt_pk_bf16_f32 v69, v76, v77
	v_max_f32_e32 v58, 0, v58
	v_max_f32_e32 v59, 0, v59
	global_store_dwordx4 v[82:83], v[66:69], off offset:256
	v_max_f32_e32 v62, v62, v62
	v_max_f32_e32 v63, v63, v63
	v_pk_mul_f32 v[68:69], v[58:59], v[58:59]
	v_max_f32_e32 v59, v60, v60
	v_max_f32_e32 v58, v64, v64
	v_max_f32_e32 v60, 0, v59
	v_max_f32_e32 v59, v65, v65
	v_max_f32_e32 v62, 0, v62
	v_max_f32_e32 v63, 0, v63
	v_max_f32_e32 v58, 0, v58
	v_max_f32_e32 v59, 0, v59
	v_max_f32_e32 v61, 0, v61
	v_pk_mul_f32 v[62:63], v[62:63], v[62:63]
	v_pk_mul_f32 v[64:65], v[58:59], v[58:59]
	v_pk_mul_f32 v[70:71], v[60:61], v[60:61]
	v_lshl_add_u64 v[66:67], v[146:147], 1, s[18:19]
	v_cvt_pk_bf16_f32 v58, v62, v63
	v_cvt_pk_bf16_f32 v59, v64, v65
	v_cvt_pk_bf16_f32 v60, v68, v69
	v_cvt_pk_bf16_f32 v61, v70, v71
	v_max_f32_e32 v50, 0, v50
	v_max_f32_e32 v51, 0, v51
	global_store_dwordx4 v[66:67], v[58:61], off
	v_max_f32_e32 v54, v54, v54
	v_max_f32_e32 v55, v55, v55
	v_pk_mul_f32 v[58:59], v[50:51], v[50:51]
	v_max_f32_e32 v51, v52, v52
	v_max_f32_e32 v50, v56, v56
	v_max_f32_e32 v52, 0, v51
	v_max_f32_e32 v51, v57, v57
	v_max_f32_e32 v54, 0, v54
	v_max_f32_e32 v55, 0, v55
	v_max_f32_e32 v50, 0, v50
	v_max_f32_e32 v51, 0, v51
	v_max_f32_e32 v53, 0, v53
	v_pk_mul_f32 v[54:55], v[54:55], v[54:55]
	v_pk_mul_f32 v[56:57], v[50:51], v[50:51]
	v_pk_mul_f32 v[60:61], v[52:53], v[52:53]
	v_cvt_pk_bf16_f32 v50, v54, v55
	v_cvt_pk_bf16_f32 v51, v56, v57
	v_cvt_pk_bf16_f32 v52, v58, v59
	v_cvt_pk_bf16_f32 v53, v60, v61
	v_max_f32_e32 v42, 0, v42
	v_max_f32_e32 v43, 0, v43
	global_store_dwordx4 v[66:67], v[50:53], off offset:256
	v_max_f32_e32 v46, v46, v46
	v_max_f32_e32 v47, v47, v47
	v_pk_mul_f32 v[52:53], v[42:43], v[42:43]
	v_max_f32_e32 v43, v44, v44
	v_max_f32_e32 v42, v48, v48
	v_max_f32_e32 v44, 0, v43
	v_max_f32_e32 v43, v49, v49
	v_max_f32_e32 v46, 0, v46
	v_max_f32_e32 v47, 0, v47
	v_max_f32_e32 v42, 0, v42
	v_max_f32_e32 v43, 0, v43
	v_max_f32_e32 v45, 0, v45
	v_pk_mul_f32 v[46:47], v[46:47], v[46:47]
	v_pk_mul_f32 v[48:49], v[42:43], v[42:43]
	v_pk_mul_f32 v[54:55], v[44:45], v[44:45]
	v_lshl_add_u64 v[50:51], v[148:149], 1, s[18:19]
	v_cvt_pk_bf16_f32 v42, v46, v47
	v_cvt_pk_bf16_f32 v43, v48, v49
	v_cvt_pk_bf16_f32 v44, v52, v53
	v_cvt_pk_bf16_f32 v45, v54, v55
	v_max_f32_e32 v34, 0, v34
	v_max_f32_e32 v35, 0, v35
	global_store_dwordx4 v[50:51], v[42:45], off
	v_max_f32_e32 v38, v38, v38
	v_max_f32_e32 v39, v39, v39
	v_pk_mul_f32 v[42:43], v[34:35], v[34:35]
	v_max_f32_e32 v35, v36, v36
	v_max_f32_e32 v34, v40, v40
	v_max_f32_e32 v36, 0, v35
	v_max_f32_e32 v35, v41, v41
	v_max_f32_e32 v38, 0, v38
	v_max_f32_e32 v39, 0, v39
	v_max_f32_e32 v34, 0, v34
	v_max_f32_e32 v35, 0, v35
	v_max_f32_e32 v37, 0, v37
	v_pk_mul_f32 v[38:39], v[38:39], v[38:39]
	v_pk_mul_f32 v[40:41], v[34:35], v[34:35]
	v_pk_mul_f32 v[44:45], v[36:37], v[36:37]
	v_cvt_pk_bf16_f32 v34, v38, v39
	v_cvt_pk_bf16_f32 v35, v40, v41
	v_cvt_pk_bf16_f32 v36, v42, v43
	v_cvt_pk_bf16_f32 v37, v44, v45
	v_max_f32_e32 v26, 0, v26
	v_max_f32_e32 v27, 0, v27
	global_store_dwordx4 v[50:51], v[34:37], off offset:256
	v_max_f32_e32 v30, v30, v30
	v_max_f32_e32 v31, v31, v31
	v_pk_mul_f32 v[36:37], v[26:27], v[26:27]
	v_max_f32_e32 v27, v28, v28
	v_max_f32_e32 v26, v32, v32
	v_max_f32_e32 v28, 0, v27
	v_max_f32_e32 v27, v33, v33
	v_max_f32_e32 v30, 0, v30
	v_max_f32_e32 v31, 0, v31
	v_max_f32_e32 v26, 0, v26
	v_max_f32_e32 v27, 0, v27
	v_max_f32_e32 v29, 0, v29
	v_pk_mul_f32 v[30:31], v[30:31], v[30:31]
	v_pk_mul_f32 v[32:33], v[26:27], v[26:27]
	v_pk_mul_f32 v[38:39], v[28:29], v[28:29]
	v_lshl_add_u64 v[34:35], v[150:151], 1, s[18:19]
	v_cvt_pk_bf16_f32 v26, v30, v31
	v_cvt_pk_bf16_f32 v27, v32, v33
	v_cvt_pk_bf16_f32 v28, v36, v37
	v_cvt_pk_bf16_f32 v29, v38, v39
	v_max_f32_e32 v18, 0, v18
	v_max_f32_e32 v19, 0, v19
	global_store_dwordx4 v[34:35], v[26:29], off
	v_max_f32_e32 v22, v22, v22
	v_max_f32_e32 v23, v23, v23
	v_pk_mul_f32 v[26:27], v[18:19], v[18:19]
	v_max_f32_e32 v19, v20, v20
	v_max_f32_e32 v18, v24, v24
	v_max_f32_e32 v20, 0, v19
	v_max_f32_e32 v19, v25, v25
	v_max_f32_e32 v22, 0, v22
	v_max_f32_e32 v23, 0, v23
	v_max_f32_e32 v18, 0, v18
	v_max_f32_e32 v19, 0, v19
	v_max_f32_e32 v21, 0, v21
	v_pk_mul_f32 v[22:23], v[22:23], v[22:23]
	v_pk_mul_f32 v[24:25], v[18:19], v[18:19]
	v_pk_mul_f32 v[28:29], v[20:21], v[20:21]
	v_cvt_pk_bf16_f32 v18, v22, v23
	v_cvt_pk_bf16_f32 v19, v24, v25
	v_cvt_pk_bf16_f32 v20, v26, v27
	v_cvt_pk_bf16_f32 v21, v28, v29
	v_max_f32_e32 v10, 0, v10
	v_max_f32_e32 v11, 0, v11
	global_store_dwordx4 v[34:35], v[18:21], off offset:256
	v_max_f32_e32 v14, v14, v14
	v_max_f32_e32 v15, v15, v15
	v_pk_mul_f32 v[20:21], v[10:11], v[10:11]
	v_max_f32_e32 v11, v12, v12
	v_max_f32_e32 v10, v16, v16
	v_max_f32_e32 v12, 0, v11
	v_max_f32_e32 v11, v17, v17
	v_max_f32_e32 v14, 0, v14
	v_max_f32_e32 v15, 0, v15
	v_max_f32_e32 v10, 0, v10
	v_max_f32_e32 v11, 0, v11
	v_max_f32_e32 v13, 0, v13
	v_pk_mul_f32 v[14:15], v[14:15], v[14:15]
	v_pk_mul_f32 v[16:17], v[10:11], v[10:11]
	v_pk_mul_f32 v[22:23], v[12:13], v[12:13]
	v_lshl_add_u64 v[18:19], v[152:153], 1, s[18:19]
	v_cvt_pk_bf16_f32 v10, v14, v15
	v_cvt_pk_bf16_f32 v11, v16, v17
	v_cvt_pk_bf16_f32 v12, v20, v21
	v_cvt_pk_bf16_f32 v13, v22, v23
	v_max_f32_e32 v2, 0, v2
	v_max_f32_e32 v3, 0, v3
	global_store_dwordx4 v[18:19], v[10:13], off
	v_max_f32_e32 v6, v6, v6
	v_max_f32_e32 v7, v7, v7
	v_pk_mul_f32 v[10:11], v[2:3], v[2:3]
	v_max_f32_e32 v3, v4, v4
	v_max_f32_e32 v2, v8, v8
	v_max_f32_e32 v4, 0, v3
	v_max_f32_e32 v3, v9, v9
	v_max_f32_e32 v6, 0, v6
	v_max_f32_e32 v7, 0, v7
	v_max_f32_e32 v2, 0, v2
	v_max_f32_e32 v3, 0, v3
	v_max_f32_e32 v5, 0, v5
	v_pk_mul_f32 v[6:7], v[6:7], v[6:7]
	v_pk_mul_f32 v[8:9], v[2:3], v[2:3]
	v_pk_mul_f32 v[12:13], v[4:5], v[4:5]
	v_cvt_pk_bf16_f32 v2, v6, v7
	v_cvt_pk_bf16_f32 v3, v8, v9
	v_cvt_pk_bf16_f32 v4, v10, v11
	v_cvt_pk_bf16_f32 v5, v12, v13
	s_and_b64 vcc, exec, s[0:1]
	s_mov_b32 s51, s30
	s_mov_b32 s52, s38
	s_mov_b64 s[20:21], s[80:81]
	s_mov_b64 s[18:19], s[42:43]
	global_store_dwordx4 v[18:19], v[2:5], off offset:256
	s_cbranch_vccz .LBB0_742
	s_waitcnt vmcnt(0)
	v_readlane_b32 s38, v255, 28
	s_cmpk_gt_u32 s26, 0xff
	v_readlane_b32 s39, v255, 29
	v_readlane_b32 s42, v255, 32
	s_cbranch_scc1 .LBB0_753
	s_barrier

.LBB0_814:
	ds_read_b128 v[158:161], v140
	ds_read_b128 v[162:165], v140 offset:1024
	ds_read_b128 v[168:171], v140 offset:2048
	ds_read_b128 v[172:175], v140 offset:3072
	ds_read_b128 v[176:179], v140 offset:4096
	ds_read_b128 v[192:195], v140 offset:5120
	ds_read_b128 v[196:199], v140 offset:6144
	ds_read_b128 v[200:203], v140 offset:7168
	s_add_i32 s22, s55, 0xffff0000
	s_and_b32 s22, s22, 0x3e0000
	s_and_b32 s23, s90, 0x100
	s_or_b32 s56, s23, s22
	s_and_b32 s22, s55, 0x7e0000
	s_add_u32 vcc_lo, s90, 0x100
	s_addc_u32 vcc_hi, s91, 0
	s_and_b32 s23, vcc_lo, 0x100
	s_or_b32 s22, s22, s23
	s_add_u32 s22, s84, s22
	s_addc_u32 s23, s85, 0
	s_add_u32 s57, s30, s90
	s_addc_u32 s58, s31, s91
	s_add_u32 s57, s57, 0x100
	s_addc_u32 s58, s58, 0
	s_add_i32 s59, 0, 0x10000
	s_cmpk_eq_i32 s54, 0x7c
	s_cselect_b32 s91, s43, s58
	s_cselect_b32 s90, s53, s57
	s_cselect_b32 s23, s51, s23
	s_cselect_b32 s22, s52, s22
	s_add_u32 s56, s84, s56
	s_addc_u32 s57, s85, 0
	s_add_u32 s56, s56, 0x10080
	s_addc_u32 s57, s57, 0
	v_lshl_add_u64 v[204:205], s[56:57], 0, v[136:137]
	s_add_i32 m0, s28, 0xc000
	s_nop 0
	global_load_lds_dwordx4 v[204:205], off
	v_lshl_add_u64 v[204:205], s[56:57], 0, v[132:133]
	s_add_i32 m0, s28, 0xe000
	s_nop 0
	global_load_lds_dwordx4 v[204:205], off
	s_waitcnt lgkmcnt(8)
	s_barrier
	s_waitcnt lgkmcnt(0)
	v_mfma_f32_16x16x32_bf16 v[86:89], v[142:145], v[158:161], v[86:89]
	v_mfma_f32_16x16x32_bf16 v[94:97], v[150:153], v[158:161], v[94:97]
	v_mfma_f32_16x16x32_bf16 v[98:101], v[142:145], v[168:171], v[98:101]
	v_mfma_f32_16x16x32_bf16 v[102:105], v[150:153], v[168:171], v[102:105]
	v_mfma_f32_16x16x32_bf16 v[114:117], v[142:145], v[176:179], v[114:117]
	v_mfma_f32_16x16x32_bf16 v[122:125], v[150:153], v[176:179], v[122:125]
	v_mfma_f32_16x16x32_bf16 v[126:129], v[142:145], v[196:199], v[126:129]
	v_mfma_f32_16x16x32_bf16 v[118:121], v[150:153], v[196:199], v[118:121]
	v_mfma_f32_16x16x32_bf16 v[86:89], v[146:149], v[162:165], v[86:89]
	v_mfma_f32_16x16x32_bf16 v[94:97], v[154:157], v[162:165], v[94:97]
	v_mfma_f32_16x16x32_bf16 v[98:101], v[146:149], v[172:175], v[98:101]
	v_mfma_f32_16x16x32_bf16 v[102:105], v[154:157], v[172:175], v[102:105]
	v_mfma_f32_16x16x32_bf16 v[114:117], v[146:149], v[192:195], v[114:117]
	v_mfma_f32_16x16x32_bf16 v[122:125], v[154:157], v[192:195], v[122:125]
	v_mfma_f32_16x16x32_bf16 v[126:129], v[146:149], v[200:203], v[126:129]
	v_mfma_f32_16x16x32_bf16 v[118:121], v[154:157], v[200:203], v[118:121]
	s_barrier
	s_add_i32 s58, 0, 0x14000
	s_add_i32 s56, s59, s81
	v_add_u32_e32 v141, s58, v139
	v_lshl_add_u64 v[212:213], s[90:91], 0, v[134:135]
	s_mov_b32 m0, s56
	ds_read_b128 v[204:207], v141
	ds_read_b128 v[208:211], v141 offset:1024
	ds_read_b128 v[224:227], v141 offset:2048
	ds_read_b128 v[228:231], v141 offset:3072
	global_load_lds_dwordx4 v[212:213], off
	v_lshl_add_u64 v[222:223], s[90:91], 0, v[130:131]
	s_add_i32 m0, s56, 0x2000
	s_nop 0
	global_load_lds_dwordx4 v[222:223], off
	s_mov_b32 m0, s28
	v_lshl_add_u64 v[232:233], s[22:23], 0, v[136:137]
	s_barrier
	s_waitcnt lgkmcnt(0)
	v_mfma_f32_16x16x32_bf16 v[2:5], v[204:207], v[158:161], v[2:5]
	v_mfma_f32_16x16x32_bf16 v[6:9], v[224:227], v[158:161], v[6:9]
	v_mfma_f32_16x16x32_bf16 v[10:13], v[204:207], v[168:171], v[10:13]
	v_mfma_f32_16x16x32_bf16 v[14:17], v[224:227], v[168:171], v[14:17]
	v_mfma_f32_16x16x32_bf16 v[22:25], v[204:207], v[176:179], v[22:25]
	v_mfma_f32_16x16x32_bf16 v[18:21], v[224:227], v[176:179], v[18:21]
	v_mfma_f32_16x16x32_bf16 v[30:33], v[204:207], v[196:199], v[30:33]
	v_mfma_f32_16x16x32_bf16 v[26:29], v[224:227], v[196:199], v[26:29]
	v_mfma_f32_16x16x32_bf16 v[2:5], v[208:211], v[162:165], v[2:5]
	v_mfma_f32_16x16x32_bf16 v[6:9], v[228:231], v[162:165], v[6:9]
	v_mfma_f32_16x16x32_bf16 v[10:13], v[208:211], v[172:175], v[10:13]
	v_mfma_f32_16x16x32_bf16 v[14:17], v[228:231], v[172:175], v[14:17]
	v_mfma_f32_16x16x32_bf16 v[22:25], v[208:211], v[192:195], v[22:25]
	v_mfma_f32_16x16x32_bf16 v[18:21], v[228:231], v[192:195], v[18:21]
	v_mfma_f32_16x16x32_bf16 v[30:33], v[208:211], v[200:203], v[30:33]
	v_mfma_f32_16x16x32_bf16 v[26:29], v[228:231], v[200:203], v[26:29]
	s_barrier
	ds_read_b128 v[158:161], v140 offset:16384
	ds_read_b128 v[162:165], v140 offset:17408
	ds_read_b128 v[168:171], v140 offset:18432
	ds_read_b128 v[172:175], v140 offset:19456
	ds_read_b128 v[176:179], v140 offset:20480
	ds_read_b128 v[192:195], v140 offset:21504
	ds_read_b128 v[196:199], v140 offset:22528
	ds_read_b128 v[200:203], v140 offset:23552
	global_load_lds_dwordx4 v[232:233], off
	v_lshl_add_u64 v[234:235], s[22:23], 0, v[132:133]
	s_mov_b32 m0, s29
	s_nop 0
	global_load_lds_dwordx4 v[234:235], off
	s_waitcnt vmcnt(10)
	s_barrier
	s_waitcnt lgkmcnt(0)
	v_mfma_f32_16x16x32_bf16 v[110:113], v[142:145], v[158:161], v[110:113]
	v_mfma_f32_16x16x32_bf16 v[106:109], v[150:153], v[158:161], v[106:109]
	v_mfma_f32_16x16x32_bf16 v[90:93], v[142:145], v[168:171], v[90:93]
	v_mfma_f32_16x16x32_bf16 v[82:85], v[150:153], v[168:171], v[82:85]
	v_mfma_f32_16x16x32_bf16 v[78:81], v[142:145], v[176:179], v[78:81]
	v_mfma_f32_16x16x32_bf16 v[74:77], v[150:153], v[176:179], v[74:77]
	v_mfma_f32_16x16x32_bf16 v[70:73], v[142:145], v[196:199], v[70:73]
	v_mfma_f32_16x16x32_bf16 v[66:69], v[150:153], v[196:199], v[66:69]
	v_mfma_f32_16x16x32_bf16 v[110:113], v[146:149], v[162:165], v[110:113]
	v_mfma_f32_16x16x32_bf16 v[106:109], v[154:157], v[162:165], v[106:109]
	v_mfma_f32_16x16x32_bf16 v[90:93], v[146:149], v[172:175], v[90:93]
	v_mfma_f32_16x16x32_bf16 v[82:85], v[154:157], v[172:175], v[82:85]
	v_mfma_f32_16x16x32_bf16 v[78:81], v[146:149], v[192:195], v[78:81]
	v_mfma_f32_16x16x32_bf16 v[74:77], v[154:157], v[192:195], v[74:77]
	v_mfma_f32_16x16x32_bf16 v[70:73], v[146:149], v[200:203], v[70:73]
	v_mfma_f32_16x16x32_bf16 v[66:69], v[154:157], v[200:203], v[66:69]
	s_barrier
	s_add_u32 s56, s90, 0x200000
	s_addc_u32 s57, s91, 0
	s_add_i32 s58, s58, s81
	v_lshl_add_u64 v[142:143], s[56:57], 0, v[134:135]
	s_mov_b32 m0, s58
	s_nop 0
	global_load_lds_dwordx4 v[142:143], off
	v_lshl_add_u64 v[142:143], s[56:57], 0, v[130:131]
	s_add_i32 m0, s58, 0x2000
	s_nop 0
	global_load_lds_dwordx4 v[142:143], off
	v_add_u32_e32 v141, 0x18000, v139
	ds_read_b128 v[142:145], v141
	ds_read_b128 v[146:149], v141 offset:1024
	ds_read_b128 v[150:153], v141 offset:2048
	ds_read_b128 v[154:157], v141 offset:3072
	s_add_i32 s56, 0, 0x18000
	s_waitcnt vmcnt(6)
	s_barrier
	v_mfma_f32_16x16x32_bf16 v[38:41], v[204:207], v[158:161], v[38:41]
	v_mfma_f32_16x16x32_bf16 v[34:37], v[224:227], v[158:161], v[34:37]
	v_mfma_f32_16x16x32_bf16 v[46:49], v[204:207], v[168:171], v[46:49]
	v_mfma_f32_16x16x32_bf16 v[42:45], v[224:227], v[168:171], v[42:45]
	v_mfma_f32_16x16x32_bf16 v[54:57], v[204:207], v[176:179], v[54:57]
	v_mfma_f32_16x16x32_bf16 v[50:53], v[224:227], v[176:179], v[50:53]
	v_mfma_f32_16x16x32_bf16 v[62:65], v[204:207], v[196:199], v[62:65]
	v_mfma_f32_16x16x32_bf16 v[58:61], v[224:227], v[196:199], v[58:61]
	v_mfma_f32_16x16x32_bf16 v[38:41], v[208:211], v[162:165], v[38:41]
	v_mfma_f32_16x16x32_bf16 v[34:37], v[228:231], v[162:165], v[34:37]
	v_mfma_f32_16x16x32_bf16 v[46:49], v[208:211], v[172:175], v[46:49]
	v_mfma_f32_16x16x32_bf16 v[42:45], v[228:231], v[172:175], v[42:45]
	v_mfma_f32_16x16x32_bf16 v[54:57], v[208:211], v[192:195], v[54:57]
	v_mfma_f32_16x16x32_bf16 v[50:53], v[228:231], v[192:195], v[50:53]
	v_mfma_f32_16x16x32_bf16 v[62:65], v[208:211], v[200:203], v[62:65]
	v_mfma_f32_16x16x32_bf16 v[58:61], v[228:231], v[200:203], v[58:61]
	s_barrier
	ds_read_b128 v[158:161], v140 offset:32768
	ds_read_b128 v[162:165], v140 offset:33792
	ds_read_b128 v[168:171], v140 offset:34816
	ds_read_b128 v[172:175], v140 offset:35840
	ds_read_b128 v[176:179], v140 offset:36864
	ds_read_b128 v[192:195], v140 offset:37888
	ds_read_b128 v[196:199], v140 offset:38912
	ds_read_b128 v[200:203], v140 offset:39936
	s_add_u32 s22, s22, 0x10000
	s_addc_u32 s23, s23, 0
	s_mov_b32 m0, s44
	v_lshl_add_u64 v[204:205], s[22:23], 0, v[136:137]
	global_load_lds_dwordx4 v[204:205], off
	v_lshl_add_u64 v[204:205], s[22:23], 0, v[132:133]
	s_mov_b32 m0, s45
	s_nop 0
	global_load_lds_dwordx4 v[204:205], off
	s_waitcnt lgkmcnt(8)
	s_barrier
	s_waitcnt lgkmcnt(0)
	v_mfma_f32_16x16x32_bf16 v[86:89], v[142:145], v[158:161], v[86:89]
	v_mfma_f32_16x16x32_bf16 v[94:97], v[150:153], v[158:161], v[94:97]
	v_mfma_f32_16x16x32_bf16 v[98:101], v[142:145], v[168:171], v[98:101]
	v_mfma_f32_16x16x32_bf16 v[102:105], v[150:153], v[168:171], v[102:105]
	v_mfma_f32_16x16x32_bf16 v[114:117], v[142:145], v[176:179], v[114:117]
	v_mfma_f32_16x16x32_bf16 v[122:125], v[150:153], v[176:179], v[122:125]
	v_mfma_f32_16x16x32_bf16 v[126:129], v[142:145], v[196:199], v[126:129]
	v_mfma_f32_16x16x32_bf16 v[118:121], v[150:153], v[196:199], v[118:121]
	v_mfma_f32_16x16x32_bf16 v[86:89], v[146:149], v[162:165], v[86:89]
	v_mfma_f32_16x16x32_bf16 v[94:97], v[154:157], v[162:165], v[94:97]
	v_mfma_f32_16x16x32_bf16 v[98:101], v[146:149], v[172:175], v[98:101]
	v_mfma_f32_16x16x32_bf16 v[102:105], v[154:157], v[172:175], v[102:105]
	v_mfma_f32_16x16x32_bf16 v[114:117], v[146:149], v[192:195], v[114:117]
	v_mfma_f32_16x16x32_bf16 v[122:125], v[154:157], v[192:195], v[122:125]
	v_mfma_f32_16x16x32_bf16 v[126:129], v[146:149], v[200:203], v[126:129]
	v_mfma_f32_16x16x32_bf16 v[118:121], v[154:157], v[200:203], v[118:121]
	s_barrier
	s_add_i32 s57, 0, 0x1c000
	s_add_i32 s22, s56, s81
	v_add_u32_e32 v141, s57, v139
	v_lshl_add_u64 v[212:213], v[212:213], 0, s[78:79]
	s_mov_b32 m0, s22
	ds_read_b128 v[204:207], v141
	ds_read_b128 v[208:211], v141 offset:1024
	ds_read_b128 v[224:227], v141 offset:2048
	ds_read_b128 v[228:231], v141 offset:3072
	global_load_lds_dwordx4 v[212:213], off
	v_lshl_add_u64 v[212:213], v[222:223], 0, s[78:79]
	s_add_i32 m0, s22, 0x2000
	s_nop 0
	global_load_lds_dwordx4 v[212:213], off
	s_mov_b32 m0, s47
	v_lshl_add_u64 v[212:213], v[232:233], 0, s[78:79]
	s_barrier
	s_waitcnt lgkmcnt(0)
	v_mfma_f32_16x16x32_bf16 v[2:5], v[204:207], v[158:161], v[2:5]
	v_mfma_f32_16x16x32_bf16 v[6:9], v[224:227], v[158:161], v[6:9]
	v_mfma_f32_16x16x32_bf16 v[10:13], v[204:207], v[168:171], v[10:13]
	v_mfma_f32_16x16x32_bf16 v[14:17], v[224:227], v[168:171], v[14:17]
	v_mfma_f32_16x16x32_bf16 v[22:25], v[204:207], v[176:179], v[22:25]
	v_mfma_f32_16x16x32_bf16 v[18:21], v[224:227], v[176:179], v[18:21]
	v_mfma_f32_16x16x32_bf16 v[30:33], v[204:207], v[196:199], v[30:33]
	v_mfma_f32_16x16x32_bf16 v[26:29], v[224:227], v[196:199], v[26:29]
	v_mfma_f32_16x16x32_bf16 v[2:5], v[208:211], v[162:165], v[2:5]
	v_mfma_f32_16x16x32_bf16 v[6:9], v[228:231], v[162:165], v[6:9]
	v_mfma_f32_16x16x32_bf16 v[10:13], v[208:211], v[172:175], v[10:13]
	v_mfma_f32_16x16x32_bf16 v[14:17], v[228:231], v[172:175], v[14:17]
	v_mfma_f32_16x16x32_bf16 v[22:25], v[208:211], v[192:195], v[22:25]
	v_mfma_f32_16x16x32_bf16 v[18:21], v[228:231], v[192:195], v[18:21]
	v_mfma_f32_16x16x32_bf16 v[30:33], v[208:211], v[200:203], v[30:33]
	v_mfma_f32_16x16x32_bf16 v[26:29], v[228:231], v[200:203], v[26:29]
	s_barrier
	ds_read_b128 v[158:161], v140 offset:49152
	ds_read_b128 v[162:165], v140 offset:50176
	ds_read_b128 v[168:171], v140 offset:51200
	ds_read_b128 v[172:175], v140 offset:52224
	ds_read_b128 v[176:179], v140 offset:53248
	ds_read_b128 v[192:195], v140 offset:54272
	ds_read_b128 v[196:199], v140 offset:55296
	ds_read_b128 v[200:203], v140 offset:56320
	global_load_lds_dwordx4 v[212:213], off
	v_lshl_add_u64 v[212:213], v[234:235], 0, s[78:79]
	s_mov_b32 m0, s48
	s_nop 0
	global_load_lds_dwordx4 v[212:213], off
	s_waitcnt vmcnt(10)
	s_barrier
	s_waitcnt lgkmcnt(0)
	v_mfma_f32_16x16x32_bf16 v[110:113], v[142:145], v[158:161], v[110:113]
	v_mfma_f32_16x16x32_bf16 v[106:109], v[150:153], v[158:161], v[106:109]
	v_mfma_f32_16x16x32_bf16 v[90:93], v[142:145], v[168:171], v[90:93]
	v_mfma_f32_16x16x32_bf16 v[82:85], v[150:153], v[168:171], v[82:85]
	v_mfma_f32_16x16x32_bf16 v[78:81], v[142:145], v[176:179], v[78:81]
	v_mfma_f32_16x16x32_bf16 v[74:77], v[150:153], v[176:179], v[74:77]
	v_mfma_f32_16x16x32_bf16 v[70:73], v[142:145], v[196:199], v[70:73]
	v_mfma_f32_16x16x32_bf16 v[66:69], v[150:153], v[196:199], v[66:69]
	v_mfma_f32_16x16x32_bf16 v[110:113], v[146:149], v[162:165], v[110:113]
	v_mfma_f32_16x16x32_bf16 v[106:109], v[154:157], v[162:165], v[106:109]
	v_mfma_f32_16x16x32_bf16 v[90:93], v[146:149], v[172:175], v[90:93]
	v_mfma_f32_16x16x32_bf16 v[82:85], v[154:157], v[172:175], v[82:85]
	v_mfma_f32_16x16x32_bf16 v[78:81], v[146:149], v[192:195], v[78:81]
	v_mfma_f32_16x16x32_bf16 v[74:77], v[154:157], v[192:195], v[74:77]
	v_mfma_f32_16x16x32_bf16 v[70:73], v[146:149], v[200:203], v[70:73]
	v_mfma_f32_16x16x32_bf16 v[66:69], v[154:157], v[200:203], v[66:69]
	s_barrier
	s_add_u32 s22, s90, 0x200080
	s_addc_u32 s23, s91, 0
	s_add_i32 s56, s57, s81
	v_lshl_add_u64 v[142:143], s[22:23], 0, v[134:135]
	s_mov_b32 m0, s56
	s_nop 0
	global_load_lds_dwordx4 v[142:143], off
	v_lshl_add_u64 v[142:143], s[22:23], 0, v[130:131]
	s_add_i32 m0, s56, 0x2000
	s_nop 0
	global_load_lds_dwordx4 v[142:143], off
	v_add_u32_e32 v141, 0x10000, v139
	ds_read_b128 v[142:145], v141
	ds_read_b128 v[146:149], v141 offset:1024
	ds_read_b128 v[150:153], v141 offset:2048
	ds_read_b128 v[154:157], v141 offset:3072
	s_add_i32 s54, s54, 2
	s_add_i32 s55, s55, 0x10000
	s_cmpk_gt_u32 s54, 0x7d
	s_mov_b64 s[90:91], vcc
	s_waitcnt vmcnt(6)
	s_barrier
	v_mfma_f32_16x16x32_bf16 v[38:41], v[204:207], v[158:161], v[38:41]
	v_mfma_f32_16x16x32_bf16 v[34:37], v[224:227], v[158:161], v[34:37]
	v_mfma_f32_16x16x32_bf16 v[46:49], v[204:207], v[168:171], v[46:49]
	v_mfma_f32_16x16x32_bf16 v[42:45], v[224:227], v[168:171], v[42:45]
	v_mfma_f32_16x16x32_bf16 v[54:57], v[204:207], v[176:179], v[54:57]
	v_mfma_f32_16x16x32_bf16 v[50:53], v[224:227], v[176:179], v[50:53]
	v_mfma_f32_16x16x32_bf16 v[62:65], v[204:207], v[196:199], v[62:65]
	v_mfma_f32_16x16x32_bf16 v[58:61], v[224:227], v[196:199], v[58:61]
	v_mfma_f32_16x16x32_bf16 v[38:41], v[208:211], v[162:165], v[38:41]
	v_mfma_f32_16x16x32_bf16 v[34:37], v[228:231], v[162:165], v[34:37]
	v_mfma_f32_16x16x32_bf16 v[46:49], v[208:211], v[172:175], v[46:49]
	v_mfma_f32_16x16x32_bf16 v[42:45], v[228:231], v[172:175], v[42:45]
	v_mfma_f32_16x16x32_bf16 v[54:57], v[208:211], v[192:195], v[54:57]
	v_mfma_f32_16x16x32_bf16 v[50:53], v[228:231], v[192:195], v[50:53]
	v_mfma_f32_16x16x32_bf16 v[62:65], v[208:211], v[200:203], v[62:65]
	v_mfma_f32_16x16x32_bf16 v[58:61], v[228:231], v[200:203], v[58:61]
	s_barrier
	s_cbranch_scc0 .LBB0_814
	s_waitcnt lgkmcnt(0)
	s_andn2_b64 vcc, exec, s[38:39]
	s_cbranch_vccnz .LBB0_806
	v_mov_b32_e32 v58, 0
	s_mov_b32 s80, s42
	s_mov_b32 s25, s82
	s_mov_b64 s[30:31], s[20:21]
	s_mov_b64 s[84:85], s[18:19]
	s_mov_b32 s49, s50
	v_mov_b32_e32 v59, v58
	v_mov_b32_e32 v60, v58
	v_mov_b32_e32 v61, v58
	v_mov_b32_e32 v62, v58
	v_mov_b32_e32 v63, v58
	v_mov_b32_e32 v64, v58
	v_mov_b32_e32 v65, v58
	v_mov_b32_e32 v50, v58
	v_mov_b32_e32 v51, v58
	v_mov_b32_e32 v52, v58
	v_mov_b32_e32 v53, v58
	v_mov_b32_e32 v54, v58
	v_mov_b32_e32 v55, v58
	v_mov_b32_e32 v56, v58
	v_mov_b32_e32 v57, v58
	v_mov_b32_e32 v42, v58
	v_mov_b32_e32 v43, v58
	v_mov_b32_e32 v44, v58
	v_mov_b32_e32 v45, v58
	v_mov_b32_e32 v46, v58
	v_mov_b32_e32 v47, v58
	v_mov_b32_e32 v48, v58
	v_mov_b32_e32 v49, v58
	v_mov_b32_e32 v34, v58
	v_mov_b32_e32 v35, v58
	v_mov_b32_e32 v36, v58
	v_mov_b32_e32 v37, v58
	v_mov_b32_e32 v38, v58
	v_mov_b32_e32 v39, v58
	v_mov_b32_e32 v40, v58
	v_mov_b32_e32 v41, v58
	v_mov_b32_e32 v66, v58
	v_mov_b32_e32 v67, v58
	v_mov_b32_e32 v68, v58
	v_mov_b32_e32 v69, v58
	v_mov_b32_e32 v70, v58
	v_mov_b32_e32 v71, v58
	v_mov_b32_e32 v72, v58
	v_mov_b32_e32 v73, v58
	v_mov_b32_e32 v74, v58
	v_mov_b32_e32 v75, v58
	v_mov_b32_e32 v76, v58
	v_mov_b32_e32 v77, v58
	v_mov_b32_e32 v78, v58
	v_mov_b32_e32 v79, v58
	v_mov_b32_e32 v80, v58
	v_mov_b32_e32 v81, v58
	v_mov_b32_e32 v82, v58
	v_mov_b32_e32 v83, v58
	v_mov_b32_e32 v84, v58
	v_mov_b32_e32 v85, v58
	v_mov_b32_e32 v90, v58
	v_mov_b32_e32 v91, v58
	v_mov_b32_e32 v92, v58
	v_mov_b32_e32 v93, v58
	v_mov_b32_e32 v106, v58
	v_mov_b32_e32 v107, v58
	v_mov_b32_e32 v108, v58
	v_mov_b32_e32 v109, v58
	v_mov_b32_e32 v110, v58
	v_mov_b32_e32 v111, v58
	v_mov_b32_e32 v112, v58
	v_mov_b32_e32 v113, v58
	v_mov_b32_e32 v26, v58
	v_mov_b32_e32 v27, v58
	v_mov_b32_e32 v28, v58
	v_mov_b32_e32 v29, v58
	v_mov_b32_e32 v30, v58
	v_mov_b32_e32 v31, v58
	v_mov_b32_e32 v32, v58
	v_mov_b32_e32 v33, v58
	v_mov_b32_e32 v18, v58
	v_mov_b32_e32 v19, v58
	v_mov_b32_e32 v20, v58
	v_mov_b32_e32 v21, v58
	v_mov_b32_e32 v22, v58
	v_mov_b32_e32 v23, v58
	v_mov_b32_e32 v24, v58
	v_mov_b32_e32 v25, v58
	v_mov_b32_e32 v14, v58
	v_mov_b32_e32 v15, v58
	v_mov_b32_e32 v16, v58
	v_mov_b32_e32 v17, v58
	v_mov_b32_e32 v10, v58
	v_mov_b32_e32 v11, v58
	v_mov_b32_e32 v12, v58
	v_mov_b32_e32 v13, v58
	v_mov_b32_e32 v6, v58
	v_mov_b32_e32 v7, v58
	v_mov_b32_e32 v8, v58
	v_mov_b32_e32 v9, v58
	v_mov_b32_e32 v2, v58
	v_mov_b32_e32 v3, v58
	v_mov_b32_e32 v4, v58
	v_mov_b32_e32 v5, v58
	v_mov_b32_e32 v118, v58
	v_mov_b32_e32 v119, v58
	v_mov_b32_e32 v120, v58
	v_mov_b32_e32 v121, v58
	v_mov_b32_e32 v126, v58
	v_mov_b32_e32 v127, v58
	v_mov_b32_e32 v128, v58
	v_mov_b32_e32 v129, v58
	v_mov_b32_e32 v122, v58
	v_mov_b32_e32 v123, v58
	v_mov_b32_e32 v124, v58
	v_mov_b32_e32 v125, v58
	v_mov_b32_e32 v114, v58
	v_mov_b32_e32 v115, v58
	v_mov_b32_e32 v116, v58
	v_mov_b32_e32 v117, v58
	v_mov_b32_e32 v102, v58
	v_mov_b32_e32 v103, v58
	v_mov_b32_e32 v104, v58
	v_mov_b32_e32 v105, v58
	v_mov_b32_e32 v98, v58
	v_mov_b32_e32 v99, v58
	v_mov_b32_e32 v100, v58
	v_mov_b32_e32 v101, v58
	v_mov_b32_e32 v94, v58
	v_mov_b32_e32 v95, v58
	v_mov_b32_e32 v96, v58
	v_mov_b32_e32 v97, v58
	v_mov_b32_e32 v86, v58
	v_mov_b32_e32 v87, v58
	v_mov_b32_e32 v88, v58
	v_mov_b32_e32 v89, v58
	s_branch .LBB0_806
